# v16 lean + all s_setprio flips of the K-loops removed
# baseline (speedup 1.0000x reference)
.LBB0_642:
	ds_read_b128 v[148:151], v139
	ds_read_b128 v[152:155], v139 offset:1024
	ds_read_b128 v[156:159], v139 offset:2048
	ds_read_b128 v[160:163], v139 offset:3072
	ds_read_b128 v[164:167], v140
	ds_read_b128 v[168:171], v140 offset:1024
	ds_read_b128 v[172:175], v140 offset:2048
	ds_read_b128 v[176:179], v140 offset:3072
	s_add_i32 s18, s71, 0xffe80080
	s_cmp_eq_u32 s58, s73
	s_cselect_b32 s74, s69, s18
	s_cselect_b32 s76, s70, s72
	s_or_b32 s75, s74, 0x80
	s_add_i32 s18, s71, 0xfff80000
	s_mov_b32 m0, s59
	ds_read_b128 v[180:183], v141
	ds_read_b128 v[184:187], v141 offset:1024
	ds_read_b128 v[188:191], v141 offset:2048
	ds_read_b128 v[192:195], v141 offset:3072
	ds_read_b128 v[196:199], v141 offset:4096
	ds_read_b128 v[200:203], v141 offset:5120
	ds_read_b128 v[204:207], v141 offset:6144
	ds_read_b128 v[208:211], v141 offset:7168
	buffer_load_dwordx4 v137, s[12:15], s18 offen lds
	s_mov_b32 m0, s60
	s_nop 0
	buffer_load_dwordx4 v137, s[12:15], s71 offen lds
	s_waitcnt vmcnt(8) lgkmcnt(0)
	v_mfma_f32_16x16x32_bf16 v[118:121], v[148:151], v[180:183], v[118:121]
	s_barrier
	v_mfma_f32_16x16x32_bf16 v[118:121], v[152:155], v[184:187], v[118:121]
	v_mfma_f32_16x16x32_bf16 v[114:117], v[156:159], v[180:183], v[114:117]
	v_mfma_f32_16x16x32_bf16 v[114:117], v[160:163], v[184:187], v[114:117]
	v_mfma_f32_16x16x32_bf16 v[126:129], v[164:167], v[180:183], v[126:129]
	v_mfma_f32_16x16x32_bf16 v[126:129], v[168:171], v[184:187], v[126:129]
	v_mfma_f32_16x16x32_bf16 v[122:125], v[172:175], v[180:183], v[122:125]
	v_mfma_f32_16x16x32_bf16 v[122:125], v[176:179], v[184:187], v[122:125]
	v_mfma_f32_16x16x32_bf16 v[98:101], v[172:175], v[188:191], v[98:101]
	v_mfma_f32_16x16x32_bf16 v[98:101], v[176:179], v[192:195], v[98:101]
	v_mfma_f32_16x16x32_bf16 v[106:109], v[164:167], v[188:191], v[106:109]
	v_mfma_f32_16x16x32_bf16 v[106:109], v[168:171], v[192:195], v[106:109]
	v_mfma_f32_16x16x32_bf16 v[102:105], v[156:159], v[188:191], v[102:105]
	v_mfma_f32_16x16x32_bf16 v[102:105], v[160:163], v[192:195], v[102:105]
	v_mfma_f32_16x16x32_bf16 v[110:113], v[148:151], v[188:191], v[110:113]
	v_mfma_f32_16x16x32_bf16 v[110:113], v[152:155], v[192:195], v[110:113]
	v_mfma_f32_16x16x32_bf16 v[94:97], v[148:151], v[196:199], v[94:97]
	v_mfma_f32_16x16x32_bf16 v[94:97], v[152:155], v[200:203], v[94:97]
	v_mfma_f32_16x16x32_bf16 v[86:89], v[156:159], v[196:199], v[86:89]
	v_mfma_f32_16x16x32_bf16 v[86:89], v[160:163], v[200:203], v[86:89]
	v_mfma_f32_16x16x32_bf16 v[90:93], v[164:167], v[196:199], v[90:93]
	v_mfma_f32_16x16x32_bf16 v[90:93], v[168:171], v[200:203], v[90:93]
	v_mfma_f32_16x16x32_bf16 v[82:85], v[172:175], v[196:199], v[82:85]
	v_mfma_f32_16x16x32_bf16 v[82:85], v[176:179], v[200:203], v[82:85]
	v_mfma_f32_16x16x32_bf16 v[70:73], v[172:175], v[204:207], v[70:73]
	v_mfma_f32_16x16x32_bf16 v[70:73], v[176:179], v[208:211], v[70:73]
	v_mfma_f32_16x16x32_bf16 v[74:77], v[164:167], v[204:207], v[74:77]
	v_mfma_f32_16x16x32_bf16 v[74:77], v[168:171], v[208:211], v[74:77]
	v_mfma_f32_16x16x32_bf16 v[66:69], v[156:159], v[204:207], v[66:69]
	v_mfma_f32_16x16x32_bf16 v[66:69], v[160:163], v[208:211], v[66:69]
	v_mfma_f32_16x16x32_bf16 v[78:81], v[148:151], v[204:207], v[78:81]
	v_mfma_f32_16x16x32_bf16 v[78:81], v[152:155], v[208:211], v[78:81]
	s_barrier
	s_mov_b32 m0, s30
	s_mov_b32 s18, s14
	s_mov_b32 s19, s15
	ds_read_b128 v[180:183], v141 offset:16384
	ds_read_b128 v[184:187], v141 offset:17408
	ds_read_b128 v[188:191], v141 offset:18432
	ds_read_b128 v[192:195], v141 offset:19456
	ds_read_b128 v[196:199], v141 offset:20480
	ds_read_b128 v[200:203], v141 offset:21504
	ds_read_b128 v[204:207], v141 offset:22528
	ds_read_b128 v[208:211], v141 offset:23552
	buffer_load_dwordx4 v138, s[16:19], s76 offen lds
	s_mov_b32 m0, s31
	s_add_i32 s77, s76, 0x80000
	buffer_load_dwordx4 v138, s[16:19], s77 offen lds
	s_mov_b32 m0, s44
	s_add_i32 s77, s76, 0x100000
	buffer_load_dwordx4 v138, s[16:19], s77 offen lds
	s_mov_b32 m0, s45
	s_add_i32 s77, s76, 0x180000
	buffer_load_dwordx4 v138, s[16:19], s77 offen lds
	s_mov_b32 m0, s27
	s_add_i32 s77, s74, 0x80000
	buffer_load_dwordx4 v137, s[12:15], s74 offen lds
	s_mov_b32 m0, s46
	s_nop 0
	buffer_load_dwordx4 v137, s[12:15], s77 offen lds
	s_waitcnt vmcnt(8) lgkmcnt(0)
	v_mfma_f32_16x16x32_bf16 v[62:65], v[148:151], v[180:183], v[62:65]
	s_barrier
	v_mfma_f32_16x16x32_bf16 v[62:65], v[152:155], v[184:187], v[62:65]
	v_mfma_f32_16x16x32_bf16 v[54:57], v[156:159], v[180:183], v[54:57]
	v_mfma_f32_16x16x32_bf16 v[54:57], v[160:163], v[184:187], v[54:57]
	v_mfma_f32_16x16x32_bf16 v[58:61], v[164:167], v[180:183], v[58:61]
	v_mfma_f32_16x16x32_bf16 v[58:61], v[168:171], v[184:187], v[58:61]
	v_mfma_f32_16x16x32_bf16 v[50:53], v[172:175], v[180:183], v[50:53]
	v_mfma_f32_16x16x32_bf16 v[50:53], v[176:179], v[184:187], v[50:53]
	v_mfma_f32_16x16x32_bf16 v[34:37], v[172:175], v[188:191], v[34:37]
	v_mfma_f32_16x16x32_bf16 v[34:37], v[176:179], v[192:195], v[34:37]
	v_mfma_f32_16x16x32_bf16 v[42:45], v[164:167], v[188:191], v[42:45]
	v_mfma_f32_16x16x32_bf16 v[42:45], v[168:171], v[192:195], v[42:45]
	v_mfma_f32_16x16x32_bf16 v[38:41], v[156:159], v[188:191], v[38:41]
	v_mfma_f32_16x16x32_bf16 v[38:41], v[160:163], v[192:195], v[38:41]
	v_mfma_f32_16x16x32_bf16 v[46:49], v[148:151], v[188:191], v[46:49]
	v_mfma_f32_16x16x32_bf16 v[46:49], v[152:155], v[192:195], v[46:49]
	v_mfma_f32_16x16x32_bf16 v[30:33], v[148:151], v[196:199], v[30:33]
	v_mfma_f32_16x16x32_bf16 v[30:33], v[152:155], v[200:203], v[30:33]
	v_mfma_f32_16x16x32_bf16 v[22:25], v[156:159], v[196:199], v[22:25]
	v_mfma_f32_16x16x32_bf16 v[22:25], v[160:163], v[200:203], v[22:25]
	v_mfma_f32_16x16x32_bf16 v[26:29], v[164:167], v[196:199], v[26:29]
	v_mfma_f32_16x16x32_bf16 v[26:29], v[168:171], v[200:203], v[26:29]
	v_mfma_f32_16x16x32_bf16 v[18:21], v[172:175], v[196:199], v[18:21]
	v_mfma_f32_16x16x32_bf16 v[18:21], v[176:179], v[200:203], v[18:21]
	v_mfma_f32_16x16x32_bf16 v[2:5], v[172:175], v[204:207], v[2:5]
	v_mfma_f32_16x16x32_bf16 v[2:5], v[176:179], v[208:211], v[2:5]
	v_mfma_f32_16x16x32_bf16 v[10:13], v[164:167], v[204:207], v[10:13]
	v_mfma_f32_16x16x32_bf16 v[10:13], v[168:171], v[208:211], v[10:13]
	v_mfma_f32_16x16x32_bf16 v[6:9], v[156:159], v[204:207], v[6:9]
	v_mfma_f32_16x16x32_bf16 v[6:9], v[160:163], v[208:211], v[6:9]
	v_mfma_f32_16x16x32_bf16 v[14:17], v[148:151], v[204:207], v[14:17]
	v_mfma_f32_16x16x32_bf16 v[14:17], v[152:155], v[208:211], v[14:17]
	s_barrier
	ds_read_b128 v[148:151], v142
	ds_read_b128 v[152:155], v142 offset:1024
	ds_read_b128 v[156:159], v142 offset:2048
	ds_read_b128 v[160:163], v142 offset:3072
	ds_read_b128 v[164:167], v143
	ds_read_b128 v[168:171], v143 offset:1024
	ds_read_b128 v[172:175], v143 offset:2048
	ds_read_b128 v[176:179], v143 offset:3072
	s_mov_b32 m0, s47
	s_add_i32 s77, s74, 0x100000
	ds_read_b128 v[180:183], v141 offset:32768
	ds_read_b128 v[184:187], v141 offset:33792
	ds_read_b128 v[188:191], v141 offset:34816
	ds_read_b128 v[192:195], v141 offset:35840
	ds_read_b128 v[196:199], v141 offset:36864
	ds_read_b128 v[200:203], v141 offset:37888
	ds_read_b128 v[204:207], v141 offset:38912
	ds_read_b128 v[208:211], v141 offset:39936
	buffer_load_dwordx4 v137, s[12:15], s77 offen lds
	s_mov_b32 m0, s48
	s_add_i32 s77, s74, 0x180000
	buffer_load_dwordx4 v137, s[12:15], s77 offen lds
	s_waitcnt vmcnt(8) lgkmcnt(0)
	v_mfma_f32_16x16x32_bf16 v[118:121], v[148:151], v[180:183], v[118:121]
	s_barrier
	v_mfma_f32_16x16x32_bf16 v[118:121], v[152:155], v[184:187], v[118:121]
	v_mfma_f32_16x16x32_bf16 v[114:117], v[156:159], v[180:183], v[114:117]
	v_mfma_f32_16x16x32_bf16 v[114:117], v[160:163], v[184:187], v[114:117]
	v_mfma_f32_16x16x32_bf16 v[126:129], v[164:167], v[180:183], v[126:129]
	v_mfma_f32_16x16x32_bf16 v[126:129], v[168:171], v[184:187], v[126:129]
	v_mfma_f32_16x16x32_bf16 v[122:125], v[172:175], v[180:183], v[122:125]
	v_mfma_f32_16x16x32_bf16 v[122:125], v[176:179], v[184:187], v[122:125]
	v_mfma_f32_16x16x32_bf16 v[98:101], v[172:175], v[188:191], v[98:101]
	v_mfma_f32_16x16x32_bf16 v[98:101], v[176:179], v[192:195], v[98:101]
	v_mfma_f32_16x16x32_bf16 v[106:109], v[164:167], v[188:191], v[106:109]
	v_mfma_f32_16x16x32_bf16 v[106:109], v[168:171], v[192:195], v[106:109]
	v_mfma_f32_16x16x32_bf16 v[102:105], v[156:159], v[188:191], v[102:105]
	v_mfma_f32_16x16x32_bf16 v[102:105], v[160:163], v[192:195], v[102:105]
	v_mfma_f32_16x16x32_bf16 v[110:113], v[148:151], v[188:191], v[110:113]
	v_mfma_f32_16x16x32_bf16 v[110:113], v[152:155], v[192:195], v[110:113]
	v_mfma_f32_16x16x32_bf16 v[94:97], v[148:151], v[196:199], v[94:97]
	v_mfma_f32_16x16x32_bf16 v[94:97], v[152:155], v[200:203], v[94:97]
	v_mfma_f32_16x16x32_bf16 v[86:89], v[156:159], v[196:199], v[86:89]
	v_mfma_f32_16x16x32_bf16 v[86:89], v[160:163], v[200:203], v[86:89]
	v_mfma_f32_16x16x32_bf16 v[90:93], v[164:167], v[196:199], v[90:93]
	v_mfma_f32_16x16x32_bf16 v[90:93], v[168:171], v[200:203], v[90:93]
	v_mfma_f32_16x16x32_bf16 v[82:85], v[172:175], v[196:199], v[82:85]
	v_mfma_f32_16x16x32_bf16 v[82:85], v[176:179], v[200:203], v[82:85]
	v_mfma_f32_16x16x32_bf16 v[70:73], v[172:175], v[204:207], v[70:73]
	v_mfma_f32_16x16x32_bf16 v[70:73], v[176:179], v[208:211], v[70:73]
	v_mfma_f32_16x16x32_bf16 v[74:77], v[164:167], v[204:207], v[74:77]
	v_mfma_f32_16x16x32_bf16 v[74:77], v[168:171], v[208:211], v[74:77]
	v_mfma_f32_16x16x32_bf16 v[66:69], v[156:159], v[204:207], v[66:69]
	v_mfma_f32_16x16x32_bf16 v[66:69], v[160:163], v[208:211], v[66:69]
	v_mfma_f32_16x16x32_bf16 v[78:81], v[148:151], v[204:207], v[78:81]
	v_mfma_f32_16x16x32_bf16 v[78:81], v[152:155], v[208:211], v[78:81]
	s_barrier
	s_mov_b32 m0, s50
	s_or_b32 s77, s76, 0x80
	ds_read_b128 v[180:183], v141 offset:49152
	ds_read_b128 v[184:187], v141 offset:50176
	ds_read_b128 v[188:191], v141 offset:51200
	ds_read_b128 v[192:195], v141 offset:52224
	ds_read_b128 v[196:199], v141 offset:53248
	ds_read_b128 v[200:203], v141 offset:54272
	ds_read_b128 v[204:207], v141 offset:55296
	ds_read_b128 v[208:211], v141 offset:56320
	buffer_load_dwordx4 v138, s[16:19], s77 offen lds
	s_add_i32 s77, s76, 0x80080
	s_mov_b32 m0, s51
	s_add_i32 s74, s74, 0x80080
	buffer_load_dwordx4 v138, s[16:19], s77 offen lds
	s_add_i32 s77, s76, 0x100080
	s_mov_b32 m0, s54
	s_add_i32 s76, s76, 0x180080
	buffer_load_dwordx4 v138, s[16:19], s77 offen lds
	s_mov_b32 m0, s55
	s_nop 0
	buffer_load_dwordx4 v138, s[16:19], s76 offen lds
	s_mov_b32 m0, s52
	s_nop 0
	buffer_load_dwordx4 v137, s[12:15], s75 offen lds
	s_mov_b32 m0, s53
	s_nop 0
	buffer_load_dwordx4 v137, s[12:15], s74 offen lds
	s_waitcnt vmcnt(8) lgkmcnt(0)
	v_mfma_f32_16x16x32_bf16 v[62:65], v[148:151], v[180:183], v[62:65]
	s_barrier
	v_mfma_f32_16x16x32_bf16 v[62:65], v[152:155], v[184:187], v[62:65]
	v_mfma_f32_16x16x32_bf16 v[54:57], v[156:159], v[180:183], v[54:57]
	v_mfma_f32_16x16x32_bf16 v[54:57], v[160:163], v[184:187], v[54:57]
	v_mfma_f32_16x16x32_bf16 v[58:61], v[164:167], v[180:183], v[58:61]
	v_mfma_f32_16x16x32_bf16 v[58:61], v[168:171], v[184:187], v[58:61]
	v_mfma_f32_16x16x32_bf16 v[50:53], v[172:175], v[180:183], v[50:53]
	v_mfma_f32_16x16x32_bf16 v[50:53], v[176:179], v[184:187], v[50:53]
	v_mfma_f32_16x16x32_bf16 v[34:37], v[172:175], v[188:191], v[34:37]
	v_mfma_f32_16x16x32_bf16 v[34:37], v[176:179], v[192:195], v[34:37]
	v_mfma_f32_16x16x32_bf16 v[42:45], v[164:167], v[188:191], v[42:45]
	v_mfma_f32_16x16x32_bf16 v[42:45], v[168:171], v[192:195], v[42:45]
	v_mfma_f32_16x16x32_bf16 v[38:41], v[156:159], v[188:191], v[38:41]
	v_mfma_f32_16x16x32_bf16 v[38:41], v[160:163], v[192:195], v[38:41]
	v_mfma_f32_16x16x32_bf16 v[46:49], v[148:151], v[188:191], v[46:49]
	v_mfma_f32_16x16x32_bf16 v[46:49], v[152:155], v[192:195], v[46:49]
	v_mfma_f32_16x16x32_bf16 v[30:33], v[148:151], v[196:199], v[30:33]
	v_mfma_f32_16x16x32_bf16 v[30:33], v[152:155], v[200:203], v[30:33]
	v_mfma_f32_16x16x32_bf16 v[22:25], v[156:159], v[196:199], v[22:25]
	v_mfma_f32_16x16x32_bf16 v[22:25], v[160:163], v[200:203], v[22:25]
	v_mfma_f32_16x16x32_bf16 v[26:29], v[164:167], v[196:199], v[26:29]
	v_mfma_f32_16x16x32_bf16 v[26:29], v[168:171], v[200:203], v[26:29]
	v_mfma_f32_16x16x32_bf16 v[18:21], v[172:175], v[196:199], v[18:21]
	v_mfma_f32_16x16x32_bf16 v[18:21], v[176:179], v[200:203], v[18:21]
	v_mfma_f32_16x16x32_bf16 v[2:5], v[172:175], v[204:207], v[2:5]
	v_mfma_f32_16x16x32_bf16 v[2:5], v[176:179], v[208:211], v[2:5]
	v_mfma_f32_16x16x32_bf16 v[10:13], v[164:167], v[204:207], v[10:13]
	v_mfma_f32_16x16x32_bf16 v[10:13], v[168:171], v[208:211], v[10:13]
	v_mfma_f32_16x16x32_bf16 v[6:9], v[156:159], v[204:207], v[6:9]
	v_mfma_f32_16x16x32_bf16 v[6:9], v[160:163], v[208:211], v[6:9]
	v_mfma_f32_16x16x32_bf16 v[14:17], v[148:151], v[204:207], v[14:17]
	v_mfma_f32_16x16x32_bf16 v[14:17], v[152:155], v[208:211], v[14:17]
	s_barrier
	s_add_i32 s73, s73, 2
	s_addk_i32 s71, 0x100
	s_addk_i32 s72, 0x100
	s_cmp_ge_i32 s73, s3
	s_cbranch_scc0 .LBB0_642
	s_and_b64 vcc, exec, s[42:43]
	s_cbranch_vccz .LBB0_645

.LBB0_799:
	ds_read_b128 v[134:137], v210
	ds_read_b128 v[138:141], v210 offset:1024
	ds_read_b128 v[142:145], v210 offset:2048
	ds_read_b128 v[148:151], v210 offset:3072
	ds_read_b128 v[152:155], v211
	ds_read_b128 v[156:159], v211 offset:1024
	ds_read_b128 v[160:163], v211 offset:2048
	ds_read_b128 v[164:167], v211 offset:3072
	s_add_i32 s18, s77, 0xffbf8080
	s_cmp_eq_u32 s62, s79
	s_cselect_b32 s80, s6, s18
	s_cselect_b32 s82, s7, s78
	s_or_b32 s81, s80, 0x80
	s_add_i32 s18, s77, 0xffea8000
	s_mov_b32 m0, s63
	ds_read_b128 v[168:171], v212
	ds_read_b128 v[172:175], v212 offset:1024
	ds_read_b128 v[176:179], v212 offset:2048
	ds_read_b128 v[180:183], v212 offset:3072
	ds_read_b128 v[184:187], v212 offset:4096
	ds_read_b128 v[188:191], v212 offset:5120
	ds_read_b128 v[192:195], v212 offset:6144
	ds_read_b128 v[196:199], v212 offset:7168
	buffer_load_dwordx4 v208, s[12:15], s18 offen lds
	s_mov_b32 m0, s66
	s_nop 0
	buffer_load_dwordx4 v208, s[12:15], s77 offen lds
	s_waitcnt vmcnt(8) lgkmcnt(0)
	v_mfma_f32_16x16x32_bf16 v[126:129], v[134:137], v[168:171], v[126:129]
	s_barrier
	v_mfma_f32_16x16x32_bf16 v[126:129], v[138:141], v[172:175], v[126:129]
	v_mfma_f32_16x16x32_bf16 v[122:125], v[142:145], v[168:171], v[122:125]
	v_mfma_f32_16x16x32_bf16 v[122:125], v[148:151], v[172:175], v[122:125]
	v_mfma_f32_16x16x32_bf16 v[110:113], v[152:155], v[168:171], v[110:113]
	v_mfma_f32_16x16x32_bf16 v[110:113], v[156:159], v[172:175], v[110:113]
	v_mfma_f32_16x16x32_bf16 v[102:105], v[160:163], v[168:171], v[102:105]
	v_mfma_f32_16x16x32_bf16 v[102:105], v[164:167], v[172:175], v[102:105]
	v_mfma_f32_16x16x32_bf16 v[86:89], v[160:163], v[176:179], v[86:89]
	v_mfma_f32_16x16x32_bf16 v[86:89], v[164:167], v[180:183], v[86:89]
	v_mfma_f32_16x16x32_bf16 v[94:97], v[152:155], v[176:179], v[94:97]
	v_mfma_f32_16x16x32_bf16 v[94:97], v[156:159], v[180:183], v[94:97]
	v_mfma_f32_16x16x32_bf16 v[114:117], v[142:145], v[176:179], v[114:117]
	v_mfma_f32_16x16x32_bf16 v[114:117], v[148:151], v[180:183], v[114:117]
	v_mfma_f32_16x16x32_bf16 v[118:121], v[134:137], v[176:179], v[118:121]
	v_mfma_f32_16x16x32_bf16 v[118:121], v[138:141], v[180:183], v[118:121]
	v_mfma_f32_16x16x32_bf16 v[106:109], v[134:137], v[184:187], v[106:109]
	v_mfma_f32_16x16x32_bf16 v[106:109], v[138:141], v[188:191], v[106:109]
	v_mfma_f32_16x16x32_bf16 v[98:101], v[142:145], v[184:187], v[98:101]
	v_mfma_f32_16x16x32_bf16 v[98:101], v[148:151], v[188:191], v[98:101]
	v_mfma_f32_16x16x32_bf16 v[78:81], v[152:155], v[184:187], v[78:81]
	v_mfma_f32_16x16x32_bf16 v[78:81], v[156:159], v[188:191], v[78:81]
	v_mfma_f32_16x16x32_bf16 v[74:77], v[160:163], v[184:187], v[74:77]
	v_mfma_f32_16x16x32_bf16 v[74:77], v[164:167], v[188:191], v[74:77]
	v_mfma_f32_16x16x32_bf16 v[66:69], v[160:163], v[192:195], v[66:69]
	v_mfma_f32_16x16x32_bf16 v[66:69], v[164:167], v[196:199], v[66:69]
	v_mfma_f32_16x16x32_bf16 v[70:73], v[152:155], v[192:195], v[70:73]
	v_mfma_f32_16x16x32_bf16 v[70:73], v[156:159], v[196:199], v[70:73]
	v_mfma_f32_16x16x32_bf16 v[82:85], v[142:145], v[192:195], v[82:85]
	v_mfma_f32_16x16x32_bf16 v[82:85], v[148:151], v[196:199], v[82:85]
	v_mfma_f32_16x16x32_bf16 v[90:93], v[134:137], v[192:195], v[90:93]
	v_mfma_f32_16x16x32_bf16 v[90:93], v[138:141], v[196:199], v[90:93]
	s_barrier
	s_mov_b32 m0, s25
	s_mov_b32 s18, s14
	s_mov_b32 s19, s15
	ds_read_b128 v[168:171], v212 offset:16384
	ds_read_b128 v[172:175], v212 offset:17408
	ds_read_b128 v[176:179], v212 offset:18432
	ds_read_b128 v[180:183], v212 offset:19456
	ds_read_b128 v[184:187], v212 offset:20480
	ds_read_b128 v[188:191], v212 offset:21504
	ds_read_b128 v[192:195], v212 offset:22528
	ds_read_b128 v[196:199], v212 offset:23552
	buffer_load_dwordx4 v209, s[16:19], s82 offen lds
	s_mov_b32 m0, s27
	s_add_i32 s83, s82, 0x158000
	buffer_load_dwordx4 v209, s[16:19], s83 offen lds
	s_mov_b32 m0, s30
	s_add_i32 s83, s82, 0x2b0000
	buffer_load_dwordx4 v209, s[16:19], s83 offen lds
	s_mov_b32 m0, s31
	s_add_i32 s83, s82, 0x408000
	buffer_load_dwordx4 v209, s[16:19], s83 offen lds
	s_mov_b32 m0, s21
	s_add_i32 s83, s80, 0x158000
	buffer_load_dwordx4 v208, s[12:15], s80 offen lds
	s_mov_b32 m0, s48
	s_nop 0
	buffer_load_dwordx4 v208, s[12:15], s83 offen lds
	s_waitcnt vmcnt(8) lgkmcnt(0)
	v_mfma_f32_16x16x32_bf16 v[62:65], v[134:137], v[168:171], v[62:65]
	s_barrier
	v_mfma_f32_16x16x32_bf16 v[62:65], v[138:141], v[172:175], v[62:65]
	v_mfma_f32_16x16x32_bf16 v[58:61], v[142:145], v[168:171], v[58:61]
	v_mfma_f32_16x16x32_bf16 v[58:61], v[148:151], v[172:175], v[58:61]
	v_mfma_f32_16x16x32_bf16 v[46:49], v[152:155], v[168:171], v[46:49]
	v_mfma_f32_16x16x32_bf16 v[46:49], v[156:159], v[172:175], v[46:49]
	v_mfma_f32_16x16x32_bf16 v[38:41], v[160:163], v[168:171], v[38:41]
	v_mfma_f32_16x16x32_bf16 v[38:41], v[164:167], v[172:175], v[38:41]
	v_mfma_f32_16x16x32_bf16 v[22:25], v[160:163], v[176:179], v[22:25]
	v_mfma_f32_16x16x32_bf16 v[22:25], v[164:167], v[180:183], v[22:25]
	v_mfma_f32_16x16x32_bf16 v[30:33], v[152:155], v[176:179], v[30:33]
	v_mfma_f32_16x16x32_bf16 v[30:33], v[156:159], v[180:183], v[30:33]
	v_mfma_f32_16x16x32_bf16 v[50:53], v[142:145], v[176:179], v[50:53]
	v_mfma_f32_16x16x32_bf16 v[50:53], v[148:151], v[180:183], v[50:53]
	v_mfma_f32_16x16x32_bf16 v[54:57], v[134:137], v[176:179], v[54:57]
	v_mfma_f32_16x16x32_bf16 v[54:57], v[138:141], v[180:183], v[54:57]
	v_mfma_f32_16x16x32_bf16 v[42:45], v[134:137], v[184:187], v[42:45]
	v_mfma_f32_16x16x32_bf16 v[42:45], v[138:141], v[188:191], v[42:45]
	v_mfma_f32_16x16x32_bf16 v[34:37], v[142:145], v[184:187], v[34:37]
	v_mfma_f32_16x16x32_bf16 v[34:37], v[148:151], v[188:191], v[34:37]
	v_mfma_f32_16x16x32_bf16 v[14:17], v[152:155], v[184:187], v[14:17]
	v_mfma_f32_16x16x32_bf16 v[14:17], v[156:159], v[188:191], v[14:17]
	v_mfma_f32_16x16x32_bf16 v[10:13], v[160:163], v[184:187], v[10:13]
	v_mfma_f32_16x16x32_bf16 v[10:13], v[164:167], v[188:191], v[10:13]
	v_mfma_f32_16x16x32_bf16 v[2:5], v[160:163], v[192:195], v[2:5]
	v_mfma_f32_16x16x32_bf16 v[2:5], v[164:167], v[196:199], v[2:5]
	v_mfma_f32_16x16x32_bf16 v[6:9], v[152:155], v[192:195], v[6:9]
	v_mfma_f32_16x16x32_bf16 v[6:9], v[156:159], v[196:199], v[6:9]
	v_mfma_f32_16x16x32_bf16 v[18:21], v[142:145], v[192:195], v[18:21]
	v_mfma_f32_16x16x32_bf16 v[18:21], v[148:151], v[196:199], v[18:21]
	v_mfma_f32_16x16x32_bf16 v[26:29], v[134:137], v[192:195], v[26:29]
	v_mfma_f32_16x16x32_bf16 v[26:29], v[138:141], v[196:199], v[26:29]
	s_barrier
	ds_read_b128 v[134:137], v213
	ds_read_b128 v[138:141], v213 offset:1024
	ds_read_b128 v[142:145], v213 offset:2048
	ds_read_b128 v[148:151], v213 offset:3072
	ds_read_b128 v[152:155], v214
	ds_read_b128 v[156:159], v214 offset:1024
	ds_read_b128 v[160:163], v214 offset:2048
	ds_read_b128 v[164:167], v214 offset:3072
	s_mov_b32 m0, s49
	s_add_i32 s83, s80, 0x2b0000
	ds_read_b128 v[168:171], v212 offset:32768
	ds_read_b128 v[172:175], v212 offset:33792
	ds_read_b128 v[176:179], v212 offset:34816
	ds_read_b128 v[180:183], v212 offset:35840
	ds_read_b128 v[184:187], v212 offset:36864
	ds_read_b128 v[188:191], v212 offset:37888
	ds_read_b128 v[192:195], v212 offset:38912
	ds_read_b128 v[196:199], v212 offset:39936
	buffer_load_dwordx4 v208, s[12:15], s83 offen lds
	s_mov_b32 m0, s50
	s_add_i32 s83, s80, 0x408000
	buffer_load_dwordx4 v208, s[12:15], s83 offen lds
	s_waitcnt vmcnt(8) lgkmcnt(0)
	v_mfma_f32_16x16x32_bf16 v[126:129], v[134:137], v[168:171], v[126:129]
	s_barrier
	v_mfma_f32_16x16x32_bf16 v[126:129], v[138:141], v[172:175], v[126:129]
	v_mfma_f32_16x16x32_bf16 v[122:125], v[142:145], v[168:171], v[122:125]
	v_mfma_f32_16x16x32_bf16 v[122:125], v[148:151], v[172:175], v[122:125]
	v_mfma_f32_16x16x32_bf16 v[110:113], v[152:155], v[168:171], v[110:113]
	v_mfma_f32_16x16x32_bf16 v[110:113], v[156:159], v[172:175], v[110:113]
	v_mfma_f32_16x16x32_bf16 v[102:105], v[160:163], v[168:171], v[102:105]
	v_mfma_f32_16x16x32_bf16 v[102:105], v[164:167], v[172:175], v[102:105]
	v_mfma_f32_16x16x32_bf16 v[86:89], v[160:163], v[176:179], v[86:89]
	v_mfma_f32_16x16x32_bf16 v[86:89], v[164:167], v[180:183], v[86:89]
	v_mfma_f32_16x16x32_bf16 v[94:97], v[152:155], v[176:179], v[94:97]
	v_mfma_f32_16x16x32_bf16 v[94:97], v[156:159], v[180:183], v[94:97]
	v_mfma_f32_16x16x32_bf16 v[114:117], v[142:145], v[176:179], v[114:117]
	v_mfma_f32_16x16x32_bf16 v[114:117], v[148:151], v[180:183], v[114:117]
	v_mfma_f32_16x16x32_bf16 v[118:121], v[134:137], v[176:179], v[118:121]
	v_mfma_f32_16x16x32_bf16 v[118:121], v[138:141], v[180:183], v[118:121]
	v_mfma_f32_16x16x32_bf16 v[106:109], v[134:137], v[184:187], v[106:109]
	v_mfma_f32_16x16x32_bf16 v[106:109], v[138:141], v[188:191], v[106:109]
	v_mfma_f32_16x16x32_bf16 v[98:101], v[142:145], v[184:187], v[98:101]
	v_mfma_f32_16x16x32_bf16 v[98:101], v[148:151], v[188:191], v[98:101]
	v_mfma_f32_16x16x32_bf16 v[78:81], v[152:155], v[184:187], v[78:81]
	v_mfma_f32_16x16x32_bf16 v[78:81], v[156:159], v[188:191], v[78:81]
	v_mfma_f32_16x16x32_bf16 v[74:77], v[160:163], v[184:187], v[74:77]
	v_mfma_f32_16x16x32_bf16 v[74:77], v[164:167], v[188:191], v[74:77]
	v_mfma_f32_16x16x32_bf16 v[66:69], v[160:163], v[192:195], v[66:69]
	v_mfma_f32_16x16x32_bf16 v[66:69], v[164:167], v[196:199], v[66:69]
	v_mfma_f32_16x16x32_bf16 v[70:73], v[152:155], v[192:195], v[70:73]
	v_mfma_f32_16x16x32_bf16 v[70:73], v[156:159], v[196:199], v[70:73]
	v_mfma_f32_16x16x32_bf16 v[82:85], v[142:145], v[192:195], v[82:85]
	v_mfma_f32_16x16x32_bf16 v[82:85], v[148:151], v[196:199], v[82:85]
	v_mfma_f32_16x16x32_bf16 v[90:93], v[134:137], v[192:195], v[90:93]
	v_mfma_f32_16x16x32_bf16 v[90:93], v[138:141], v[196:199], v[90:93]
	s_barrier
	s_mov_b32 m0, s54
	s_or_b32 s83, s82, 0x80
	ds_read_b128 v[168:171], v212 offset:49152
	ds_read_b128 v[172:175], v212 offset:50176
	ds_read_b128 v[176:179], v212 offset:51200
	ds_read_b128 v[180:183], v212 offset:52224
	ds_read_b128 v[184:187], v212 offset:53248
	ds_read_b128 v[188:191], v212 offset:54272
	ds_read_b128 v[192:195], v212 offset:55296
	ds_read_b128 v[196:199], v212 offset:56320
	buffer_load_dwordx4 v209, s[16:19], s83 offen lds
	s_add_i32 s83, s82, 0x158080
	s_mov_b32 m0, s55
	s_add_i32 s80, s80, 0x158080
	buffer_load_dwordx4 v209, s[16:19], s83 offen lds
	s_add_i32 s83, s82, 0x2b0080
	s_mov_b32 m0, s58
	s_add_i32 s82, s82, 0x408080
	buffer_load_dwordx4 v209, s[16:19], s83 offen lds
	s_mov_b32 m0, s59
	s_nop 0
	buffer_load_dwordx4 v209, s[16:19], s82 offen lds
	s_mov_b32 m0, s56
	s_nop 0
	buffer_load_dwordx4 v208, s[12:15], s81 offen lds
	s_mov_b32 m0, s57
	s_nop 0
	buffer_load_dwordx4 v208, s[12:15], s80 offen lds
	s_waitcnt vmcnt(8) lgkmcnt(0)
	v_mfma_f32_16x16x32_bf16 v[62:65], v[134:137], v[168:171], v[62:65]
	s_barrier
	v_mfma_f32_16x16x32_bf16 v[62:65], v[138:141], v[172:175], v[62:65]
	v_mfma_f32_16x16x32_bf16 v[58:61], v[142:145], v[168:171], v[58:61]
	v_mfma_f32_16x16x32_bf16 v[58:61], v[148:151], v[172:175], v[58:61]
	v_mfma_f32_16x16x32_bf16 v[46:49], v[152:155], v[168:171], v[46:49]
	v_mfma_f32_16x16x32_bf16 v[46:49], v[156:159], v[172:175], v[46:49]
	v_mfma_f32_16x16x32_bf16 v[38:41], v[160:163], v[168:171], v[38:41]
	v_mfma_f32_16x16x32_bf16 v[38:41], v[164:167], v[172:175], v[38:41]
	v_mfma_f32_16x16x32_bf16 v[22:25], v[160:163], v[176:179], v[22:25]
	v_mfma_f32_16x16x32_bf16 v[22:25], v[164:167], v[180:183], v[22:25]
	v_mfma_f32_16x16x32_bf16 v[30:33], v[152:155], v[176:179], v[30:33]
	v_mfma_f32_16x16x32_bf16 v[30:33], v[156:159], v[180:183], v[30:33]
	v_mfma_f32_16x16x32_bf16 v[50:53], v[142:145], v[176:179], v[50:53]
	v_mfma_f32_16x16x32_bf16 v[50:53], v[148:151], v[180:183], v[50:53]
	v_mfma_f32_16x16x32_bf16 v[54:57], v[134:137], v[176:179], v[54:57]
	v_mfma_f32_16x16x32_bf16 v[54:57], v[138:141], v[180:183], v[54:57]
	v_mfma_f32_16x16x32_bf16 v[42:45], v[134:137], v[184:187], v[42:45]
	v_mfma_f32_16x16x32_bf16 v[42:45], v[138:141], v[188:191], v[42:45]
	v_mfma_f32_16x16x32_bf16 v[34:37], v[142:145], v[184:187], v[34:37]
	v_mfma_f32_16x16x32_bf16 v[34:37], v[148:151], v[188:191], v[34:37]
	v_mfma_f32_16x16x32_bf16 v[14:17], v[152:155], v[184:187], v[14:17]
	v_mfma_f32_16x16x32_bf16 v[14:17], v[156:159], v[188:191], v[14:17]
	v_mfma_f32_16x16x32_bf16 v[10:13], v[160:163], v[184:187], v[10:13]
	v_mfma_f32_16x16x32_bf16 v[10:13], v[164:167], v[188:191], v[10:13]
	v_mfma_f32_16x16x32_bf16 v[2:5], v[160:163], v[192:195], v[2:5]
	v_mfma_f32_16x16x32_bf16 v[2:5], v[164:167], v[196:199], v[2:5]
	v_mfma_f32_16x16x32_bf16 v[6:9], v[152:155], v[192:195], v[6:9]
	v_mfma_f32_16x16x32_bf16 v[6:9], v[156:159], v[196:199], v[6:9]
	v_mfma_f32_16x16x32_bf16 v[18:21], v[142:145], v[192:195], v[18:21]
	v_mfma_f32_16x16x32_bf16 v[18:21], v[148:151], v[196:199], v[18:21]
	v_mfma_f32_16x16x32_bf16 v[26:29], v[134:137], v[192:195], v[26:29]
	v_mfma_f32_16x16x32_bf16 v[26:29], v[138:141], v[196:199], v[26:29]
	s_barrier
	s_add_i32 s79, s79, 2
	s_addk_i32 s77, 0x100
	s_addk_i32 s78, 0x100
	s_cmp_ge_i32 s79, s3
	s_cbranch_scc0 .LBB0_799
	v_pk_mul_f32 v[184:185], v[128:129], 0.5 op_sel_hi:[1,0]
	v_pk_mul_f32 v[186:187], v[126:127], 0.5 op_sel_hi:[1,0]
	v_pk_mul_f32 v[188:189], v[124:125], 0.5 op_sel_hi:[1,0]
	v_pk_mul_f32 v[190:191], v[122:123], 0.5 op_sel_hi:[1,0]
	v_pk_mul_f32 v[198:199], v[112:113], 0.5 op_sel_hi:[1,0]
	v_pk_mul_f32 v[196:197], v[110:111], 0.5 op_sel_hi:[1,0]
	v_pk_mul_f32 v[194:195], v[104:105], 0.5 op_sel_hi:[1,0]
	v_pk_mul_f32 v[192:193], v[102:103], 0.5 op_sel_hi:[1,0]
	v_pk_mul_f32 v[182:183], v[120:121], 0.5 op_sel_hi:[1,0]
	v_pk_mul_f32 v[180:181], v[118:119], 0.5 op_sel_hi:[1,0]
	v_pk_mul_f32 v[178:179], v[116:117], 0.5 op_sel_hi:[1,0]
	v_pk_mul_f32 v[176:177], v[114:115], 0.5 op_sel_hi:[1,0]
	v_pk_mul_f32 v[172:173], v[96:97], 0.5 op_sel_hi:[1,0]
	v_pk_mul_f32 v[170:171], v[94:95], 0.5 op_sel_hi:[1,0]
	v_pk_mul_f32 v[168:169], v[88:89], 0.5 op_sel_hi:[1,0]
	v_pk_mul_f32 v[166:167], v[86:87], 0.5 op_sel_hi:[1,0]
	v_pk_mul_f32 v[164:165], v[108:109], 0.5 op_sel_hi:[1,0]
	v_pk_mul_f32 v[162:163], v[106:107], 0.5 op_sel_hi:[1,0]
	v_pk_mul_f32 v[160:161], v[100:101], 0.5 op_sel_hi:[1,0]
	v_pk_mul_f32 v[158:159], v[98:99], 0.5 op_sel_hi:[1,0]
	v_pk_mul_f32 v[156:157], v[80:81], 0.5 op_sel_hi:[1,0]
	v_pk_mul_f32 v[154:155], v[78:79], 0.5 op_sel_hi:[1,0]
	v_pk_mul_f32 v[152:153], v[76:77], 0.5 op_sel_hi:[1,0]
	v_pk_mul_f32 v[150:151], v[74:75], 0.5 op_sel_hi:[1,0]
	v_pk_mul_f32 v[144:145], v[92:93], 0.5 op_sel_hi:[1,0]
	v_pk_mul_f32 v[142:143], v[90:91], 0.5 op_sel_hi:[1,0]
	v_pk_mul_f32 v[140:141], v[84:85], 0.5 op_sel_hi:[1,0]
	v_pk_mul_f32 v[138:139], v[82:83], 0.5 op_sel_hi:[1,0]
	v_pk_mul_f32 v[136:137], v[72:73], 0.5 op_sel_hi:[1,0]
	v_pk_mul_f32 v[134:135], v[70:71], 0.5 op_sel_hi:[1,0]
	v_pk_mul_f32 v[128:129], v[68:69], 0.5 op_sel_hi:[1,0]
	v_pk_mul_f32 v[126:127], v[66:67], 0.5 op_sel_hi:[1,0]
	v_pk_mul_f32 v[122:123], v[64:65], 0.5 op_sel_hi:[1,0]
	v_pk_mul_f32 v[120:121], v[62:63], 0.5 op_sel_hi:[1,0]
	v_pk_mul_f32 v[118:119], v[60:61], 0.5 op_sel_hi:[1,0]
	v_pk_mul_f32 v[116:117], v[58:59], 0.5 op_sel_hi:[1,0]
	v_pk_mul_f32 v[112:113], v[48:49], 0.5 op_sel_hi:[1,0]
	v_pk_mul_f32 v[110:111], v[46:47], 0.5 op_sel_hi:[1,0]
	v_pk_mul_f32 v[108:109], v[40:41], 0.5 op_sel_hi:[1,0]
	v_pk_mul_f32 v[106:107], v[38:39], 0.5 op_sel_hi:[1,0]
	v_pk_mul_f32 v[104:105], v[56:57], 0.5 op_sel_hi:[1,0]
	v_pk_mul_f32 v[102:103], v[54:55], 0.5 op_sel_hi:[1,0]
	v_pk_mul_f32 v[100:101], v[52:53], 0.5 op_sel_hi:[1,0]
	v_pk_mul_f32 v[98:99], v[50:51], 0.5 op_sel_hi:[1,0]
	v_pk_mul_f32 v[96:97], v[32:33], 0.5 op_sel_hi:[1,0]
	v_pk_mul_f32 v[94:95], v[30:31], 0.5 op_sel_hi:[1,0]
	v_pk_mul_f32 v[92:93], v[24:25], 0.5 op_sel_hi:[1,0]
	v_pk_mul_f32 v[90:91], v[22:23], 0.5 op_sel_hi:[1,0]
	v_pk_mul_f32 v[88:89], v[44:45], 0.5 op_sel_hi:[1,0]
	v_pk_mul_f32 v[86:87], v[42:43], 0.5 op_sel_hi:[1,0]
	v_pk_mul_f32 v[84:85], v[36:37], 0.5 op_sel_hi:[1,0]
	v_pk_mul_f32 v[82:83], v[34:35], 0.5 op_sel_hi:[1,0]
	v_pk_mul_f32 v[80:81], v[16:17], 0.5 op_sel_hi:[1,0]
	v_pk_mul_f32 v[78:79], v[14:15], 0.5 op_sel_hi:[1,0]
	v_pk_mul_f32 v[76:77], v[12:13], 0.5 op_sel_hi:[1,0]
	v_pk_mul_f32 v[74:75], v[10:11], 0.5 op_sel_hi:[1,0]
	v_pk_mul_f32 v[72:73], v[28:29], 0.5 op_sel_hi:[1,0]
	v_pk_mul_f32 v[70:71], v[26:27], 0.5 op_sel_hi:[1,0]
	v_pk_mul_f32 v[68:69], v[20:21], 0.5 op_sel_hi:[1,0]
	v_pk_mul_f32 v[66:67], v[18:19], 0.5 op_sel_hi:[1,0]
	v_pk_mul_f32 v[64:65], v[8:9], 0.5 op_sel_hi:[1,0]
	v_pk_mul_f32 v[62:63], v[6:7], 0.5 op_sel_hi:[1,0]
	v_pk_mul_f32 v[60:61], v[4:5], 0.5 op_sel_hi:[1,0]
	v_pk_mul_f32 v[58:59], v[2:3], 0.5 op_sel_hi:[1,0]
	s_and_b64 vcc, exec, s[38:39]
	s_cbranch_vccz .LBB0_802

.LBB0_892:
	ds_read_b128 v[130:133], v172
	ds_read_b128 v[134:137], v172 offset:1024
	ds_read_b128 v[148:151], v172 offset:2048
	ds_read_b128 v[152:155], v172 offset:3072
	ds_read_b128 v[156:159], v173
	ds_read_b128 v[160:163], v173 offset:1024
	ds_read_b128 v[164:167], v173 offset:2048
	ds_read_b128 v[180:183], v173 offset:3072
	s_add_i32 s18, s8, 0xffe80080
	s_cmp_eq_u32 s77, s52
	s_cselect_b32 s53, s6, s18
	s_cselect_b32 s58, s7, s9
	s_or_b32 s57, s53, 0x80
	s_add_i32 s18, s8, 0xfff80000
	s_mov_b32 m0, s78
	ds_read_b128 v[184:187], v174
	ds_read_b128 v[188:191], v174 offset:1024
	ds_read_b128 v[192:195], v174 offset:2048
	ds_read_b128 v[196:199], v174 offset:3072
	ds_read_b128 v[200:203], v174 offset:4096
	ds_read_b128 v[204:207], v174 offset:5120
	ds_read_b128 v[208:211], v174 offset:6144
	ds_read_b128 v[212:215], v174 offset:7168
	buffer_load_dwordx4 v170, s[12:15], s18 offen lds
	s_mov_b32 m0, s79
	s_nop 0
	buffer_load_dwordx4 v170, s[12:15], s8 offen lds
	s_waitcnt vmcnt(8) lgkmcnt(0)
	v_mfma_f32_16x16x32_bf16 v[126:129], v[130:133], v[184:187], v[126:129]
	s_barrier
	v_mfma_f32_16x16x32_bf16 v[126:129], v[134:137], v[188:191], v[126:129]
	v_mfma_f32_16x16x32_bf16 v[118:121], v[148:151], v[184:187], v[118:121]
	v_mfma_f32_16x16x32_bf16 v[118:121], v[152:155], v[188:191], v[118:121]
	v_mfma_f32_16x16x32_bf16 v[122:125], v[156:159], v[184:187], v[122:125]
	v_mfma_f32_16x16x32_bf16 v[122:125], v[160:163], v[188:191], v[122:125]
	v_mfma_f32_16x16x32_bf16 v[114:117], v[164:167], v[184:187], v[114:117]
	v_mfma_f32_16x16x32_bf16 v[114:117], v[180:183], v[188:191], v[114:117]
	v_mfma_f32_16x16x32_bf16 v[98:101], v[164:167], v[192:195], v[98:101]
	v_mfma_f32_16x16x32_bf16 v[98:101], v[180:183], v[196:199], v[98:101]
	v_mfma_f32_16x16x32_bf16 v[106:109], v[156:159], v[192:195], v[106:109]
	v_mfma_f32_16x16x32_bf16 v[106:109], v[160:163], v[196:199], v[106:109]
	v_mfma_f32_16x16x32_bf16 v[102:105], v[148:151], v[192:195], v[102:105]
	v_mfma_f32_16x16x32_bf16 v[102:105], v[152:155], v[196:199], v[102:105]
	v_mfma_f32_16x16x32_bf16 v[110:113], v[130:133], v[192:195], v[110:113]
	v_mfma_f32_16x16x32_bf16 v[110:113], v[134:137], v[196:199], v[110:113]
	v_mfma_f32_16x16x32_bf16 v[94:97], v[130:133], v[200:203], v[94:97]
	v_mfma_f32_16x16x32_bf16 v[94:97], v[134:137], v[204:207], v[94:97]
	v_mfma_f32_16x16x32_bf16 v[90:93], v[148:151], v[200:203], v[90:93]
	v_mfma_f32_16x16x32_bf16 v[90:93], v[152:155], v[204:207], v[90:93]
	v_mfma_f32_16x16x32_bf16 v[86:89], v[156:159], v[200:203], v[86:89]
	v_mfma_f32_16x16x32_bf16 v[86:89], v[160:163], v[204:207], v[86:89]
	v_mfma_f32_16x16x32_bf16 v[82:85], v[164:167], v[200:203], v[82:85]
	v_mfma_f32_16x16x32_bf16 v[82:85], v[180:183], v[204:207], v[82:85]
	v_mfma_f32_16x16x32_bf16 v[66:69], v[164:167], v[208:211], v[66:69]
	v_mfma_f32_16x16x32_bf16 v[66:69], v[180:183], v[212:215], v[66:69]
	v_mfma_f32_16x16x32_bf16 v[74:77], v[156:159], v[208:211], v[74:77]
	v_mfma_f32_16x16x32_bf16 v[74:77], v[160:163], v[212:215], v[74:77]
	v_mfma_f32_16x16x32_bf16 v[70:73], v[148:151], v[208:211], v[70:73]
	v_mfma_f32_16x16x32_bf16 v[70:73], v[152:155], v[212:215], v[70:73]
	v_mfma_f32_16x16x32_bf16 v[78:81], v[130:133], v[208:211], v[78:81]
	v_mfma_f32_16x16x32_bf16 v[78:81], v[134:137], v[212:215], v[78:81]
	s_barrier
	s_mov_b32 m0, s27
	s_mov_b32 s18, s14
	s_mov_b32 s19, s15
	ds_read_b128 v[184:187], v174 offset:16384
	ds_read_b128 v[188:191], v174 offset:17408
	ds_read_b128 v[192:195], v174 offset:18432
	ds_read_b128 v[196:199], v174 offset:19456
	ds_read_b128 v[200:203], v174 offset:20480
	ds_read_b128 v[204:207], v174 offset:21504
	ds_read_b128 v[208:211], v174 offset:22528
	ds_read_b128 v[212:215], v174 offset:23552
	buffer_load_dwordx4 v171, s[16:19], s58 offen lds
	s_mov_b32 m0, s60
	s_add_i32 s59, s58, 0x80000
	buffer_load_dwordx4 v171, s[16:19], s59 offen lds
	s_mov_b32 m0, s61
	s_add_i32 s59, s58, 0x100000
	buffer_load_dwordx4 v171, s[16:19], s59 offen lds
	s_mov_b32 m0, s62
	s_add_i32 s59, s58, 0x180000
	buffer_load_dwordx4 v171, s[16:19], s59 offen lds
	s_mov_b32 m0, s25
	s_add_i32 s59, s53, 0x80000
	buffer_load_dwordx4 v170, s[12:15], s53 offen lds
	s_mov_b32 m0, s63
	s_nop 0
	buffer_load_dwordx4 v170, s[12:15], s59 offen lds
	s_waitcnt vmcnt(8) lgkmcnt(0)
	v_mfma_f32_16x16x32_bf16 v[62:65], v[130:133], v[184:187], v[62:65]
	s_barrier
	v_mfma_f32_16x16x32_bf16 v[62:65], v[134:137], v[188:191], v[62:65]
	v_mfma_f32_16x16x32_bf16 v[54:57], v[148:151], v[184:187], v[54:57]
	v_mfma_f32_16x16x32_bf16 v[54:57], v[152:155], v[188:191], v[54:57]
	v_mfma_f32_16x16x32_bf16 v[58:61], v[156:159], v[184:187], v[58:61]
	v_mfma_f32_16x16x32_bf16 v[58:61], v[160:163], v[188:191], v[58:61]
	v_mfma_f32_16x16x32_bf16 v[50:53], v[164:167], v[184:187], v[50:53]
	v_mfma_f32_16x16x32_bf16 v[50:53], v[180:183], v[188:191], v[50:53]
	v_mfma_f32_16x16x32_bf16 v[34:37], v[164:167], v[192:195], v[34:37]
	v_mfma_f32_16x16x32_bf16 v[34:37], v[180:183], v[196:199], v[34:37]
	v_mfma_f32_16x16x32_bf16 v[42:45], v[156:159], v[192:195], v[42:45]
	v_mfma_f32_16x16x32_bf16 v[42:45], v[160:163], v[196:199], v[42:45]
	v_mfma_f32_16x16x32_bf16 v[38:41], v[148:151], v[192:195], v[38:41]
	v_mfma_f32_16x16x32_bf16 v[38:41], v[152:155], v[196:199], v[38:41]
	v_mfma_f32_16x16x32_bf16 v[46:49], v[130:133], v[192:195], v[46:49]
	v_mfma_f32_16x16x32_bf16 v[46:49], v[134:137], v[196:199], v[46:49]
	v_mfma_f32_16x16x32_bf16 v[30:33], v[130:133], v[200:203], v[30:33]
	v_mfma_f32_16x16x32_bf16 v[30:33], v[134:137], v[204:207], v[30:33]
	v_mfma_f32_16x16x32_bf16 v[22:25], v[148:151], v[200:203], v[22:25]
	v_mfma_f32_16x16x32_bf16 v[22:25], v[152:155], v[204:207], v[22:25]
	v_mfma_f32_16x16x32_bf16 v[26:29], v[156:159], v[200:203], v[26:29]
	v_mfma_f32_16x16x32_bf16 v[26:29], v[160:163], v[204:207], v[26:29]
	v_mfma_f32_16x16x32_bf16 v[18:21], v[164:167], v[200:203], v[18:21]
	v_mfma_f32_16x16x32_bf16 v[18:21], v[180:183], v[204:207], v[18:21]
	v_mfma_f32_16x16x32_bf16 v[2:5], v[164:167], v[208:211], v[2:5]
	v_mfma_f32_16x16x32_bf16 v[2:5], v[180:183], v[212:215], v[2:5]
	v_mfma_f32_16x16x32_bf16 v[10:13], v[156:159], v[208:211], v[10:13]
	v_mfma_f32_16x16x32_bf16 v[10:13], v[160:163], v[212:215], v[10:13]
	v_mfma_f32_16x16x32_bf16 v[6:9], v[148:151], v[208:211], v[6:9]
	v_mfma_f32_16x16x32_bf16 v[6:9], v[152:155], v[212:215], v[6:9]
	v_mfma_f32_16x16x32_bf16 v[14:17], v[130:133], v[208:211], v[14:17]
	v_mfma_f32_16x16x32_bf16 v[14:17], v[134:137], v[212:215], v[14:17]
	s_barrier
	ds_read_b128 v[130:133], v175
	ds_read_b128 v[134:137], v175 offset:1024
	ds_read_b128 v[148:151], v175 offset:2048
	ds_read_b128 v[152:155], v175 offset:3072
	ds_read_b128 v[156:159], v176
	ds_read_b128 v[160:163], v176 offset:1024
	ds_read_b128 v[164:167], v176 offset:2048
	ds_read_b128 v[180:183], v176 offset:3072
	s_mov_b32 m0, s64
	s_add_i32 s59, s53, 0x100000
	ds_read_b128 v[184:187], v174 offset:32768
	ds_read_b128 v[188:191], v174 offset:33792
	ds_read_b128 v[192:195], v174 offset:34816
	ds_read_b128 v[196:199], v174 offset:35840
	ds_read_b128 v[200:203], v174 offset:36864
	ds_read_b128 v[204:207], v174 offset:37888
	ds_read_b128 v[208:211], v174 offset:38912
	ds_read_b128 v[212:215], v174 offset:39936
	buffer_load_dwordx4 v170, s[12:15], s59 offen lds
	s_mov_b32 m0, s65
	s_add_i32 s59, s53, 0x180000
	buffer_load_dwordx4 v170, s[12:15], s59 offen lds
	s_waitcnt vmcnt(8) lgkmcnt(0)
	v_mfma_f32_16x16x32_bf16 v[126:129], v[130:133], v[184:187], v[126:129]
	s_barrier
	v_mfma_f32_16x16x32_bf16 v[126:129], v[134:137], v[188:191], v[126:129]
	v_mfma_f32_16x16x32_bf16 v[118:121], v[148:151], v[184:187], v[118:121]
	v_mfma_f32_16x16x32_bf16 v[118:121], v[152:155], v[188:191], v[118:121]
	v_mfma_f32_16x16x32_bf16 v[122:125], v[156:159], v[184:187], v[122:125]
	v_mfma_f32_16x16x32_bf16 v[122:125], v[160:163], v[188:191], v[122:125]
	v_mfma_f32_16x16x32_bf16 v[114:117], v[164:167], v[184:187], v[114:117]
	v_mfma_f32_16x16x32_bf16 v[114:117], v[180:183], v[188:191], v[114:117]
	v_mfma_f32_16x16x32_bf16 v[98:101], v[164:167], v[192:195], v[98:101]
	v_mfma_f32_16x16x32_bf16 v[98:101], v[180:183], v[196:199], v[98:101]
	v_mfma_f32_16x16x32_bf16 v[106:109], v[156:159], v[192:195], v[106:109]
	v_mfma_f32_16x16x32_bf16 v[106:109], v[160:163], v[196:199], v[106:109]
	v_mfma_f32_16x16x32_bf16 v[102:105], v[148:151], v[192:195], v[102:105]
	v_mfma_f32_16x16x32_bf16 v[102:105], v[152:155], v[196:199], v[102:105]
	v_mfma_f32_16x16x32_bf16 v[110:113], v[130:133], v[192:195], v[110:113]
	v_mfma_f32_16x16x32_bf16 v[110:113], v[134:137], v[196:199], v[110:113]
	v_mfma_f32_16x16x32_bf16 v[94:97], v[130:133], v[200:203], v[94:97]
	v_mfma_f32_16x16x32_bf16 v[94:97], v[134:137], v[204:207], v[94:97]
	v_mfma_f32_16x16x32_bf16 v[90:93], v[148:151], v[200:203], v[90:93]
	v_mfma_f32_16x16x32_bf16 v[90:93], v[152:155], v[204:207], v[90:93]
	v_mfma_f32_16x16x32_bf16 v[86:89], v[156:159], v[200:203], v[86:89]
	v_mfma_f32_16x16x32_bf16 v[86:89], v[160:163], v[204:207], v[86:89]
	v_mfma_f32_16x16x32_bf16 v[82:85], v[164:167], v[200:203], v[82:85]
	v_mfma_f32_16x16x32_bf16 v[82:85], v[180:183], v[204:207], v[82:85]
	v_mfma_f32_16x16x32_bf16 v[66:69], v[164:167], v[208:211], v[66:69]
	v_mfma_f32_16x16x32_bf16 v[66:69], v[180:183], v[212:215], v[66:69]
	v_mfma_f32_16x16x32_bf16 v[74:77], v[156:159], v[208:211], v[74:77]
	v_mfma_f32_16x16x32_bf16 v[74:77], v[160:163], v[212:215], v[74:77]
	v_mfma_f32_16x16x32_bf16 v[70:73], v[148:151], v[208:211], v[70:73]
	v_mfma_f32_16x16x32_bf16 v[70:73], v[152:155], v[212:215], v[70:73]
	v_mfma_f32_16x16x32_bf16 v[78:81], v[130:133], v[208:211], v[78:81]
	v_mfma_f32_16x16x32_bf16 v[78:81], v[134:137], v[212:215], v[78:81]
	s_barrier
	s_mov_b32 m0, s70
	s_or_b32 s59, s58, 0x80
	ds_read_b128 v[184:187], v174 offset:49152
	ds_read_b128 v[188:191], v174 offset:50176
	ds_read_b128 v[192:195], v174 offset:51200
	ds_read_b128 v[196:199], v174 offset:52224
	ds_read_b128 v[200:203], v174 offset:53248
	ds_read_b128 v[204:207], v174 offset:54272
	ds_read_b128 v[208:211], v174 offset:55296
	ds_read_b128 v[212:215], v174 offset:56320
	buffer_load_dwordx4 v171, s[16:19], s59 offen lds
	s_add_i32 s59, s58, 0x80080
	s_mov_b32 m0, s71
	s_add_i32 s53, s53, 0x80080
	buffer_load_dwordx4 v171, s[16:19], s59 offen lds
	s_add_i32 s59, s58, 0x100080
	s_mov_b32 m0, s74
	s_add_i32 s58, s58, 0x180080
	buffer_load_dwordx4 v171, s[16:19], s59 offen lds
	s_mov_b32 m0, s75
	s_nop 0
	buffer_load_dwordx4 v171, s[16:19], s58 offen lds
	s_mov_b32 m0, s72
	s_nop 0
	buffer_load_dwordx4 v170, s[12:15], s57 offen lds
	s_mov_b32 m0, s73
	s_nop 0
	buffer_load_dwordx4 v170, s[12:15], s53 offen lds
	s_waitcnt vmcnt(8) lgkmcnt(0)
	v_mfma_f32_16x16x32_bf16 v[62:65], v[130:133], v[184:187], v[62:65]
	s_barrier
	v_mfma_f32_16x16x32_bf16 v[62:65], v[134:137], v[188:191], v[62:65]
	v_mfma_f32_16x16x32_bf16 v[54:57], v[148:151], v[184:187], v[54:57]
	v_mfma_f32_16x16x32_bf16 v[54:57], v[152:155], v[188:191], v[54:57]
	v_mfma_f32_16x16x32_bf16 v[58:61], v[156:159], v[184:187], v[58:61]
	v_mfma_f32_16x16x32_bf16 v[58:61], v[160:163], v[188:191], v[58:61]
	v_mfma_f32_16x16x32_bf16 v[50:53], v[164:167], v[184:187], v[50:53]
	v_mfma_f32_16x16x32_bf16 v[50:53], v[180:183], v[188:191], v[50:53]
	v_mfma_f32_16x16x32_bf16 v[34:37], v[164:167], v[192:195], v[34:37]
	v_mfma_f32_16x16x32_bf16 v[34:37], v[180:183], v[196:199], v[34:37]
	v_mfma_f32_16x16x32_bf16 v[42:45], v[156:159], v[192:195], v[42:45]
	v_mfma_f32_16x16x32_bf16 v[42:45], v[160:163], v[196:199], v[42:45]
	v_mfma_f32_16x16x32_bf16 v[38:41], v[148:151], v[192:195], v[38:41]
	v_mfma_f32_16x16x32_bf16 v[38:41], v[152:155], v[196:199], v[38:41]
	v_mfma_f32_16x16x32_bf16 v[46:49], v[130:133], v[192:195], v[46:49]
	v_mfma_f32_16x16x32_bf16 v[46:49], v[134:137], v[196:199], v[46:49]
	v_mfma_f32_16x16x32_bf16 v[30:33], v[130:133], v[200:203], v[30:33]
	v_mfma_f32_16x16x32_bf16 v[30:33], v[134:137], v[204:207], v[30:33]
	v_mfma_f32_16x16x32_bf16 v[22:25], v[148:151], v[200:203], v[22:25]
	v_mfma_f32_16x16x32_bf16 v[22:25], v[152:155], v[204:207], v[22:25]
	v_mfma_f32_16x16x32_bf16 v[26:29], v[156:159], v[200:203], v[26:29]
	v_mfma_f32_16x16x32_bf16 v[26:29], v[160:163], v[204:207], v[26:29]
	v_mfma_f32_16x16x32_bf16 v[18:21], v[164:167], v[200:203], v[18:21]
	v_mfma_f32_16x16x32_bf16 v[18:21], v[180:183], v[204:207], v[18:21]
	v_mfma_f32_16x16x32_bf16 v[2:5], v[164:167], v[208:211], v[2:5]
	v_mfma_f32_16x16x32_bf16 v[2:5], v[180:183], v[212:215], v[2:5]
	v_mfma_f32_16x16x32_bf16 v[10:13], v[156:159], v[208:211], v[10:13]
	v_mfma_f32_16x16x32_bf16 v[10:13], v[160:163], v[212:215], v[10:13]
	v_mfma_f32_16x16x32_bf16 v[6:9], v[148:151], v[208:211], v[6:9]
	v_mfma_f32_16x16x32_bf16 v[6:9], v[152:155], v[212:215], v[6:9]
	v_mfma_f32_16x16x32_bf16 v[14:17], v[130:133], v[208:211], v[14:17]
	v_mfma_f32_16x16x32_bf16 v[14:17], v[134:137], v[212:215], v[14:17]
	s_barrier
	s_add_i32 s52, s52, 2
	s_addk_i32 s8, 0x100
	s_addk_i32 s9, 0x100
	s_cmp_ge_i32 s52, s21
	s_cbranch_scc0 .LBB0_892
	s_and_b64 vcc, exec, s[48:49]
	s_cbranch_vccz .LBB0_895

.LBB0_1020:
	v_add_u32_e32 v142, 0x10000, v162
	v_add_u32_e32 v150, 0x14000, v162
	ds_read_b128 v[130:133], v142
	ds_read_b128 v[134:137], v142 offset:1024
	ds_read_b128 v[138:141], v142 offset:2048
	ds_read_b128 v[142:145], v142 offset:3072
	ds_read_b128 v[154:157], v150
	ds_read_b128 v[164:167], v150 offset:1024
	ds_read_b128 v[168:171], v150 offset:2048
	ds_read_b128 v[172:175], v150 offset:3072
	s_add_i32 s90, s6, 0x100
	s_add_i32 s7, s88, s6
	s_cmp_eq_u32 s81, s89
	s_cselect_b32 s91, 0, s90
	s_cselect_b32 s93, s87, s7
	s_add_i32 s91, s91, s70
	s_or_b32 s92, s91, 0x80
	s_add_i32 s6, s3, s6
	s_mov_b32 m0, s82
	s_add_i32 s7, s6, 0x20080
	ds_read_b128 v[176:179], v163
	ds_read_b128 v[180:183], v163 offset:1024
	ds_read_b128 v[184:187], v163 offset:2048
	ds_read_b128 v[188:191], v163 offset:3072
	ds_read_b128 v[192:195], v163 offset:4096
	ds_read_b128 v[196:199], v163 offset:5120
	ds_read_b128 v[200:203], v163 offset:6144
	ds_read_b128 v[204:207], v163 offset:7168
	buffer_load_dwordx4 v161, s[12:15], s7 offen lds
	s_mov_b32 m0, s83
	s_add_i32 s6, s6, 0x30080
	buffer_load_dwordx4 v161, s[12:15], s6 offen lds
	s_waitcnt vmcnt(8) lgkmcnt(0)
	v_mfma_f32_16x16x32_bf16 v[126:129], v[130:133], v[176:179], v[126:129]
	s_barrier
	v_mfma_f32_16x16x32_bf16 v[126:129], v[134:137], v[180:183], v[126:129]
	v_mfma_f32_16x16x32_bf16 v[122:125], v[138:141], v[176:179], v[122:125]
	v_mfma_f32_16x16x32_bf16 v[122:125], v[142:145], v[180:183], v[122:125]
	v_mfma_f32_16x16x32_bf16 v[118:121], v[154:157], v[176:179], v[118:121]
	v_mfma_f32_16x16x32_bf16 v[118:121], v[164:167], v[180:183], v[118:121]
	v_mfma_f32_16x16x32_bf16 v[114:117], v[168:171], v[176:179], v[114:117]
	v_mfma_f32_16x16x32_bf16 v[114:117], v[172:175], v[180:183], v[114:117]
	v_mfma_f32_16x16x32_bf16 v[98:101], v[168:171], v[184:187], v[98:101]
	v_mfma_f32_16x16x32_bf16 v[98:101], v[172:175], v[188:191], v[98:101]
	v_mfma_f32_16x16x32_bf16 v[102:105], v[154:157], v[184:187], v[102:105]
	v_mfma_f32_16x16x32_bf16 v[102:105], v[164:167], v[188:191], v[102:105]
	v_mfma_f32_16x16x32_bf16 v[106:109], v[138:141], v[184:187], v[106:109]
	v_mfma_f32_16x16x32_bf16 v[106:109], v[142:145], v[188:191], v[106:109]
	v_mfma_f32_16x16x32_bf16 v[110:113], v[130:133], v[184:187], v[110:113]
	v_mfma_f32_16x16x32_bf16 v[110:113], v[134:137], v[188:191], v[110:113]
	v_mfma_f32_16x16x32_bf16 v[94:97], v[130:133], v[192:195], v[94:97]
	v_mfma_f32_16x16x32_bf16 v[94:97], v[134:137], v[196:199], v[94:97]
	v_mfma_f32_16x16x32_bf16 v[90:93], v[138:141], v[192:195], v[90:93]
	v_mfma_f32_16x16x32_bf16 v[90:93], v[142:145], v[196:199], v[90:93]
	v_mfma_f32_16x16x32_bf16 v[86:89], v[154:157], v[192:195], v[86:89]
	v_mfma_f32_16x16x32_bf16 v[86:89], v[164:167], v[196:199], v[86:89]
	v_mfma_f32_16x16x32_bf16 v[82:85], v[168:171], v[192:195], v[82:85]
	v_mfma_f32_16x16x32_bf16 v[82:85], v[172:175], v[196:199], v[82:85]
	v_mfma_f32_16x16x32_bf16 v[66:69], v[168:171], v[200:203], v[66:69]
	v_mfma_f32_16x16x32_bf16 v[66:69], v[172:175], v[204:207], v[66:69]
	v_mfma_f32_16x16x32_bf16 v[70:73], v[154:157], v[200:203], v[70:73]
	v_mfma_f32_16x16x32_bf16 v[70:73], v[164:167], v[204:207], v[70:73]
	v_mfma_f32_16x16x32_bf16 v[74:77], v[138:141], v[200:203], v[74:77]
	v_mfma_f32_16x16x32_bf16 v[74:77], v[142:145], v[204:207], v[74:77]
	v_mfma_f32_16x16x32_bf16 v[78:81], v[130:133], v[200:203], v[78:81]
	v_mfma_f32_16x16x32_bf16 v[78:81], v[134:137], v[204:207], v[78:81]
	s_barrier
	s_mov_b32 m0, s66
	s_mov_b32 s6, s14
	s_mov_b32 s7, s15
	ds_read_b128 v[176:179], v163 offset:16384
	ds_read_b128 v[180:183], v163 offset:17408
	ds_read_b128 v[184:187], v163 offset:18432
	ds_read_b128 v[188:191], v163 offset:19456
	ds_read_b128 v[192:195], v163 offset:20480
	ds_read_b128 v[196:199], v163 offset:21504
	ds_read_b128 v[200:203], v163 offset:22528
	ds_read_b128 v[204:207], v163 offset:23552
	buffer_load_dwordx4 v160, s[4:7], s93 offen lds
	s_mov_b32 m0, s67
	s_add_i32 s94, s93, 0x10000
	buffer_load_dwordx4 v160, s[4:7], s94 offen lds
	s_mov_b32 m0, s68
	s_add_i32 s94, s93, 0x20000
	buffer_load_dwordx4 v160, s[4:7], s94 offen lds
	s_mov_b32 m0, s69
	s_add_i32 s94, s93, 0x30000
	buffer_load_dwordx4 v160, s[4:7], s94 offen lds
	s_mov_b32 m0, s65
	s_add_i32 s94, s91, 0x10000
	buffer_load_dwordx4 v161, s[12:15], s91 offen lds
	s_mov_b32 m0, s71
	s_nop 0
	buffer_load_dwordx4 v161, s[12:15], s94 offen lds
	s_waitcnt vmcnt(8) lgkmcnt(0)
	v_mfma_f32_16x16x32_bf16 v[62:65], v[130:133], v[176:179], v[62:65]
	s_barrier
	v_mfma_f32_16x16x32_bf16 v[62:65], v[134:137], v[180:183], v[62:65]
	v_mfma_f32_16x16x32_bf16 v[58:61], v[138:141], v[176:179], v[58:61]
	v_mfma_f32_16x16x32_bf16 v[58:61], v[142:145], v[180:183], v[58:61]
	v_mfma_f32_16x16x32_bf16 v[54:57], v[154:157], v[176:179], v[54:57]
	v_mfma_f32_16x16x32_bf16 v[54:57], v[164:167], v[180:183], v[54:57]
	v_mfma_f32_16x16x32_bf16 v[50:53], v[168:171], v[176:179], v[50:53]
	v_mfma_f32_16x16x32_bf16 v[50:53], v[172:175], v[180:183], v[50:53]
	v_mfma_f32_16x16x32_bf16 v[34:37], v[168:171], v[184:187], v[34:37]
	v_mfma_f32_16x16x32_bf16 v[34:37], v[172:175], v[188:191], v[34:37]
	v_mfma_f32_16x16x32_bf16 v[38:41], v[154:157], v[184:187], v[38:41]
	v_mfma_f32_16x16x32_bf16 v[38:41], v[164:167], v[188:191], v[38:41]
	v_mfma_f32_16x16x32_bf16 v[42:45], v[138:141], v[184:187], v[42:45]
	v_mfma_f32_16x16x32_bf16 v[42:45], v[142:145], v[188:191], v[42:45]
	v_mfma_f32_16x16x32_bf16 v[46:49], v[130:133], v[184:187], v[46:49]
	v_mfma_f32_16x16x32_bf16 v[46:49], v[134:137], v[188:191], v[46:49]
	v_mfma_f32_16x16x32_bf16 v[30:33], v[130:133], v[192:195], v[30:33]
	v_mfma_f32_16x16x32_bf16 v[30:33], v[134:137], v[196:199], v[30:33]
	v_mfma_f32_16x16x32_bf16 v[26:29], v[138:141], v[192:195], v[26:29]
	v_mfma_f32_16x16x32_bf16 v[26:29], v[142:145], v[196:199], v[26:29]
	v_mfma_f32_16x16x32_bf16 v[22:25], v[154:157], v[192:195], v[22:25]
	v_mfma_f32_16x16x32_bf16 v[22:25], v[164:167], v[196:199], v[22:25]
	v_mfma_f32_16x16x32_bf16 v[18:21], v[168:171], v[192:195], v[18:21]
	v_mfma_f32_16x16x32_bf16 v[18:21], v[172:175], v[196:199], v[18:21]
	v_mfma_f32_16x16x32_bf16 v[2:5], v[168:171], v[200:203], v[2:5]
	v_mfma_f32_16x16x32_bf16 v[2:5], v[172:175], v[204:207], v[2:5]
	v_mfma_f32_16x16x32_bf16 v[6:9], v[154:157], v[200:203], v[6:9]
	v_mfma_f32_16x16x32_bf16 v[6:9], v[164:167], v[204:207], v[6:9]
	v_mfma_f32_16x16x32_bf16 v[10:13], v[138:141], v[200:203], v[10:13]
	v_mfma_f32_16x16x32_bf16 v[10:13], v[142:145], v[204:207], v[10:13]
	v_mfma_f32_16x16x32_bf16 v[14:17], v[130:133], v[200:203], v[14:17]
	v_mfma_f32_16x16x32_bf16 v[14:17], v[134:137], v[204:207], v[14:17]
	s_barrier
	v_add_u32_e32 v142, 0x18000, v162
	v_add_u32_e32 v150, 0x1c000, v162
	ds_read_b128 v[130:133], v142
	ds_read_b128 v[134:137], v142 offset:1024
	ds_read_b128 v[138:141], v142 offset:2048
	ds_read_b128 v[142:145], v142 offset:3072
	ds_read_b128 v[154:157], v150
	ds_read_b128 v[164:167], v150 offset:1024
	ds_read_b128 v[168:171], v150 offset:2048
	ds_read_b128 v[172:175], v150 offset:3072
	s_mov_b32 m0, s72
	s_add_i32 s94, s91, 0x20000
	ds_read_b128 v[176:179], v163 offset:32768
	ds_read_b128 v[180:183], v163 offset:33792
	ds_read_b128 v[184:187], v163 offset:34816
	ds_read_b128 v[188:191], v163 offset:35840
	ds_read_b128 v[192:195], v163 offset:36864
	ds_read_b128 v[196:199], v163 offset:37888
	ds_read_b128 v[200:203], v163 offset:38912
	ds_read_b128 v[204:207], v163 offset:39936
	buffer_load_dwordx4 v161, s[12:15], s94 offen lds
	s_mov_b32 m0, s73
	s_add_i32 s94, s91, 0x30000
	buffer_load_dwordx4 v161, s[12:15], s94 offen lds
	s_waitcnt vmcnt(8) lgkmcnt(0)
	v_mfma_f32_16x16x32_bf16 v[126:129], v[130:133], v[176:179], v[126:129]
	s_barrier
	v_mfma_f32_16x16x32_bf16 v[126:129], v[134:137], v[180:183], v[126:129]
	v_mfma_f32_16x16x32_bf16 v[122:125], v[138:141], v[176:179], v[122:125]
	v_mfma_f32_16x16x32_bf16 v[122:125], v[142:145], v[180:183], v[122:125]
	v_mfma_f32_16x16x32_bf16 v[118:121], v[154:157], v[176:179], v[118:121]
	v_mfma_f32_16x16x32_bf16 v[118:121], v[164:167], v[180:183], v[118:121]
	v_mfma_f32_16x16x32_bf16 v[114:117], v[168:171], v[176:179], v[114:117]
	v_mfma_f32_16x16x32_bf16 v[114:117], v[172:175], v[180:183], v[114:117]
	v_mfma_f32_16x16x32_bf16 v[98:101], v[168:171], v[184:187], v[98:101]
	v_mfma_f32_16x16x32_bf16 v[98:101], v[172:175], v[188:191], v[98:101]
	v_mfma_f32_16x16x32_bf16 v[102:105], v[154:157], v[184:187], v[102:105]
	v_mfma_f32_16x16x32_bf16 v[102:105], v[164:167], v[188:191], v[102:105]
	v_mfma_f32_16x16x32_bf16 v[106:109], v[138:141], v[184:187], v[106:109]
	v_mfma_f32_16x16x32_bf16 v[106:109], v[142:145], v[188:191], v[106:109]
	v_mfma_f32_16x16x32_bf16 v[110:113], v[130:133], v[184:187], v[110:113]
	v_mfma_f32_16x16x32_bf16 v[110:113], v[134:137], v[188:191], v[110:113]
	v_mfma_f32_16x16x32_bf16 v[94:97], v[130:133], v[192:195], v[94:97]
	v_mfma_f32_16x16x32_bf16 v[94:97], v[134:137], v[196:199], v[94:97]
	v_mfma_f32_16x16x32_bf16 v[90:93], v[138:141], v[192:195], v[90:93]
	v_mfma_f32_16x16x32_bf16 v[90:93], v[142:145], v[196:199], v[90:93]
	v_mfma_f32_16x16x32_bf16 v[86:89], v[154:157], v[192:195], v[86:89]
	v_mfma_f32_16x16x32_bf16 v[86:89], v[164:167], v[196:199], v[86:89]
	v_mfma_f32_16x16x32_bf16 v[82:85], v[168:171], v[192:195], v[82:85]
	v_mfma_f32_16x16x32_bf16 v[82:85], v[172:175], v[196:199], v[82:85]
	v_mfma_f32_16x16x32_bf16 v[66:69], v[168:171], v[200:203], v[66:69]
	v_mfma_f32_16x16x32_bf16 v[66:69], v[172:175], v[204:207], v[66:69]
	v_mfma_f32_16x16x32_bf16 v[70:73], v[154:157], v[200:203], v[70:73]
	v_mfma_f32_16x16x32_bf16 v[70:73], v[164:167], v[204:207], v[70:73]
	v_mfma_f32_16x16x32_bf16 v[74:77], v[138:141], v[200:203], v[74:77]
	v_mfma_f32_16x16x32_bf16 v[74:77], v[142:145], v[204:207], v[74:77]
	v_mfma_f32_16x16x32_bf16 v[78:81], v[130:133], v[200:203], v[78:81]
	v_mfma_f32_16x16x32_bf16 v[78:81], v[134:137], v[204:207], v[78:81]
	s_barrier
	s_mov_b32 m0, s74
	s_or_b32 s94, s93, 0x80
	ds_read_b128 v[176:179], v163 offset:49152
	ds_read_b128 v[180:183], v163 offset:50176
	ds_read_b128 v[184:187], v163 offset:51200
	ds_read_b128 v[188:191], v163 offset:52224
	ds_read_b128 v[192:195], v163 offset:53248
	ds_read_b128 v[196:199], v163 offset:54272
	ds_read_b128 v[200:203], v163 offset:55296
	ds_read_b128 v[204:207], v163 offset:56320
	buffer_load_dwordx4 v160, s[4:7], s94 offen lds
	s_add_i32 s94, s93, 0x10080
	s_mov_b32 m0, s75
	s_add_i32 s91, s91, 0x10080
	buffer_load_dwordx4 v160, s[4:7], s94 offen lds
	s_add_i32 s94, s93, 0x20080
	s_mov_b32 m0, s78
	s_add_i32 s93, s93, 0x30080
	buffer_load_dwordx4 v160, s[4:7], s94 offen lds
	s_mov_b32 m0, s79
	s_nop 0
	buffer_load_dwordx4 v160, s[4:7], s93 offen lds
	s_mov_b32 m0, s76
	s_nop 0
	buffer_load_dwordx4 v161, s[12:15], s92 offen lds
	s_mov_b32 m0, s77
	s_nop 0
	buffer_load_dwordx4 v161, s[12:15], s91 offen lds
	s_waitcnt vmcnt(8) lgkmcnt(0)
	v_mfma_f32_16x16x32_bf16 v[62:65], v[130:133], v[176:179], v[62:65]
	s_barrier
	v_mfma_f32_16x16x32_bf16 v[62:65], v[134:137], v[180:183], v[62:65]
	v_mfma_f32_16x16x32_bf16 v[58:61], v[138:141], v[176:179], v[58:61]
	v_mfma_f32_16x16x32_bf16 v[58:61], v[142:145], v[180:183], v[58:61]
	v_mfma_f32_16x16x32_bf16 v[54:57], v[154:157], v[176:179], v[54:57]
	v_mfma_f32_16x16x32_bf16 v[54:57], v[164:167], v[180:183], v[54:57]
	v_mfma_f32_16x16x32_bf16 v[50:53], v[168:171], v[176:179], v[50:53]
	v_mfma_f32_16x16x32_bf16 v[50:53], v[172:175], v[180:183], v[50:53]
	v_mfma_f32_16x16x32_bf16 v[34:37], v[168:171], v[184:187], v[34:37]
	v_mfma_f32_16x16x32_bf16 v[34:37], v[172:175], v[188:191], v[34:37]
	v_mfma_f32_16x16x32_bf16 v[38:41], v[154:157], v[184:187], v[38:41]
	v_mfma_f32_16x16x32_bf16 v[38:41], v[164:167], v[188:191], v[38:41]
	v_mfma_f32_16x16x32_bf16 v[42:45], v[138:141], v[184:187], v[42:45]
	v_mfma_f32_16x16x32_bf16 v[42:45], v[142:145], v[188:191], v[42:45]
	v_mfma_f32_16x16x32_bf16 v[46:49], v[130:133], v[184:187], v[46:49]
	v_mfma_f32_16x16x32_bf16 v[46:49], v[134:137], v[188:191], v[46:49]
	v_mfma_f32_16x16x32_bf16 v[30:33], v[130:133], v[192:195], v[30:33]
	v_mfma_f32_16x16x32_bf16 v[30:33], v[134:137], v[196:199], v[30:33]
	v_mfma_f32_16x16x32_bf16 v[26:29], v[138:141], v[192:195], v[26:29]
	v_mfma_f32_16x16x32_bf16 v[26:29], v[142:145], v[196:199], v[26:29]
	v_mfma_f32_16x16x32_bf16 v[22:25], v[154:157], v[192:195], v[22:25]
	v_mfma_f32_16x16x32_bf16 v[22:25], v[164:167], v[196:199], v[22:25]
	v_mfma_f32_16x16x32_bf16 v[18:21], v[168:171], v[192:195], v[18:21]
	v_mfma_f32_16x16x32_bf16 v[18:21], v[172:175], v[196:199], v[18:21]
	v_mfma_f32_16x16x32_bf16 v[2:5], v[168:171], v[200:203], v[2:5]
	v_mfma_f32_16x16x32_bf16 v[2:5], v[172:175], v[204:207], v[2:5]
	v_mfma_f32_16x16x32_bf16 v[6:9], v[154:157], v[200:203], v[6:9]
	v_mfma_f32_16x16x32_bf16 v[6:9], v[164:167], v[204:207], v[6:9]
	v_mfma_f32_16x16x32_bf16 v[10:13], v[138:141], v[200:203], v[10:13]
	v_mfma_f32_16x16x32_bf16 v[10:13], v[142:145], v[204:207], v[10:13]
	v_mfma_f32_16x16x32_bf16 v[14:17], v[130:133], v[200:203], v[14:17]
	v_mfma_f32_16x16x32_bf16 v[14:17], v[134:137], v[204:207], v[14:17]
	s_barrier
	s_add_i32 s89, s89, 2
	s_cmp_ge_i32 s89, s63
	s_mov_b32 s6, s90
	s_cbranch_scc0 .LBB0_1020
	s_and_b64 vcc, exec, s[54:55]
	s_cbranch_vccz .LBB0_1023

.LBB0_1035:
	ds_read_b128 v[140:143], v134
	ds_read_b128 v[148:151], v134 offset:1024
	ds_read_b128 v[152:155], v134 offset:2048
	ds_read_b128 v[156:159], v134 offset:3072
	ds_read_b128 v[160:163], v135
	ds_read_b128 v[164:167], v135 offset:1024
	ds_read_b128 v[168:171], v135 offset:2048
	ds_read_b128 v[172:175], v135 offset:3072
	s_add_i32 s73, s70, 0xfffb8080
	s_cmp_eq_u32 s53, s72
	s_cselect_b32 s73, s68, s73
	s_cselect_b32 s75, s69, s71
	s_add_i32 s74, s73, 0x80
	s_add_i32 s76, s70, 0xfffe8000
	s_mov_b32 m0, s54
	ds_read_b128 v[176:179], v136
	ds_read_b128 v[180:183], v136 offset:1024
	ds_read_b128 v[184:187], v136 offset:2048
	ds_read_b128 v[188:191], v136 offset:3072
	ds_read_b128 v[192:195], v136 offset:4096
	ds_read_b128 v[196:199], v136 offset:5120
	ds_read_b128 v[200:203], v136 offset:6144
	ds_read_b128 v[204:207], v136 offset:7168
	buffer_load_dwordx4 v132, s[12:15], s76 offen lds
	s_mov_b32 m0, s55
	s_nop 0
	buffer_load_dwordx4 v132, s[12:15], s70 offen lds
	s_waitcnt vmcnt(8) lgkmcnt(0)
	v_mfma_f32_16x16x32_bf16 v[126:129], v[140:143], v[176:179], v[126:129]
	s_barrier
	v_mfma_f32_16x16x32_bf16 v[126:129], v[148:151], v[180:183], v[126:129]
	v_mfma_f32_16x16x32_bf16 v[122:125], v[152:155], v[176:179], v[122:125]
	v_mfma_f32_16x16x32_bf16 v[122:125], v[156:159], v[180:183], v[122:125]
	v_mfma_f32_16x16x32_bf16 v[118:121], v[160:163], v[176:179], v[118:121]
	v_mfma_f32_16x16x32_bf16 v[118:121], v[164:167], v[180:183], v[118:121]
	v_mfma_f32_16x16x32_bf16 v[114:117], v[168:171], v[176:179], v[114:117]
	v_mfma_f32_16x16x32_bf16 v[114:117], v[172:175], v[180:183], v[114:117]
	v_mfma_f32_16x16x32_bf16 v[98:101], v[168:171], v[184:187], v[98:101]
	v_mfma_f32_16x16x32_bf16 v[98:101], v[172:175], v[188:191], v[98:101]
	v_mfma_f32_16x16x32_bf16 v[102:105], v[160:163], v[184:187], v[102:105]
	v_mfma_f32_16x16x32_bf16 v[102:105], v[164:167], v[188:191], v[102:105]
	v_mfma_f32_16x16x32_bf16 v[106:109], v[152:155], v[184:187], v[106:109]
	v_mfma_f32_16x16x32_bf16 v[106:109], v[156:159], v[188:191], v[106:109]
	v_mfma_f32_16x16x32_bf16 v[110:113], v[140:143], v[184:187], v[110:113]
	v_mfma_f32_16x16x32_bf16 v[110:113], v[148:151], v[188:191], v[110:113]
	v_mfma_f32_16x16x32_bf16 v[94:97], v[140:143], v[192:195], v[94:97]
	v_mfma_f32_16x16x32_bf16 v[94:97], v[148:151], v[196:199], v[94:97]
	v_mfma_f32_16x16x32_bf16 v[90:93], v[152:155], v[192:195], v[90:93]
	v_mfma_f32_16x16x32_bf16 v[90:93], v[156:159], v[196:199], v[90:93]
	v_mfma_f32_16x16x32_bf16 v[86:89], v[160:163], v[192:195], v[86:89]
	v_mfma_f32_16x16x32_bf16 v[86:89], v[164:167], v[196:199], v[86:89]
	v_mfma_f32_16x16x32_bf16 v[82:85], v[168:171], v[192:195], v[82:85]
	v_mfma_f32_16x16x32_bf16 v[82:85], v[172:175], v[196:199], v[82:85]
	v_mfma_f32_16x16x32_bf16 v[66:69], v[168:171], v[200:203], v[66:69]
	v_mfma_f32_16x16x32_bf16 v[66:69], v[172:175], v[204:207], v[66:69]
	v_mfma_f32_16x16x32_bf16 v[70:73], v[160:163], v[200:203], v[70:73]
	v_mfma_f32_16x16x32_bf16 v[70:73], v[164:167], v[204:207], v[70:73]
	v_mfma_f32_16x16x32_bf16 v[74:77], v[152:155], v[200:203], v[74:77]
	v_mfma_f32_16x16x32_bf16 v[74:77], v[156:159], v[204:207], v[74:77]
	v_mfma_f32_16x16x32_bf16 v[78:81], v[140:143], v[200:203], v[78:81]
	v_mfma_f32_16x16x32_bf16 v[78:81], v[148:151], v[204:207], v[78:81]
	s_barrier
	s_mov_b32 m0, s30
	ds_read_b128 v[176:179], v136 offset:16384
	ds_read_b128 v[180:183], v136 offset:17408
	ds_read_b128 v[184:187], v136 offset:18432
	ds_read_b128 v[188:191], v136 offset:19456
	ds_read_b128 v[192:195], v136 offset:20480
	ds_read_b128 v[196:199], v136 offset:21504
	ds_read_b128 v[200:203], v136 offset:22528
	ds_read_b128 v[204:207], v136 offset:23552
	buffer_load_dwordx4 v133, s[16:19], s75 offen lds
	s_mov_b32 m0, s31
	s_add_i32 s76, s75, 0x200000
	buffer_load_dwordx4 v133, s[16:19], s76 offen lds
	s_mov_b32 m0, s35
	s_add_i32 s76, s75, 0x400000
	buffer_load_dwordx4 v133, s[16:19], s76 offen lds
	s_mov_b32 m0, s42
	s_add_i32 s76, s75, 0x600000
	buffer_load_dwordx4 v133, s[16:19], s76 offen lds
	s_mov_b32 m0, s27
	s_add_i32 s76, s73, 0x18000
	buffer_load_dwordx4 v132, s[12:15], s73 offen lds
	s_mov_b32 m0, s43
	s_nop 0
	buffer_load_dwordx4 v132, s[12:15], s76 offen lds
	s_waitcnt vmcnt(8) lgkmcnt(0)
	v_mfma_f32_16x16x32_bf16 v[62:65], v[140:143], v[176:179], v[62:65]
	s_barrier
	v_mfma_f32_16x16x32_bf16 v[62:65], v[148:151], v[180:183], v[62:65]
	v_mfma_f32_16x16x32_bf16 v[58:61], v[152:155], v[176:179], v[58:61]
	v_mfma_f32_16x16x32_bf16 v[58:61], v[156:159], v[180:183], v[58:61]
	v_mfma_f32_16x16x32_bf16 v[54:57], v[160:163], v[176:179], v[54:57]
	v_mfma_f32_16x16x32_bf16 v[54:57], v[164:167], v[180:183], v[54:57]
	v_mfma_f32_16x16x32_bf16 v[50:53], v[168:171], v[176:179], v[50:53]
	v_mfma_f32_16x16x32_bf16 v[50:53], v[172:175], v[180:183], v[50:53]
	v_mfma_f32_16x16x32_bf16 v[34:37], v[168:171], v[184:187], v[34:37]
	v_mfma_f32_16x16x32_bf16 v[34:37], v[172:175], v[188:191], v[34:37]
	v_mfma_f32_16x16x32_bf16 v[38:41], v[160:163], v[184:187], v[38:41]
	v_mfma_f32_16x16x32_bf16 v[38:41], v[164:167], v[188:191], v[38:41]
	v_mfma_f32_16x16x32_bf16 v[42:45], v[152:155], v[184:187], v[42:45]
	v_mfma_f32_16x16x32_bf16 v[42:45], v[156:159], v[188:191], v[42:45]
	v_mfma_f32_16x16x32_bf16 v[46:49], v[140:143], v[184:187], v[46:49]
	v_mfma_f32_16x16x32_bf16 v[46:49], v[148:151], v[188:191], v[46:49]
	v_mfma_f32_16x16x32_bf16 v[30:33], v[140:143], v[192:195], v[30:33]
	v_mfma_f32_16x16x32_bf16 v[30:33], v[148:151], v[196:199], v[30:33]
	v_mfma_f32_16x16x32_bf16 v[26:29], v[152:155], v[192:195], v[26:29]
	v_mfma_f32_16x16x32_bf16 v[26:29], v[156:159], v[196:199], v[26:29]
	v_mfma_f32_16x16x32_bf16 v[22:25], v[160:163], v[192:195], v[22:25]
	v_mfma_f32_16x16x32_bf16 v[22:25], v[164:167], v[196:199], v[22:25]
	v_mfma_f32_16x16x32_bf16 v[18:21], v[168:171], v[192:195], v[18:21]
	v_mfma_f32_16x16x32_bf16 v[18:21], v[172:175], v[196:199], v[18:21]
	v_mfma_f32_16x16x32_bf16 v[2:5], v[168:171], v[200:203], v[2:5]
	v_mfma_f32_16x16x32_bf16 v[2:5], v[172:175], v[204:207], v[2:5]
	v_mfma_f32_16x16x32_bf16 v[6:9], v[160:163], v[200:203], v[6:9]
	v_mfma_f32_16x16x32_bf16 v[6:9], v[164:167], v[204:207], v[6:9]
	v_mfma_f32_16x16x32_bf16 v[10:13], v[152:155], v[200:203], v[10:13]
	v_mfma_f32_16x16x32_bf16 v[10:13], v[156:159], v[204:207], v[10:13]
	v_mfma_f32_16x16x32_bf16 v[14:17], v[140:143], v[200:203], v[14:17]
	v_mfma_f32_16x16x32_bf16 v[14:17], v[148:151], v[204:207], v[14:17]
	s_barrier
	ds_read_b128 v[140:143], v137
	ds_read_b128 v[148:151], v137 offset:1024
	ds_read_b128 v[152:155], v137 offset:2048
	ds_read_b128 v[156:159], v137 offset:3072
	ds_read_b128 v[160:163], v138
	ds_read_b128 v[164:167], v138 offset:1024
	ds_read_b128 v[168:171], v138 offset:2048
	ds_read_b128 v[172:175], v138 offset:3072
	s_mov_b32 m0, s44
	s_add_i32 s76, s73, 0x30000
	ds_read_b128 v[176:179], v136 offset:32768
	ds_read_b128 v[180:183], v136 offset:33792
	ds_read_b128 v[184:187], v136 offset:34816
	ds_read_b128 v[188:191], v136 offset:35840
	ds_read_b128 v[192:195], v136 offset:36864
	ds_read_b128 v[196:199], v136 offset:37888
	ds_read_b128 v[200:203], v136 offset:38912
	ds_read_b128 v[204:207], v136 offset:39936
	buffer_load_dwordx4 v132, s[12:15], s76 offen lds
	s_mov_b32 m0, s45
	s_add_i32 s76, s73, 0x48000
	buffer_load_dwordx4 v132, s[12:15], s76 offen lds
	s_waitcnt vmcnt(8) lgkmcnt(0)
	v_mfma_f32_16x16x32_bf16 v[126:129], v[140:143], v[176:179], v[126:129]
	s_barrier
	v_mfma_f32_16x16x32_bf16 v[126:129], v[148:151], v[180:183], v[126:129]
	v_mfma_f32_16x16x32_bf16 v[122:125], v[152:155], v[176:179], v[122:125]
	v_mfma_f32_16x16x32_bf16 v[122:125], v[156:159], v[180:183], v[122:125]
	v_mfma_f32_16x16x32_bf16 v[118:121], v[160:163], v[176:179], v[118:121]
	v_mfma_f32_16x16x32_bf16 v[118:121], v[164:167], v[180:183], v[118:121]
	v_mfma_f32_16x16x32_bf16 v[114:117], v[168:171], v[176:179], v[114:117]
	v_mfma_f32_16x16x32_bf16 v[114:117], v[172:175], v[180:183], v[114:117]
	v_mfma_f32_16x16x32_bf16 v[98:101], v[168:171], v[184:187], v[98:101]
	v_mfma_f32_16x16x32_bf16 v[98:101], v[172:175], v[188:191], v[98:101]
	v_mfma_f32_16x16x32_bf16 v[102:105], v[160:163], v[184:187], v[102:105]
	v_mfma_f32_16x16x32_bf16 v[102:105], v[164:167], v[188:191], v[102:105]
	v_mfma_f32_16x16x32_bf16 v[106:109], v[152:155], v[184:187], v[106:109]
	v_mfma_f32_16x16x32_bf16 v[106:109], v[156:159], v[188:191], v[106:109]
	v_mfma_f32_16x16x32_bf16 v[110:113], v[140:143], v[184:187], v[110:113]
	v_mfma_f32_16x16x32_bf16 v[110:113], v[148:151], v[188:191], v[110:113]
	v_mfma_f32_16x16x32_bf16 v[94:97], v[140:143], v[192:195], v[94:97]
	v_mfma_f32_16x16x32_bf16 v[94:97], v[148:151], v[196:199], v[94:97]
	v_mfma_f32_16x16x32_bf16 v[90:93], v[152:155], v[192:195], v[90:93]
	v_mfma_f32_16x16x32_bf16 v[90:93], v[156:159], v[196:199], v[90:93]
	v_mfma_f32_16x16x32_bf16 v[86:89], v[160:163], v[192:195], v[86:89]
	v_mfma_f32_16x16x32_bf16 v[86:89], v[164:167], v[196:199], v[86:89]
	v_mfma_f32_16x16x32_bf16 v[82:85], v[168:171], v[192:195], v[82:85]
	v_mfma_f32_16x16x32_bf16 v[82:85], v[172:175], v[196:199], v[82:85]
	v_mfma_f32_16x16x32_bf16 v[66:69], v[168:171], v[200:203], v[66:69]
	v_mfma_f32_16x16x32_bf16 v[66:69], v[172:175], v[204:207], v[66:69]
	v_mfma_f32_16x16x32_bf16 v[70:73], v[160:163], v[200:203], v[70:73]
	v_mfma_f32_16x16x32_bf16 v[70:73], v[164:167], v[204:207], v[70:73]
	v_mfma_f32_16x16x32_bf16 v[74:77], v[152:155], v[200:203], v[74:77]
	v_mfma_f32_16x16x32_bf16 v[74:77], v[156:159], v[204:207], v[74:77]
	v_mfma_f32_16x16x32_bf16 v[78:81], v[140:143], v[200:203], v[78:81]
	v_mfma_f32_16x16x32_bf16 v[78:81], v[148:151], v[204:207], v[78:81]
	s_barrier
	s_mov_b32 m0, s46
	s_add_i32 s76, s75, 0x80
	ds_read_b128 v[176:179], v136 offset:49152
	ds_read_b128 v[180:183], v136 offset:50176
	ds_read_b128 v[184:187], v136 offset:51200
	ds_read_b128 v[188:191], v136 offset:52224
	ds_read_b128 v[192:195], v136 offset:53248
	ds_read_b128 v[196:199], v136 offset:54272
	ds_read_b128 v[200:203], v136 offset:55296
	ds_read_b128 v[204:207], v136 offset:56320
	buffer_load_dwordx4 v133, s[16:19], s76 offen lds
	s_add_i32 s76, s75, 0x200080
	s_mov_b32 m0, s47
	s_add_i32 s73, s73, 0x18080
	buffer_load_dwordx4 v133, s[16:19], s76 offen lds
	s_add_i32 s76, s75, 0x400080
	s_mov_b32 m0, s50
	s_add_i32 s75, s75, 0x600080
	buffer_load_dwordx4 v133, s[16:19], s76 offen lds
	s_mov_b32 m0, s51
	s_nop 0
	buffer_load_dwordx4 v133, s[16:19], s75 offen lds
	s_mov_b32 m0, s48
	s_nop 0
	buffer_load_dwordx4 v132, s[12:15], s74 offen lds
	s_mov_b32 m0, s49
	s_nop 0
	buffer_load_dwordx4 v132, s[12:15], s73 offen lds
	s_waitcnt vmcnt(8) lgkmcnt(0)
	v_mfma_f32_16x16x32_bf16 v[62:65], v[140:143], v[176:179], v[62:65]
	s_barrier
	v_mfma_f32_16x16x32_bf16 v[62:65], v[148:151], v[180:183], v[62:65]
	v_mfma_f32_16x16x32_bf16 v[58:61], v[152:155], v[176:179], v[58:61]
	v_mfma_f32_16x16x32_bf16 v[58:61], v[156:159], v[180:183], v[58:61]
	v_mfma_f32_16x16x32_bf16 v[54:57], v[160:163], v[176:179], v[54:57]
	v_mfma_f32_16x16x32_bf16 v[54:57], v[164:167], v[180:183], v[54:57]
	v_mfma_f32_16x16x32_bf16 v[50:53], v[168:171], v[176:179], v[50:53]
	v_mfma_f32_16x16x32_bf16 v[50:53], v[172:175], v[180:183], v[50:53]
	v_mfma_f32_16x16x32_bf16 v[34:37], v[168:171], v[184:187], v[34:37]
	v_mfma_f32_16x16x32_bf16 v[34:37], v[172:175], v[188:191], v[34:37]
	v_mfma_f32_16x16x32_bf16 v[38:41], v[160:163], v[184:187], v[38:41]
	v_mfma_f32_16x16x32_bf16 v[38:41], v[164:167], v[188:191], v[38:41]
	v_mfma_f32_16x16x32_bf16 v[42:45], v[152:155], v[184:187], v[42:45]
	v_mfma_f32_16x16x32_bf16 v[42:45], v[156:159], v[188:191], v[42:45]
	v_mfma_f32_16x16x32_bf16 v[46:49], v[140:143], v[184:187], v[46:49]
	v_mfma_f32_16x16x32_bf16 v[46:49], v[148:151], v[188:191], v[46:49]
	v_mfma_f32_16x16x32_bf16 v[30:33], v[140:143], v[192:195], v[30:33]
	v_mfma_f32_16x16x32_bf16 v[30:33], v[148:151], v[196:199], v[30:33]
	v_mfma_f32_16x16x32_bf16 v[26:29], v[152:155], v[192:195], v[26:29]
	v_mfma_f32_16x16x32_bf16 v[26:29], v[156:159], v[196:199], v[26:29]
	v_mfma_f32_16x16x32_bf16 v[22:25], v[160:163], v[192:195], v[22:25]
	v_mfma_f32_16x16x32_bf16 v[22:25], v[164:167], v[196:199], v[22:25]
	v_mfma_f32_16x16x32_bf16 v[18:21], v[168:171], v[192:195], v[18:21]
	v_mfma_f32_16x16x32_bf16 v[18:21], v[172:175], v[196:199], v[18:21]
	v_mfma_f32_16x16x32_bf16 v[2:5], v[168:171], v[200:203], v[2:5]
	v_mfma_f32_16x16x32_bf16 v[2:5], v[172:175], v[204:207], v[2:5]
	v_mfma_f32_16x16x32_bf16 v[6:9], v[160:163], v[200:203], v[6:9]
	v_mfma_f32_16x16x32_bf16 v[6:9], v[164:167], v[204:207], v[6:9]
	v_mfma_f32_16x16x32_bf16 v[10:13], v[152:155], v[200:203], v[10:13]
	v_mfma_f32_16x16x32_bf16 v[10:13], v[156:159], v[204:207], v[10:13]
	v_mfma_f32_16x16x32_bf16 v[14:17], v[140:143], v[200:203], v[14:17]
	v_mfma_f32_16x16x32_bf16 v[14:17], v[148:151], v[204:207], v[14:17]
	s_barrier
	s_add_i32 s72, s72, 2
	s_addk_i32 s70, 0x100
	s_addk_i32 s71, 0x100
	s_cmp_ge_i32 s72, s21
	s_cbranch_scc0 .LBB0_1035

.LBB0_1050:
	ds_read_b128 v[132:135], v142
	ds_read_b128 v[136:139], v142 offset:1024
	ds_read_b128 v[148:151], v142 offset:2048
	ds_read_b128 v[152:155], v142 offset:3072
	ds_read_b128 v[156:159], v143
	ds_read_b128 v[160:163], v143 offset:1024
	ds_read_b128 v[164:167], v143 offset:2048
	ds_read_b128 v[168:171], v143 offset:3072
	s_add_i32 s18, s61, 0xfff40080
	s_cmp_eq_u32 s54, s62
	s_cselect_b32 s64, s35, s18
	s_add_i32 s63, s64, 0x80
	s_add_i32 s18, s61, 0xfffc0000
	s_mov_b32 m0, s55
	ds_read_b128 v[172:175], v144
	ds_read_b128 v[176:179], v144 offset:1024
	ds_read_b128 v[180:183], v144 offset:2048
	ds_read_b128 v[184:187], v144 offset:3072
	ds_read_b128 v[188:191], v144 offset:4096
	ds_read_b128 v[192:195], v144 offset:5120
	ds_read_b128 v[196:199], v144 offset:6144
	ds_read_b128 v[200:203], v144 offset:7168
	buffer_load_dwordx4 v140, s[12:15], s18 offen lds
	s_mov_b32 m0, s56
	s_nop 0
	buffer_load_dwordx4 v140, s[12:15], s61 offen lds
	s_waitcnt vmcnt(8) lgkmcnt(0)
	v_mfma_f32_16x16x32_bf16 v[126:129], v[132:135], v[172:175], v[126:129]
	s_barrier
	v_mfma_f32_16x16x32_bf16 v[126:129], v[136:139], v[176:179], v[126:129]
	v_mfma_f32_16x16x32_bf16 v[122:125], v[148:151], v[172:175], v[122:125]
	v_mfma_f32_16x16x32_bf16 v[122:125], v[152:155], v[176:179], v[122:125]
	v_mfma_f32_16x16x32_bf16 v[118:121], v[156:159], v[172:175], v[118:121]
	v_mfma_f32_16x16x32_bf16 v[118:121], v[160:163], v[176:179], v[118:121]
	v_mfma_f32_16x16x32_bf16 v[114:117], v[164:167], v[172:175], v[114:117]
	v_mfma_f32_16x16x32_bf16 v[114:117], v[168:171], v[176:179], v[114:117]
	v_mfma_f32_16x16x32_bf16 v[98:101], v[164:167], v[180:183], v[98:101]
	v_mfma_f32_16x16x32_bf16 v[98:101], v[168:171], v[184:187], v[98:101]
	v_mfma_f32_16x16x32_bf16 v[102:105], v[156:159], v[180:183], v[102:105]
	v_mfma_f32_16x16x32_bf16 v[102:105], v[160:163], v[184:187], v[102:105]
	v_mfma_f32_16x16x32_bf16 v[106:109], v[148:151], v[180:183], v[106:109]
	v_mfma_f32_16x16x32_bf16 v[106:109], v[152:155], v[184:187], v[106:109]
	v_mfma_f32_16x16x32_bf16 v[110:113], v[132:135], v[180:183], v[110:113]
	v_mfma_f32_16x16x32_bf16 v[110:113], v[136:139], v[184:187], v[110:113]
	v_mfma_f32_16x16x32_bf16 v[94:97], v[132:135], v[188:191], v[94:97]
	v_mfma_f32_16x16x32_bf16 v[94:97], v[136:139], v[192:195], v[94:97]
	v_mfma_f32_16x16x32_bf16 v[90:93], v[148:151], v[188:191], v[90:93]
	v_mfma_f32_16x16x32_bf16 v[90:93], v[152:155], v[192:195], v[90:93]
	v_mfma_f32_16x16x32_bf16 v[86:89], v[156:159], v[188:191], v[86:89]
	v_mfma_f32_16x16x32_bf16 v[86:89], v[160:163], v[192:195], v[86:89]
	v_mfma_f32_16x16x32_bf16 v[82:85], v[164:167], v[188:191], v[82:85]
	v_mfma_f32_16x16x32_bf16 v[82:85], v[168:171], v[192:195], v[82:85]
	v_mfma_f32_16x16x32_bf16 v[66:69], v[164:167], v[196:199], v[66:69]
	v_mfma_f32_16x16x32_bf16 v[66:69], v[168:171], v[200:203], v[66:69]
	v_mfma_f32_16x16x32_bf16 v[70:73], v[156:159], v[196:199], v[70:73]
	v_mfma_f32_16x16x32_bf16 v[70:73], v[160:163], v[200:203], v[70:73]
	v_mfma_f32_16x16x32_bf16 v[74:77], v[148:151], v[196:199], v[74:77]
	v_mfma_f32_16x16x32_bf16 v[74:77], v[152:155], v[200:203], v[74:77]
	v_mfma_f32_16x16x32_bf16 v[78:81], v[132:135], v[196:199], v[78:81]
	v_mfma_f32_16x16x32_bf16 v[78:81], v[136:139], v[200:203], v[78:81]
	s_barrier
	s_mov_b32 m0, s25
	s_mov_b32 s18, s14
	s_mov_b32 s19, s15
	ds_read_b128 v[172:175], v144 offset:16384
	ds_read_b128 v[176:179], v144 offset:17408
	ds_read_b128 v[180:183], v144 offset:18432
	ds_read_b128 v[184:187], v144 offset:19456
	ds_read_b128 v[188:191], v144 offset:20480
	ds_read_b128 v[192:195], v144 offset:21504
	ds_read_b128 v[196:199], v144 offset:22528
	ds_read_b128 v[200:203], v144 offset:23552
	buffer_load_dwordx4 v141, s[16:19], s64 offen lds
	s_add_i32 s65, s64, 0x40000
	s_mov_b32 m0, s27
	s_add_i32 s66, s64, 0x80000
	buffer_load_dwordx4 v141, s[16:19], s65 offen lds
	s_mov_b32 m0, s30
	s_add_i32 s67, s64, 0xc0000
	buffer_load_dwordx4 v141, s[16:19], s66 offen lds
	s_mov_b32 m0, s31
	s_nop 0
	buffer_load_dwordx4 v141, s[16:19], s67 offen lds
	s_mov_b32 m0, s21
	s_nop 0
	buffer_load_dwordx4 v140, s[12:15], s64 offen lds
	s_mov_b32 m0, s38
	s_nop 0
	buffer_load_dwordx4 v140, s[12:15], s65 offen lds
	s_waitcnt vmcnt(8) lgkmcnt(0)
	v_mfma_f32_16x16x32_bf16 v[62:65], v[132:135], v[172:175], v[62:65]
	s_barrier
	v_mfma_f32_16x16x32_bf16 v[62:65], v[136:139], v[176:179], v[62:65]
	v_mfma_f32_16x16x32_bf16 v[58:61], v[148:151], v[172:175], v[58:61]
	v_mfma_f32_16x16x32_bf16 v[58:61], v[152:155], v[176:179], v[58:61]
	v_mfma_f32_16x16x32_bf16 v[54:57], v[156:159], v[172:175], v[54:57]
	v_mfma_f32_16x16x32_bf16 v[54:57], v[160:163], v[176:179], v[54:57]
	v_mfma_f32_16x16x32_bf16 v[50:53], v[164:167], v[172:175], v[50:53]
	v_mfma_f32_16x16x32_bf16 v[50:53], v[168:171], v[176:179], v[50:53]
	v_mfma_f32_16x16x32_bf16 v[34:37], v[164:167], v[180:183], v[34:37]
	v_mfma_f32_16x16x32_bf16 v[34:37], v[168:171], v[184:187], v[34:37]
	v_mfma_f32_16x16x32_bf16 v[38:41], v[156:159], v[180:183], v[38:41]
	v_mfma_f32_16x16x32_bf16 v[38:41], v[160:163], v[184:187], v[38:41]
	v_mfma_f32_16x16x32_bf16 v[42:45], v[148:151], v[180:183], v[42:45]
	v_mfma_f32_16x16x32_bf16 v[42:45], v[152:155], v[184:187], v[42:45]
	v_mfma_f32_16x16x32_bf16 v[46:49], v[132:135], v[180:183], v[46:49]
	v_mfma_f32_16x16x32_bf16 v[46:49], v[136:139], v[184:187], v[46:49]
	v_mfma_f32_16x16x32_bf16 v[30:33], v[132:135], v[188:191], v[30:33]
	v_mfma_f32_16x16x32_bf16 v[30:33], v[136:139], v[192:195], v[30:33]
	v_mfma_f32_16x16x32_bf16 v[26:29], v[148:151], v[188:191], v[26:29]
	v_mfma_f32_16x16x32_bf16 v[26:29], v[152:155], v[192:195], v[26:29]
	v_mfma_f32_16x16x32_bf16 v[22:25], v[156:159], v[188:191], v[22:25]
	v_mfma_f32_16x16x32_bf16 v[22:25], v[160:163], v[192:195], v[22:25]
	v_mfma_f32_16x16x32_bf16 v[18:21], v[164:167], v[188:191], v[18:21]
	v_mfma_f32_16x16x32_bf16 v[18:21], v[168:171], v[192:195], v[18:21]
	v_mfma_f32_16x16x32_bf16 v[2:5], v[164:167], v[196:199], v[2:5]
	v_mfma_f32_16x16x32_bf16 v[2:5], v[168:171], v[200:203], v[2:5]
	v_mfma_f32_16x16x32_bf16 v[6:9], v[156:159], v[196:199], v[6:9]
	v_mfma_f32_16x16x32_bf16 v[6:9], v[160:163], v[200:203], v[6:9]
	v_mfma_f32_16x16x32_bf16 v[10:13], v[148:151], v[196:199], v[10:13]
	v_mfma_f32_16x16x32_bf16 v[10:13], v[152:155], v[200:203], v[10:13]
	v_mfma_f32_16x16x32_bf16 v[14:17], v[132:135], v[196:199], v[14:17]
	v_mfma_f32_16x16x32_bf16 v[14:17], v[136:139], v[200:203], v[14:17]
	s_barrier
	ds_read_b128 v[132:135], v145
	ds_read_b128 v[136:139], v145 offset:1024
	ds_read_b128 v[148:151], v145 offset:2048
	ds_read_b128 v[152:155], v145 offset:3072
	ds_read_b128 v[156:159], v147
	ds_read_b128 v[160:163], v147 offset:1024
	ds_read_b128 v[164:167], v147 offset:2048
	ds_read_b128 v[168:171], v147 offset:3072
	s_mov_b32 m0, s39
	ds_read_b128 v[172:175], v144 offset:32768
	ds_read_b128 v[176:179], v144 offset:33792
	ds_read_b128 v[180:183], v144 offset:34816
	ds_read_b128 v[184:187], v144 offset:35840
	ds_read_b128 v[188:191], v144 offset:36864
	ds_read_b128 v[192:195], v144 offset:37888
	ds_read_b128 v[196:199], v144 offset:38912
	ds_read_b128 v[200:203], v144 offset:39936
	buffer_load_dwordx4 v140, s[12:15], s66 offen lds
	s_mov_b32 m0, s40
	s_nop 0
	buffer_load_dwordx4 v140, s[12:15], s67 offen lds
	s_waitcnt vmcnt(8) lgkmcnt(0)
	v_mfma_f32_16x16x32_bf16 v[126:129], v[132:135], v[172:175], v[126:129]
	s_barrier
	v_mfma_f32_16x16x32_bf16 v[126:129], v[136:139], v[176:179], v[126:129]
	v_mfma_f32_16x16x32_bf16 v[122:125], v[148:151], v[172:175], v[122:125]
	v_mfma_f32_16x16x32_bf16 v[122:125], v[152:155], v[176:179], v[122:125]
	v_mfma_f32_16x16x32_bf16 v[118:121], v[156:159], v[172:175], v[118:121]
	v_mfma_f32_16x16x32_bf16 v[118:121], v[160:163], v[176:179], v[118:121]
	v_mfma_f32_16x16x32_bf16 v[114:117], v[164:167], v[172:175], v[114:117]
	v_mfma_f32_16x16x32_bf16 v[114:117], v[168:171], v[176:179], v[114:117]
	v_mfma_f32_16x16x32_bf16 v[98:101], v[164:167], v[180:183], v[98:101]
	v_mfma_f32_16x16x32_bf16 v[98:101], v[168:171], v[184:187], v[98:101]
	v_mfma_f32_16x16x32_bf16 v[102:105], v[156:159], v[180:183], v[102:105]
	v_mfma_f32_16x16x32_bf16 v[102:105], v[160:163], v[184:187], v[102:105]
	v_mfma_f32_16x16x32_bf16 v[106:109], v[148:151], v[180:183], v[106:109]
	v_mfma_f32_16x16x32_bf16 v[106:109], v[152:155], v[184:187], v[106:109]
	v_mfma_f32_16x16x32_bf16 v[110:113], v[132:135], v[180:183], v[110:113]
	v_mfma_f32_16x16x32_bf16 v[110:113], v[136:139], v[184:187], v[110:113]
	v_mfma_f32_16x16x32_bf16 v[94:97], v[132:135], v[188:191], v[94:97]
	v_mfma_f32_16x16x32_bf16 v[94:97], v[136:139], v[192:195], v[94:97]
	v_mfma_f32_16x16x32_bf16 v[90:93], v[148:151], v[188:191], v[90:93]
	v_mfma_f32_16x16x32_bf16 v[90:93], v[152:155], v[192:195], v[90:93]
	v_mfma_f32_16x16x32_bf16 v[86:89], v[156:159], v[188:191], v[86:89]
	v_mfma_f32_16x16x32_bf16 v[86:89], v[160:163], v[192:195], v[86:89]
	v_mfma_f32_16x16x32_bf16 v[82:85], v[164:167], v[188:191], v[82:85]
	v_mfma_f32_16x16x32_bf16 v[82:85], v[168:171], v[192:195], v[82:85]
	v_mfma_f32_16x16x32_bf16 v[66:69], v[164:167], v[196:199], v[66:69]
	v_mfma_f32_16x16x32_bf16 v[66:69], v[168:171], v[200:203], v[66:69]
	v_mfma_f32_16x16x32_bf16 v[70:73], v[156:159], v[196:199], v[70:73]
	v_mfma_f32_16x16x32_bf16 v[70:73], v[160:163], v[200:203], v[70:73]
	v_mfma_f32_16x16x32_bf16 v[74:77], v[148:151], v[196:199], v[74:77]
	v_mfma_f32_16x16x32_bf16 v[74:77], v[152:155], v[200:203], v[74:77]
	v_mfma_f32_16x16x32_bf16 v[78:81], v[132:135], v[196:199], v[78:81]
	v_mfma_f32_16x16x32_bf16 v[78:81], v[136:139], v[200:203], v[78:81]
	s_barrier
	s_mov_b32 m0, s48
	ds_read_b128 v[172:175], v144 offset:49152
	ds_read_b128 v[176:179], v144 offset:50176
	ds_read_b128 v[180:183], v144 offset:51200
	ds_read_b128 v[184:187], v144 offset:52224
	ds_read_b128 v[188:191], v144 offset:53248
	ds_read_b128 v[192:195], v144 offset:54272
	ds_read_b128 v[196:199], v144 offset:55296
	ds_read_b128 v[200:203], v144 offset:56320
	buffer_load_dwordx4 v141, s[16:19], s63 offen lds
	s_add_i32 s65, s64, 0x40080
	s_mov_b32 m0, s49
	s_add_i32 s66, s64, 0x80080
	buffer_load_dwordx4 v141, s[16:19], s65 offen lds
	s_mov_b32 m0, s52
	s_add_i32 s64, s64, 0xc0080
	buffer_load_dwordx4 v141, s[16:19], s66 offen lds
	s_mov_b32 m0, s53
	s_nop 0
	buffer_load_dwordx4 v141, s[16:19], s64 offen lds
	s_mov_b32 m0, s50
	s_nop 0
	buffer_load_dwordx4 v140, s[12:15], s63 offen lds
	s_mov_b32 m0, s51
	s_nop 0
	buffer_load_dwordx4 v140, s[12:15], s65 offen lds
	s_waitcnt vmcnt(8) lgkmcnt(0)
	v_mfma_f32_16x16x32_bf16 v[62:65], v[132:135], v[172:175], v[62:65]
	s_barrier
	v_mfma_f32_16x16x32_bf16 v[62:65], v[136:139], v[176:179], v[62:65]
	v_mfma_f32_16x16x32_bf16 v[58:61], v[148:151], v[172:175], v[58:61]
	v_mfma_f32_16x16x32_bf16 v[58:61], v[152:155], v[176:179], v[58:61]
	v_mfma_f32_16x16x32_bf16 v[54:57], v[156:159], v[172:175], v[54:57]
	v_mfma_f32_16x16x32_bf16 v[54:57], v[160:163], v[176:179], v[54:57]
	v_mfma_f32_16x16x32_bf16 v[50:53], v[164:167], v[172:175], v[50:53]
	v_mfma_f32_16x16x32_bf16 v[50:53], v[168:171], v[176:179], v[50:53]
	v_mfma_f32_16x16x32_bf16 v[34:37], v[164:167], v[180:183], v[34:37]
	v_mfma_f32_16x16x32_bf16 v[34:37], v[168:171], v[184:187], v[34:37]
	v_mfma_f32_16x16x32_bf16 v[38:41], v[156:159], v[180:183], v[38:41]
	v_mfma_f32_16x16x32_bf16 v[38:41], v[160:163], v[184:187], v[38:41]
	v_mfma_f32_16x16x32_bf16 v[42:45], v[148:151], v[180:183], v[42:45]
	v_mfma_f32_16x16x32_bf16 v[42:45], v[152:155], v[184:187], v[42:45]
	v_mfma_f32_16x16x32_bf16 v[46:49], v[132:135], v[180:183], v[46:49]
	v_mfma_f32_16x16x32_bf16 v[46:49], v[136:139], v[184:187], v[46:49]
	v_mfma_f32_16x16x32_bf16 v[30:33], v[132:135], v[188:191], v[30:33]
	v_mfma_f32_16x16x32_bf16 v[30:33], v[136:139], v[192:195], v[30:33]
	v_mfma_f32_16x16x32_bf16 v[26:29], v[148:151], v[188:191], v[26:29]
	v_mfma_f32_16x16x32_bf16 v[26:29], v[152:155], v[192:195], v[26:29]
	v_mfma_f32_16x16x32_bf16 v[22:25], v[156:159], v[188:191], v[22:25]
	v_mfma_f32_16x16x32_bf16 v[22:25], v[160:163], v[192:195], v[22:25]
	v_mfma_f32_16x16x32_bf16 v[18:21], v[164:167], v[188:191], v[18:21]
	v_mfma_f32_16x16x32_bf16 v[18:21], v[168:171], v[192:195], v[18:21]
	v_mfma_f32_16x16x32_bf16 v[2:5], v[164:167], v[196:199], v[2:5]
	v_mfma_f32_16x16x32_bf16 v[2:5], v[168:171], v[200:203], v[2:5]
	v_mfma_f32_16x16x32_bf16 v[6:9], v[156:159], v[196:199], v[6:9]
	v_mfma_f32_16x16x32_bf16 v[6:9], v[160:163], v[200:203], v[6:9]
	v_mfma_f32_16x16x32_bf16 v[10:13], v[148:151], v[196:199], v[10:13]
	v_mfma_f32_16x16x32_bf16 v[10:13], v[152:155], v[200:203], v[10:13]
	v_mfma_f32_16x16x32_bf16 v[14:17], v[132:135], v[196:199], v[14:17]
	v_mfma_f32_16x16x32_bf16 v[14:17], v[136:139], v[200:203], v[14:17]
	s_barrier
	s_add_i32 s62, s62, 2
	s_addk_i32 s61, 0x100
	s_cmp_ge_i32 s62, s3
	s_cbranch_scc0 .LBB0_1050

.LBB0_1181:
	v_add_u32_e32 v2, 0x10000, v232
	ds_read_b128 v[134:137], v2
	ds_read_b128 v[138:141], v2 offset:1024
	ds_read_b128 v[142:145], v2 offset:2048
	ds_read_b128 v[146:149], v2 offset:3072
	v_add_u32_e32 v2, 0x14000, v232
	ds_read_b128 v[150:153], v2
	ds_read_b128 v[154:157], v2 offset:1024
	ds_read_b128 v[158:161], v2 offset:2048
	ds_read_b128 v[162:165], v2 offset:3072
	s_add_i32 s50, s47, s90
	s_and_b64 s[18:19], exec, s[18:19]
	s_cselect_b32 s51, s88, s50
	s_add_i32 s50, s92, 0x80
	s_or_b32 s52, s51, 0x80
	s_add_i32 s18, s89, s93
	s_add_i32 s94, s94, 0x1bfffc80
	s_cmp_lt_u32 s91, 8
	s_cselect_b32 s18, s18, s94
	s_mov_b32 m0, s74
	s_add_i32 s19, s18, 0x80000
	ds_read_b128 v[166:169], v233
	ds_read_b128 v[170:173], v233 offset:1024
	ds_read_b128 v[174:177], v233 offset:2048
	ds_read_b128 v[178:181], v233 offset:3072
	ds_read_b128 v[182:185], v233 offset:4096
	ds_read_b128 v[186:189], v233 offset:5120
	ds_read_b128 v[190:193], v233 offset:6144
	ds_read_b128 v[194:197], v233 offset:7168
	buffer_load_dwordx4 v230, s[12:15], s19 offen lds
	s_mov_b32 m0, s75
	s_add_i32 s18, s18, 0xc0000
	buffer_load_dwordx4 v230, s[12:15], s18 offen lds
	s_waitcnt vmcnt(8) lgkmcnt(0)
	v_mfma_f32_16x16x32_bf16 v[130:133], v[134:137], v[166:169], v[130:133]
	s_barrier
	v_mfma_f32_16x16x32_bf16 v[130:133], v[138:141], v[170:173], v[130:133]
	v_mfma_f32_16x16x32_bf16 v[126:129], v[142:145], v[166:169], v[126:129]
	v_mfma_f32_16x16x32_bf16 v[126:129], v[146:149], v[170:173], v[126:129]
	v_mfma_f32_16x16x32_bf16 v[122:125], v[150:153], v[166:169], v[122:125]
	v_mfma_f32_16x16x32_bf16 v[122:125], v[154:157], v[170:173], v[122:125]
	v_mfma_f32_16x16x32_bf16 v[118:121], v[158:161], v[166:169], v[118:121]
	v_mfma_f32_16x16x32_bf16 v[118:121], v[162:165], v[170:173], v[118:121]
	v_mfma_f32_16x16x32_bf16 v[102:105], v[158:161], v[174:177], v[102:105]
	v_mfma_f32_16x16x32_bf16 v[102:105], v[162:165], v[178:181], v[102:105]
	v_mfma_f32_16x16x32_bf16 v[106:109], v[150:153], v[174:177], v[106:109]
	v_mfma_f32_16x16x32_bf16 v[106:109], v[154:157], v[178:181], v[106:109]
	v_mfma_f32_16x16x32_bf16 v[110:113], v[142:145], v[174:177], v[110:113]
	v_mfma_f32_16x16x32_bf16 v[110:113], v[146:149], v[178:181], v[110:113]
	v_mfma_f32_16x16x32_bf16 v[114:117], v[134:137], v[174:177], v[114:117]
	v_mfma_f32_16x16x32_bf16 v[114:117], v[138:141], v[178:181], v[114:117]
	v_mfma_f32_16x16x32_bf16 v[98:101], v[134:137], v[182:185], v[98:101]
	v_mfma_f32_16x16x32_bf16 v[98:101], v[138:141], v[186:189], v[98:101]
	v_mfma_f32_16x16x32_bf16 v[94:97], v[142:145], v[182:185], v[94:97]
	v_mfma_f32_16x16x32_bf16 v[94:97], v[146:149], v[186:189], v[94:97]
	v_mfma_f32_16x16x32_bf16 v[90:93], v[150:153], v[182:185], v[90:93]
	v_mfma_f32_16x16x32_bf16 v[90:93], v[154:157], v[186:189], v[90:93]
	v_mfma_f32_16x16x32_bf16 v[86:89], v[158:161], v[182:185], v[86:89]
	v_mfma_f32_16x16x32_bf16 v[86:89], v[162:165], v[186:189], v[86:89]
	v_mfma_f32_16x16x32_bf16 v[70:73], v[158:161], v[190:193], v[70:73]
	v_mfma_f32_16x16x32_bf16 v[70:73], v[162:165], v[194:197], v[70:73]
	v_mfma_f32_16x16x32_bf16 v[74:77], v[150:153], v[190:193], v[74:77]
	v_mfma_f32_16x16x32_bf16 v[74:77], v[154:157], v[194:197], v[74:77]
	v_mfma_f32_16x16x32_bf16 v[78:81], v[142:145], v[190:193], v[78:81]
	v_mfma_f32_16x16x32_bf16 v[78:81], v[146:149], v[194:197], v[78:81]
	v_mfma_f32_16x16x32_bf16 v[82:85], v[134:137], v[190:193], v[82:85]
	v_mfma_f32_16x16x32_bf16 v[82:85], v[138:141], v[194:197], v[82:85]
	s_barrier
	s_mov_b32 m0, s27
	s_mov_b32 s18, s14
	s_mov_b32 s19, s15
	ds_read_b128 v[166:169], v233 offset:16384
	ds_read_b128 v[170:173], v233 offset:17408
	ds_read_b128 v[174:177], v233 offset:18432
	ds_read_b128 v[178:181], v233 offset:19456
	ds_read_b128 v[182:185], v233 offset:20480
	ds_read_b128 v[186:189], v233 offset:21504
	ds_read_b128 v[190:193], v233 offset:22528
	ds_read_b128 v[194:197], v233 offset:23552
	buffer_load_dwordx4 v231, s[16:19], s51 offen lds
	s_mov_b32 m0, s30
	s_add_i32 s53, s51, 0x18000
	buffer_load_dwordx4 v231, s[16:19], s53 offen lds
	s_mov_b32 m0, s31
	s_add_i32 s53, s51, 0x30000
	buffer_load_dwordx4 v231, s[16:19], s53 offen lds
	s_mov_b32 m0, s54
	s_add_i32 s53, s51, 0x48000
	buffer_load_dwordx4 v231, s[16:19], s53 offen lds
	s_mov_b32 m0, s25
	s_add_i32 s53, s92, 0x40000
	buffer_load_dwordx4 v230, s[12:15], s92 offen lds
	s_mov_b32 m0, s55
	s_nop 0
	buffer_load_dwordx4 v230, s[12:15], s53 offen lds
	s_waitcnt vmcnt(8) lgkmcnt(0)
	v_mfma_f32_16x16x32_bf16 v[66:69], v[134:137], v[166:169], v[66:69]
	s_barrier
	v_mfma_f32_16x16x32_bf16 v[62:65], v[142:145], v[166:169], v[62:65]
	v_mfma_f32_16x16x32_bf16 v[50:53], v[134:137], v[174:177], v[50:53]
	v_mfma_f32_16x16x32_bf16 v[46:49], v[142:145], v[174:177], v[46:49]
	v_mfma_f32_16x16x32_bf16 v[34:37], v[134:137], v[182:185], v[34:37]
	v_mfma_f32_16x16x32_bf16 v[30:33], v[142:145], v[182:185], v[30:33]
	v_mfma_f32_16x16x32_bf16 v[18:21], v[134:137], v[190:193], v[18:21]
	v_mfma_f32_16x16x32_bf16 v[14:17], v[142:145], v[190:193], v[14:17]
	v_mfma_f32_16x16x32_bf16 v[58:61], v[150:153], v[166:169], v[58:61]
	v_mfma_f32_16x16x32_bf16 v[54:57], v[158:161], v[166:169], v[54:57]
	v_mfma_f32_16x16x32_bf16 v[42:45], v[150:153], v[174:177], v[42:45]
	v_mfma_f32_16x16x32_bf16 v[38:41], v[158:161], v[174:177], v[38:41]
	v_mfma_f32_16x16x32_bf16 v[26:29], v[150:153], v[182:185], v[26:29]
	v_mfma_f32_16x16x32_bf16 v[22:25], v[158:161], v[182:185], v[22:25]
	v_mfma_f32_16x16x32_bf16 v[10:13], v[150:153], v[190:193], v[10:13]
	v_mfma_f32_16x16x32_bf16 v[4:7], v[158:161], v[190:193], v[6:9]
	v_mfma_f32_16x16x32_bf16 v[66:69], v[138:141], v[170:173], v[66:69]
	v_mfma_f32_16x16x32_bf16 v[62:65], v[146:149], v[170:173], v[62:65]
	v_mfma_f32_16x16x32_bf16 v[50:53], v[138:141], v[178:181], v[50:53]
	v_mfma_f32_16x16x32_bf16 v[46:49], v[146:149], v[178:181], v[46:49]
	v_mfma_f32_16x16x32_bf16 v[34:37], v[138:141], v[186:189], v[34:37]
	v_mfma_f32_16x16x32_bf16 v[30:33], v[146:149], v[186:189], v[30:33]
	v_mfma_f32_16x16x32_bf16 v[18:21], v[138:141], v[194:197], v[18:21]
	v_mfma_f32_16x16x32_bf16 v[14:17], v[146:149], v[194:197], v[14:17]
	v_mfma_f32_16x16x32_bf16 v[58:61], v[154:157], v[170:173], v[58:61]
	v_mfma_f32_16x16x32_bf16 v[54:57], v[162:165], v[170:173], v[54:57]
	v_mfma_f32_16x16x32_bf16 v[42:45], v[154:157], v[178:181], v[42:45]
	v_mfma_f32_16x16x32_bf16 v[38:41], v[162:165], v[178:181], v[38:41]
	v_mfma_f32_16x16x32_bf16 v[26:29], v[154:157], v[186:189], v[26:29]
	v_mfma_f32_16x16x32_bf16 v[22:25], v[162:165], v[186:189], v[22:25]
	v_mfma_f32_16x16x32_bf16 v[10:13], v[154:157], v[194:197], v[10:13]
	v_mfma_f32_16x16x32_bf16 v[4:7], v[162:165], v[194:197], v[4:7]
	s_barrier
	v_add_u32_e32 v2, 0x18000, v232
	ds_read_b128 v[134:137], v2
	ds_read_b128 v[138:141], v2 offset:1024
	ds_read_b128 v[142:145], v2 offset:2048
	ds_read_b128 v[146:149], v2 offset:3072
	v_add_u32_e32 v2, 0x1c000, v232
	ds_read_b128 v[150:153], v2
	ds_read_b128 v[154:157], v2 offset:1024
	ds_read_b128 v[158:161], v2 offset:2048
	ds_read_b128 v[162:165], v2 offset:3072
	s_mov_b32 m0, s56
	s_add_i32 s53, s92, 0x80000
	ds_read_b128 v[166:169], v233 offset:32768
	ds_read_b128 v[170:173], v233 offset:33792
	ds_read_b128 v[174:177], v233 offset:34816
	ds_read_b128 v[178:181], v233 offset:35840
	ds_read_b128 v[182:185], v233 offset:36864
	ds_read_b128 v[186:189], v233 offset:37888
	ds_read_b128 v[190:193], v233 offset:38912
	ds_read_b128 v[194:197], v233 offset:39936
	buffer_load_dwordx4 v230, s[12:15], s53 offen lds
	s_mov_b32 m0, s57
	s_add_i32 s53, s92, 0xc0000
	buffer_load_dwordx4 v230, s[12:15], s53 offen lds
	s_waitcnt vmcnt(8) lgkmcnt(0)
	v_mfma_f32_16x16x32_bf16 v[130:133], v[134:137], v[166:169], v[130:133]
	s_barrier
	v_mfma_f32_16x16x32_bf16 v[130:133], v[138:141], v[170:173], v[130:133]
	v_mfma_f32_16x16x32_bf16 v[126:129], v[142:145], v[166:169], v[126:129]
	v_mfma_f32_16x16x32_bf16 v[126:129], v[146:149], v[170:173], v[126:129]
	v_mfma_f32_16x16x32_bf16 v[122:125], v[150:153], v[166:169], v[122:125]
	v_mfma_f32_16x16x32_bf16 v[122:125], v[154:157], v[170:173], v[122:125]
	v_mfma_f32_16x16x32_bf16 v[118:121], v[158:161], v[166:169], v[118:121]
	v_mfma_f32_16x16x32_bf16 v[118:121], v[162:165], v[170:173], v[118:121]
	v_mfma_f32_16x16x32_bf16 v[102:105], v[158:161], v[174:177], v[102:105]
	v_mfma_f32_16x16x32_bf16 v[102:105], v[162:165], v[178:181], v[102:105]
	v_mfma_f32_16x16x32_bf16 v[106:109], v[150:153], v[174:177], v[106:109]
	v_mfma_f32_16x16x32_bf16 v[106:109], v[154:157], v[178:181], v[106:109]
	v_mfma_f32_16x16x32_bf16 v[110:113], v[142:145], v[174:177], v[110:113]
	v_mfma_f32_16x16x32_bf16 v[110:113], v[146:149], v[178:181], v[110:113]
	v_mfma_f32_16x16x32_bf16 v[114:117], v[134:137], v[174:177], v[114:117]
	v_mfma_f32_16x16x32_bf16 v[114:117], v[138:141], v[178:181], v[114:117]
	v_mfma_f32_16x16x32_bf16 v[98:101], v[134:137], v[182:185], v[98:101]
	v_mfma_f32_16x16x32_bf16 v[98:101], v[138:141], v[186:189], v[98:101]
	v_mfma_f32_16x16x32_bf16 v[94:97], v[142:145], v[182:185], v[94:97]
	v_mfma_f32_16x16x32_bf16 v[94:97], v[146:149], v[186:189], v[94:97]
	v_mfma_f32_16x16x32_bf16 v[90:93], v[150:153], v[182:185], v[90:93]
	v_mfma_f32_16x16x32_bf16 v[90:93], v[154:157], v[186:189], v[90:93]
	v_mfma_f32_16x16x32_bf16 v[86:89], v[158:161], v[182:185], v[86:89]
	v_mfma_f32_16x16x32_bf16 v[86:89], v[162:165], v[186:189], v[86:89]
	v_mfma_f32_16x16x32_bf16 v[70:73], v[158:161], v[190:193], v[70:73]
	v_mfma_f32_16x16x32_bf16 v[70:73], v[162:165], v[194:197], v[70:73]
	v_mfma_f32_16x16x32_bf16 v[74:77], v[150:153], v[190:193], v[74:77]
	v_mfma_f32_16x16x32_bf16 v[74:77], v[154:157], v[194:197], v[74:77]
	v_mfma_f32_16x16x32_bf16 v[78:81], v[142:145], v[190:193], v[78:81]
	v_mfma_f32_16x16x32_bf16 v[78:81], v[146:149], v[194:197], v[78:81]
	v_mfma_f32_16x16x32_bf16 v[82:85], v[134:137], v[190:193], v[82:85]
	v_mfma_f32_16x16x32_bf16 v[82:85], v[138:141], v[194:197], v[82:85]
	s_barrier
	s_mov_b32 m0, s64
	ds_read_b128 v[166:169], v233 offset:49152
	ds_read_b128 v[170:173], v233 offset:50176
	ds_read_b128 v[174:177], v233 offset:51200
	ds_read_b128 v[178:181], v233 offset:52224
	ds_read_b128 v[182:185], v233 offset:53248
	ds_read_b128 v[186:189], v233 offset:54272
	ds_read_b128 v[190:193], v233 offset:55296
	ds_read_b128 v[194:197], v233 offset:56320
	buffer_load_dwordx4 v231, s[16:19], s52 offen lds
	s_mov_b32 m0, s65
	s_add_i32 s52, s51, 0x18080
	buffer_load_dwordx4 v231, s[16:19], s52 offen lds
	s_add_i32 s52, s51, 0x30080
	s_mov_b32 m0, s68
	s_add_i32 s51, s51, 0x48080
	buffer_load_dwordx4 v231, s[16:19], s52 offen lds
	s_mov_b32 m0, s69
	s_nop 0
	buffer_load_dwordx4 v231, s[16:19], s51 offen lds
	s_mov_b32 m0, s66
	s_add_i32 s18, s92, 0x40080
	buffer_load_dwordx4 v230, s[12:15], s50 offen lds
	s_mov_b32 m0, s67
	s_nop 0
	buffer_load_dwordx4 v230, s[12:15], s18 offen lds
	s_waitcnt vmcnt(8) lgkmcnt(0)
	v_mfma_f32_16x16x32_bf16 v[66:69], v[134:137], v[166:169], v[66:69]
	s_barrier
	v_mfma_f32_16x16x32_bf16 v[62:65], v[142:145], v[166:169], v[62:65]
	v_mfma_f32_16x16x32_bf16 v[50:53], v[134:137], v[174:177], v[50:53]
	v_mfma_f32_16x16x32_bf16 v[46:49], v[142:145], v[174:177], v[46:49]
	v_mfma_f32_16x16x32_bf16 v[34:37], v[134:137], v[182:185], v[34:37]
	v_mfma_f32_16x16x32_bf16 v[30:33], v[142:145], v[182:185], v[30:33]
	v_mfma_f32_16x16x32_bf16 v[18:21], v[134:137], v[190:193], v[18:21]
	v_mfma_f32_16x16x32_bf16 v[14:17], v[142:145], v[190:193], v[14:17]
	v_mfma_f32_16x16x32_bf16 v[58:61], v[150:153], v[166:169], v[58:61]
	v_mfma_f32_16x16x32_bf16 v[54:57], v[158:161], v[166:169], v[54:57]
	v_mfma_f32_16x16x32_bf16 v[42:45], v[150:153], v[174:177], v[42:45]
	v_mfma_f32_16x16x32_bf16 v[38:41], v[158:161], v[174:177], v[38:41]
	v_mfma_f32_16x16x32_bf16 v[26:29], v[150:153], v[182:185], v[26:29]
	v_mfma_f32_16x16x32_bf16 v[22:25], v[158:161], v[182:185], v[22:25]
	v_mfma_f32_16x16x32_bf16 v[8:11], v[150:153], v[190:193], v[10:13]
	v_mfma_f32_16x16x32_bf16 v[4:7], v[158:161], v[190:193], v[4:7]
	v_mfma_f32_16x16x32_bf16 v[66:69], v[138:141], v[170:173], v[66:69]
	v_mfma_f32_16x16x32_bf16 v[62:65], v[146:149], v[170:173], v[62:65]
	v_mfma_f32_16x16x32_bf16 v[50:53], v[138:141], v[178:181], v[50:53]
	v_mfma_f32_16x16x32_bf16 v[46:49], v[146:149], v[178:181], v[46:49]
	v_mfma_f32_16x16x32_bf16 v[34:37], v[138:141], v[186:189], v[34:37]
	v_mfma_f32_16x16x32_bf16 v[30:33], v[146:149], v[186:189], v[30:33]
	v_mfma_f32_16x16x32_bf16 v[18:21], v[138:141], v[194:197], v[18:21]
	v_mfma_f32_16x16x32_bf16 v[14:17], v[146:149], v[194:197], v[14:17]
	v_mfma_f32_16x16x32_bf16 v[58:61], v[154:157], v[170:173], v[58:61]
	v_mfma_f32_16x16x32_bf16 v[54:57], v[162:165], v[170:173], v[54:57]
	v_mfma_f32_16x16x32_bf16 v[42:45], v[154:157], v[178:181], v[42:45]
	v_mfma_f32_16x16x32_bf16 v[38:41], v[162:165], v[178:181], v[38:41]
	v_mfma_f32_16x16x32_bf16 v[26:29], v[154:157], v[186:189], v[26:29]
	v_mfma_f32_16x16x32_bf16 v[22:25], v[162:165], v[186:189], v[22:25]
	v_mfma_f32_16x16x32_bf16 v[10:13], v[154:157], v[194:197], v[8:11]
	v_mfma_f32_16x16x32_bf16 v[6:9], v[162:165], v[194:197], v[4:7]
	s_barrier
	s_add_i32 s91, s91, 2
	s_addk_i32 s90, 0x100
	s_cmp_ge_i32 s91, s3
	s_cbranch_scc1 .LBB0_1193

.LBB0_1290:
	ds_read_b128 v[106:109], v224
	ds_read_b128 v[118:121], v224 offset:1024
	ds_read_b128 v[130:133], v224 offset:2048
	ds_read_b128 v[138:141], v224 offset:3072
	ds_read_b128 v[146:149], v225
	ds_read_b128 v[150:153], v225 offset:1024
	ds_read_b128 v[154:157], v225 offset:2048
	ds_read_b128 v[158:161], v225 offset:3072
	s_add_i32 s18, s72, 0xffe80080
	s_cmp_eq_u32 s56, s74
	s_cselect_b32 s75, s6, s18
	s_cselect_b32 s77, s7, s73
	s_or_b32 s76, s75, 0x80
	s_add_i32 s18, s72, 0xfff80000
	s_mov_b32 m0, s57
	ds_read_b128 v[162:165], v226
	ds_read_b128 v[166:169], v226 offset:1024
	ds_read_b128 v[170:173], v226 offset:2048
	ds_read_b128 v[174:177], v226 offset:3072
	ds_read_b128 v[178:181], v226 offset:4096
	ds_read_b128 v[182:185], v226 offset:5120
	ds_read_b128 v[190:193], v226 offset:6144
	ds_read_b128 v[194:197], v226 offset:7168
	buffer_load_dwordx4 v222, s[12:15], s18 offen lds
	s_mov_b32 m0, s60
	s_nop 0
	buffer_load_dwordx4 v222, s[12:15], s72 offen lds
	s_waitcnt vmcnt(8) lgkmcnt(0)
	v_mfma_f32_16x16x32_bf16 v[142:145], v[106:109], v[162:165], v[142:145]
	s_barrier
	v_mfma_f32_16x16x32_bf16 v[142:145], v[118:121], v[166:169], v[142:145]
	v_mfma_f32_16x16x32_bf16 v[134:137], v[130:133], v[162:165], v[134:137]
	v_mfma_f32_16x16x32_bf16 v[134:137], v[138:141], v[166:169], v[134:137]
	v_mfma_f32_16x16x32_bf16 v[126:129], v[146:149], v[162:165], v[126:129]
	v_mfma_f32_16x16x32_bf16 v[126:129], v[150:153], v[166:169], v[126:129]
	v_mfma_f32_16x16x32_bf16 v[122:125], v[154:157], v[162:165], v[122:125]
	v_mfma_f32_16x16x32_bf16 v[122:125], v[158:161], v[166:169], v[122:125]
	v_mfma_f32_16x16x32_bf16 v[98:101], v[154:157], v[170:173], v[98:101]
	v_mfma_f32_16x16x32_bf16 v[98:101], v[158:161], v[174:177], v[98:101]
	v_mfma_f32_16x16x32_bf16 v[102:105], v[146:149], v[170:173], v[102:105]
	v_mfma_f32_16x16x32_bf16 v[102:105], v[150:153], v[174:177], v[102:105]
	v_mfma_f32_16x16x32_bf16 v[110:113], v[130:133], v[170:173], v[110:113]
	v_mfma_f32_16x16x32_bf16 v[110:113], v[138:141], v[174:177], v[110:113]
	v_mfma_f32_16x16x32_bf16 v[114:117], v[106:109], v[170:173], v[114:117]
	v_mfma_f32_16x16x32_bf16 v[114:117], v[118:121], v[174:177], v[114:117]
	v_mfma_f32_16x16x32_bf16 v[94:97], v[106:109], v[178:181], v[94:97]
	v_mfma_f32_16x16x32_bf16 v[94:97], v[118:121], v[182:185], v[94:97]
	v_mfma_f32_16x16x32_bf16 v[90:93], v[130:133], v[178:181], v[90:93]
	v_mfma_f32_16x16x32_bf16 v[90:93], v[138:141], v[182:185], v[90:93]
	v_mfma_f32_16x16x32_bf16 v[86:89], v[146:149], v[178:181], v[86:89]
	v_mfma_f32_16x16x32_bf16 v[86:89], v[150:153], v[182:185], v[86:89]
	v_mfma_f32_16x16x32_bf16 v[82:85], v[154:157], v[178:181], v[82:85]
	v_mfma_f32_16x16x32_bf16 v[82:85], v[158:161], v[182:185], v[82:85]
	v_mfma_f32_16x16x32_bf16 v[66:69], v[154:157], v[190:193], v[66:69]
	v_mfma_f32_16x16x32_bf16 v[66:69], v[158:161], v[194:197], v[66:69]
	v_mfma_f32_16x16x32_bf16 v[70:73], v[146:149], v[190:193], v[70:73]
	v_mfma_f32_16x16x32_bf16 v[70:73], v[150:153], v[194:197], v[70:73]
	v_mfma_f32_16x16x32_bf16 v[74:77], v[130:133], v[190:193], v[74:77]
	v_mfma_f32_16x16x32_bf16 v[74:77], v[138:141], v[194:197], v[74:77]
	v_mfma_f32_16x16x32_bf16 v[78:81], v[106:109], v[190:193], v[78:81]
	v_mfma_f32_16x16x32_bf16 v[78:81], v[118:121], v[194:197], v[78:81]
	s_barrier
	s_mov_b32 m0, s27
	s_mov_b32 s18, s14
	s_mov_b32 s19, s15
	ds_read_b128 v[162:165], v226 offset:16384
	ds_read_b128 v[166:169], v226 offset:17408
	ds_read_b128 v[170:173], v226 offset:18432
	ds_read_b128 v[174:177], v226 offset:19456
	ds_read_b128 v[178:181], v226 offset:20480
	ds_read_b128 v[182:185], v226 offset:21504
	ds_read_b128 v[190:193], v226 offset:22528
	ds_read_b128 v[194:197], v226 offset:23552
	buffer_load_dwordx4 v223, s[16:19], s77 offen lds
	s_mov_b32 m0, s30
	s_add_i32 s78, s77, 0x80000
	buffer_load_dwordx4 v223, s[16:19], s78 offen lds
	s_mov_b32 m0, s31
	s_add_i32 s78, s77, 0x100000
	buffer_load_dwordx4 v223, s[16:19], s78 offen lds
	s_mov_b32 m0, s41
	s_add_i32 s78, s77, 0x180000
	buffer_load_dwordx4 v223, s[16:19], s78 offen lds
	s_mov_b32 m0, s25
	s_add_i32 s78, s75, 0x80000
	buffer_load_dwordx4 v222, s[12:15], s75 offen lds
	s_mov_b32 m0, s42
	s_nop 0
	buffer_load_dwordx4 v222, s[12:15], s78 offen lds
	s_waitcnt vmcnt(8) lgkmcnt(0)
	v_mfma_f32_16x16x32_bf16 v[62:65], v[106:109], v[162:165], v[62:65]
	s_barrier
	v_mfma_f32_16x16x32_bf16 v[62:65], v[118:121], v[166:169], v[62:65]
	v_mfma_f32_16x16x32_bf16 v[58:61], v[130:133], v[162:165], v[58:61]
	v_mfma_f32_16x16x32_bf16 v[58:61], v[138:141], v[166:169], v[58:61]
	v_mfma_f32_16x16x32_bf16 v[54:57], v[146:149], v[162:165], v[54:57]
	v_mfma_f32_16x16x32_bf16 v[54:57], v[150:153], v[166:169], v[54:57]
	v_mfma_f32_16x16x32_bf16 v[50:53], v[154:157], v[162:165], v[50:53]
	v_mfma_f32_16x16x32_bf16 v[50:53], v[158:161], v[166:169], v[50:53]
	v_mfma_f32_16x16x32_bf16 v[34:37], v[154:157], v[170:173], v[34:37]
	v_mfma_f32_16x16x32_bf16 v[34:37], v[158:161], v[174:177], v[34:37]
	v_mfma_f32_16x16x32_bf16 v[38:41], v[146:149], v[170:173], v[38:41]
	v_mfma_f32_16x16x32_bf16 v[38:41], v[150:153], v[174:177], v[38:41]
	v_mfma_f32_16x16x32_bf16 v[42:45], v[130:133], v[170:173], v[42:45]
	v_mfma_f32_16x16x32_bf16 v[42:45], v[138:141], v[174:177], v[42:45]
	v_mfma_f32_16x16x32_bf16 v[46:49], v[106:109], v[170:173], v[46:49]
	v_mfma_f32_16x16x32_bf16 v[46:49], v[118:121], v[174:177], v[46:49]
	v_mfma_f32_16x16x32_bf16 v[30:33], v[106:109], v[178:181], v[30:33]
	v_mfma_f32_16x16x32_bf16 v[30:33], v[118:121], v[182:185], v[30:33]
	v_mfma_f32_16x16x32_bf16 v[26:29], v[130:133], v[178:181], v[26:29]
	v_mfma_f32_16x16x32_bf16 v[26:29], v[138:141], v[182:185], v[26:29]
	v_mfma_f32_16x16x32_bf16 v[22:25], v[146:149], v[178:181], v[22:25]
	v_mfma_f32_16x16x32_bf16 v[22:25], v[150:153], v[182:185], v[22:25]
	v_mfma_f32_16x16x32_bf16 v[18:21], v[154:157], v[178:181], v[18:21]
	v_mfma_f32_16x16x32_bf16 v[18:21], v[158:161], v[182:185], v[18:21]
	v_mfma_f32_16x16x32_bf16 v[2:5], v[154:157], v[190:193], v[2:5]
	v_mfma_f32_16x16x32_bf16 v[2:5], v[158:161], v[194:197], v[2:5]
	v_mfma_f32_16x16x32_bf16 v[6:9], v[146:149], v[190:193], v[6:9]
	v_mfma_f32_16x16x32_bf16 v[6:9], v[150:153], v[194:197], v[6:9]
	v_mfma_f32_16x16x32_bf16 v[10:13], v[130:133], v[190:193], v[10:13]
	v_mfma_f32_16x16x32_bf16 v[10:13], v[138:141], v[194:197], v[10:13]
	v_mfma_f32_16x16x32_bf16 v[14:17], v[106:109], v[190:193], v[14:17]
	v_mfma_f32_16x16x32_bf16 v[14:17], v[118:121], v[194:197], v[14:17]
	s_barrier
	ds_read_b128 v[106:109], v227
	ds_read_b128 v[118:121], v227 offset:1024
	ds_read_b128 v[130:133], v227 offset:2048
	ds_read_b128 v[138:141], v227 offset:3072
	ds_read_b128 v[146:149], v228
	ds_read_b128 v[150:153], v228 offset:1024
	ds_read_b128 v[154:157], v228 offset:2048
	ds_read_b128 v[158:161], v228 offset:3072
	s_mov_b32 m0, s43
	s_add_i32 s78, s75, 0x100000
	ds_read_b128 v[162:165], v226 offset:32768
	ds_read_b128 v[166:169], v226 offset:33792
	ds_read_b128 v[170:173], v226 offset:34816
	ds_read_b128 v[174:177], v226 offset:35840
	ds_read_b128 v[178:181], v226 offset:36864
	ds_read_b128 v[182:185], v226 offset:37888
	ds_read_b128 v[190:193], v226 offset:38912
	ds_read_b128 v[194:197], v226 offset:39936
	buffer_load_dwordx4 v222, s[12:15], s78 offen lds
	s_mov_b32 m0, s44
	s_add_i32 s78, s75, 0x180000
	buffer_load_dwordx4 v222, s[12:15], s78 offen lds
	s_waitcnt vmcnt(8) lgkmcnt(0)
	v_mfma_f32_16x16x32_bf16 v[142:145], v[106:109], v[162:165], v[142:145]
	s_barrier
	v_mfma_f32_16x16x32_bf16 v[142:145], v[118:121], v[166:169], v[142:145]
	v_mfma_f32_16x16x32_bf16 v[134:137], v[130:133], v[162:165], v[134:137]
	v_mfma_f32_16x16x32_bf16 v[134:137], v[138:141], v[166:169], v[134:137]
	v_mfma_f32_16x16x32_bf16 v[126:129], v[146:149], v[162:165], v[126:129]
	v_mfma_f32_16x16x32_bf16 v[126:129], v[150:153], v[166:169], v[126:129]
	v_mfma_f32_16x16x32_bf16 v[122:125], v[154:157], v[162:165], v[122:125]
	v_mfma_f32_16x16x32_bf16 v[122:125], v[158:161], v[166:169], v[122:125]
	v_mfma_f32_16x16x32_bf16 v[98:101], v[154:157], v[170:173], v[98:101]
	v_mfma_f32_16x16x32_bf16 v[98:101], v[158:161], v[174:177], v[98:101]
	v_mfma_f32_16x16x32_bf16 v[102:105], v[146:149], v[170:173], v[102:105]
	v_mfma_f32_16x16x32_bf16 v[102:105], v[150:153], v[174:177], v[102:105]
	v_mfma_f32_16x16x32_bf16 v[110:113], v[130:133], v[170:173], v[110:113]
	v_mfma_f32_16x16x32_bf16 v[110:113], v[138:141], v[174:177], v[110:113]
	v_mfma_f32_16x16x32_bf16 v[114:117], v[106:109], v[170:173], v[114:117]
	v_mfma_f32_16x16x32_bf16 v[114:117], v[118:121], v[174:177], v[114:117]
	v_mfma_f32_16x16x32_bf16 v[94:97], v[106:109], v[178:181], v[94:97]
	v_mfma_f32_16x16x32_bf16 v[94:97], v[118:121], v[182:185], v[94:97]
	v_mfma_f32_16x16x32_bf16 v[90:93], v[130:133], v[178:181], v[90:93]
	v_mfma_f32_16x16x32_bf16 v[90:93], v[138:141], v[182:185], v[90:93]
	v_mfma_f32_16x16x32_bf16 v[86:89], v[146:149], v[178:181], v[86:89]
	v_mfma_f32_16x16x32_bf16 v[86:89], v[150:153], v[182:185], v[86:89]
	v_mfma_f32_16x16x32_bf16 v[82:85], v[154:157], v[178:181], v[82:85]
	v_mfma_f32_16x16x32_bf16 v[82:85], v[158:161], v[182:185], v[82:85]
	v_mfma_f32_16x16x32_bf16 v[66:69], v[154:157], v[190:193], v[66:69]
	v_mfma_f32_16x16x32_bf16 v[66:69], v[158:161], v[194:197], v[66:69]
	v_mfma_f32_16x16x32_bf16 v[70:73], v[146:149], v[190:193], v[70:73]
	v_mfma_f32_16x16x32_bf16 v[70:73], v[150:153], v[194:197], v[70:73]
	v_mfma_f32_16x16x32_bf16 v[74:77], v[130:133], v[190:193], v[74:77]
	v_mfma_f32_16x16x32_bf16 v[74:77], v[138:141], v[194:197], v[74:77]
	v_mfma_f32_16x16x32_bf16 v[78:81], v[106:109], v[190:193], v[78:81]
	v_mfma_f32_16x16x32_bf16 v[78:81], v[118:121], v[194:197], v[78:81]
	s_barrier
	s_mov_b32 m0, s48
	s_or_b32 s78, s77, 0x80
	ds_read_b128 v[162:165], v226 offset:49152
	ds_read_b128 v[166:169], v226 offset:50176
	ds_read_b128 v[170:173], v226 offset:51200
	ds_read_b128 v[174:177], v226 offset:52224
	ds_read_b128 v[178:181], v226 offset:53248
	ds_read_b128 v[182:185], v226 offset:54272
	ds_read_b128 v[190:193], v226 offset:55296
	ds_read_b128 v[194:197], v226 offset:56320
	buffer_load_dwordx4 v223, s[16:19], s78 offen lds
	s_add_i32 s78, s77, 0x80080
	s_mov_b32 m0, s49
	s_add_i32 s75, s75, 0x80080
	buffer_load_dwordx4 v223, s[16:19], s78 offen lds
	s_add_i32 s78, s77, 0x100080
	s_mov_b32 m0, s52
	s_add_i32 s77, s77, 0x180080
	buffer_load_dwordx4 v223, s[16:19], s78 offen lds
	s_mov_b32 m0, s53
	s_nop 0
	buffer_load_dwordx4 v223, s[16:19], s77 offen lds
	s_mov_b32 m0, s50
	s_nop 0
	buffer_load_dwordx4 v222, s[12:15], s76 offen lds
	s_mov_b32 m0, s51
	s_nop 0
	buffer_load_dwordx4 v222, s[12:15], s75 offen lds
	s_waitcnt vmcnt(8) lgkmcnt(0)
	v_mfma_f32_16x16x32_bf16 v[62:65], v[106:109], v[162:165], v[62:65]
	s_barrier
	v_mfma_f32_16x16x32_bf16 v[62:65], v[118:121], v[166:169], v[62:65]
	v_mfma_f32_16x16x32_bf16 v[58:61], v[130:133], v[162:165], v[58:61]
	v_mfma_f32_16x16x32_bf16 v[58:61], v[138:141], v[166:169], v[58:61]
	v_mfma_f32_16x16x32_bf16 v[54:57], v[146:149], v[162:165], v[54:57]
	v_mfma_f32_16x16x32_bf16 v[54:57], v[150:153], v[166:169], v[54:57]
	v_mfma_f32_16x16x32_bf16 v[50:53], v[154:157], v[162:165], v[50:53]
	v_mfma_f32_16x16x32_bf16 v[50:53], v[158:161], v[166:169], v[50:53]
	v_mfma_f32_16x16x32_bf16 v[34:37], v[154:157], v[170:173], v[34:37]
	v_mfma_f32_16x16x32_bf16 v[34:37], v[158:161], v[174:177], v[34:37]
	v_mfma_f32_16x16x32_bf16 v[38:41], v[146:149], v[170:173], v[38:41]
	v_mfma_f32_16x16x32_bf16 v[38:41], v[150:153], v[174:177], v[38:41]
	v_mfma_f32_16x16x32_bf16 v[42:45], v[130:133], v[170:173], v[42:45]
	v_mfma_f32_16x16x32_bf16 v[42:45], v[138:141], v[174:177], v[42:45]
	v_mfma_f32_16x16x32_bf16 v[46:49], v[106:109], v[170:173], v[46:49]
	v_mfma_f32_16x16x32_bf16 v[46:49], v[118:121], v[174:177], v[46:49]
	v_mfma_f32_16x16x32_bf16 v[30:33], v[106:109], v[178:181], v[30:33]
	v_mfma_f32_16x16x32_bf16 v[30:33], v[118:121], v[182:185], v[30:33]
	v_mfma_f32_16x16x32_bf16 v[26:29], v[130:133], v[178:181], v[26:29]
	v_mfma_f32_16x16x32_bf16 v[26:29], v[138:141], v[182:185], v[26:29]
	v_mfma_f32_16x16x32_bf16 v[22:25], v[146:149], v[178:181], v[22:25]
	v_mfma_f32_16x16x32_bf16 v[22:25], v[150:153], v[182:185], v[22:25]
	v_mfma_f32_16x16x32_bf16 v[18:21], v[154:157], v[178:181], v[18:21]
	v_mfma_f32_16x16x32_bf16 v[18:21], v[158:161], v[182:185], v[18:21]
	v_mfma_f32_16x16x32_bf16 v[2:5], v[154:157], v[190:193], v[2:5]
	v_mfma_f32_16x16x32_bf16 v[2:5], v[158:161], v[194:197], v[2:5]
	v_mfma_f32_16x16x32_bf16 v[6:9], v[146:149], v[190:193], v[6:9]
	v_mfma_f32_16x16x32_bf16 v[6:9], v[150:153], v[194:197], v[6:9]
	v_mfma_f32_16x16x32_bf16 v[10:13], v[130:133], v[190:193], v[10:13]
	v_mfma_f32_16x16x32_bf16 v[10:13], v[138:141], v[194:197], v[10:13]
	v_mfma_f32_16x16x32_bf16 v[14:17], v[106:109], v[190:193], v[14:17]
	v_mfma_f32_16x16x32_bf16 v[14:17], v[118:121], v[194:197], v[14:17]
	s_barrier
	s_add_i32 s74, s74, 2
	s_addk_i32 s72, 0x100
	s_addk_i32 s73, 0x100
	s_cmp_ge_i32 s74, s3
	s_cbranch_scc0 .LBB0_1290
	s_and_b64 vcc, exec, s[38:39]
	s_cbranch_vccz .LBB0_1293

.LBB0_1382:
	ds_read_b128 v[144:147], v138
	ds_read_b128 v[148:151], v138 offset:1024
	ds_read_b128 v[152:155], v138 offset:2048
	ds_read_b128 v[156:159], v138 offset:3072
	ds_read_b128 v[160:163], v139
	ds_read_b128 v[164:167], v139 offset:1024
	ds_read_b128 v[168:171], v139 offset:2048
	ds_read_b128 v[172:175], v139 offset:3072
	s_add_i32 s14, s74, 0xffe80080
	s_cmp_eq_u32 s61, s76
	s_cselect_b32 s77, s72, s14
	s_cselect_b32 s79, s73, s75
	s_or_b32 s78, s77, 0x80
	s_add_i32 s14, s74, 0xfff80000
	s_mov_b32 m0, s62
	ds_read_b128 v[176:179], v140
	ds_read_b128 v[180:183], v140 offset:1024
	ds_read_b128 v[184:187], v140 offset:2048
	ds_read_b128 v[188:191], v140 offset:3072
	ds_read_b128 v[192:195], v140 offset:4096
	ds_read_b128 v[196:199], v140 offset:5120
	ds_read_b128 v[200:203], v140 offset:6144
	ds_read_b128 v[204:207], v140 offset:7168
	buffer_load_dwordx4 v136, s[16:19], s14 offen lds
	s_mov_b32 m0, s63
	s_nop 0
	buffer_load_dwordx4 v136, s[16:19], s74 offen lds
	s_waitcnt vmcnt(8) lgkmcnt(0)
	v_mfma_f32_16x16x32_bf16 v[118:121], v[144:147], v[176:179], v[118:121]
	s_barrier
	v_mfma_f32_16x16x32_bf16 v[118:121], v[148:151], v[180:183], v[118:121]
	v_mfma_f32_16x16x32_bf16 v[114:117], v[152:155], v[176:179], v[114:117]
	v_mfma_f32_16x16x32_bf16 v[114:117], v[156:159], v[180:183], v[114:117]
	v_mfma_f32_16x16x32_bf16 v[126:129], v[160:163], v[176:179], v[126:129]
	v_mfma_f32_16x16x32_bf16 v[126:129], v[164:167], v[180:183], v[126:129]
	v_mfma_f32_16x16x32_bf16 v[122:125], v[168:171], v[176:179], v[122:125]
	v_mfma_f32_16x16x32_bf16 v[122:125], v[172:175], v[180:183], v[122:125]
	v_mfma_f32_16x16x32_bf16 v[98:101], v[168:171], v[184:187], v[98:101]
	v_mfma_f32_16x16x32_bf16 v[98:101], v[172:175], v[188:191], v[98:101]
	v_mfma_f32_16x16x32_bf16 v[106:109], v[160:163], v[184:187], v[106:109]
	v_mfma_f32_16x16x32_bf16 v[106:109], v[164:167], v[188:191], v[106:109]
	v_mfma_f32_16x16x32_bf16 v[102:105], v[152:155], v[184:187], v[102:105]
	v_mfma_f32_16x16x32_bf16 v[102:105], v[156:159], v[188:191], v[102:105]
	v_mfma_f32_16x16x32_bf16 v[110:113], v[144:147], v[184:187], v[110:113]
	v_mfma_f32_16x16x32_bf16 v[110:113], v[148:151], v[188:191], v[110:113]
	v_mfma_f32_16x16x32_bf16 v[94:97], v[144:147], v[192:195], v[94:97]
	v_mfma_f32_16x16x32_bf16 v[94:97], v[148:151], v[196:199], v[94:97]
	v_mfma_f32_16x16x32_bf16 v[86:89], v[152:155], v[192:195], v[86:89]
	v_mfma_f32_16x16x32_bf16 v[86:89], v[156:159], v[196:199], v[86:89]
	v_mfma_f32_16x16x32_bf16 v[90:93], v[160:163], v[192:195], v[90:93]
	v_mfma_f32_16x16x32_bf16 v[90:93], v[164:167], v[196:199], v[90:93]
	v_mfma_f32_16x16x32_bf16 v[82:85], v[168:171], v[192:195], v[82:85]
	v_mfma_f32_16x16x32_bf16 v[82:85], v[172:175], v[196:199], v[82:85]
	v_mfma_f32_16x16x32_bf16 v[70:73], v[168:171], v[200:203], v[70:73]
	v_mfma_f32_16x16x32_bf16 v[70:73], v[172:175], v[204:207], v[70:73]
	v_mfma_f32_16x16x32_bf16 v[74:77], v[160:163], v[200:203], v[74:77]
	v_mfma_f32_16x16x32_bf16 v[74:77], v[164:167], v[204:207], v[74:77]
	v_mfma_f32_16x16x32_bf16 v[66:69], v[152:155], v[200:203], v[66:69]
	v_mfma_f32_16x16x32_bf16 v[66:69], v[156:159], v[204:207], v[66:69]
	v_mfma_f32_16x16x32_bf16 v[78:81], v[144:147], v[200:203], v[78:81]
	v_mfma_f32_16x16x32_bf16 v[78:81], v[148:151], v[204:207], v[78:81]
	s_barrier
	s_mov_b32 m0, s45
	s_mov_b32 s14, s18
	s_mov_b32 s15, s19
	ds_read_b128 v[176:179], v140 offset:16384
	ds_read_b128 v[180:183], v140 offset:17408
	ds_read_b128 v[184:187], v140 offset:18432
	ds_read_b128 v[188:191], v140 offset:19456
	ds_read_b128 v[192:195], v140 offset:20480
	ds_read_b128 v[196:199], v140 offset:21504
	ds_read_b128 v[200:203], v140 offset:22528
	ds_read_b128 v[204:207], v140 offset:23552
	buffer_load_dwordx4 v137, s[12:15], s79 offen lds
	s_mov_b32 m0, s46
	s_add_i32 s80, s79, 0x80000
	buffer_load_dwordx4 v137, s[12:15], s80 offen lds
	s_mov_b32 m0, s47
	s_add_i32 s80, s79, 0x100000
	buffer_load_dwordx4 v137, s[12:15], s80 offen lds
	s_mov_b32 m0, s48
	s_add_i32 s80, s79, 0x180000
	buffer_load_dwordx4 v137, s[12:15], s80 offen lds
	s_mov_b32 m0, s44
	s_add_i32 s80, s77, 0x80000
	buffer_load_dwordx4 v136, s[16:19], s77 offen lds
	s_mov_b32 m0, s49
	s_nop 0
	buffer_load_dwordx4 v136, s[16:19], s80 offen lds
	s_waitcnt vmcnt(8) lgkmcnt(0)
	v_mfma_f32_16x16x32_bf16 v[62:65], v[144:147], v[176:179], v[62:65]
	s_barrier
	v_mfma_f32_16x16x32_bf16 v[62:65], v[148:151], v[180:183], v[62:65]
	v_mfma_f32_16x16x32_bf16 v[54:57], v[152:155], v[176:179], v[54:57]
	v_mfma_f32_16x16x32_bf16 v[54:57], v[156:159], v[180:183], v[54:57]
	v_mfma_f32_16x16x32_bf16 v[58:61], v[160:163], v[176:179], v[58:61]
	v_mfma_f32_16x16x32_bf16 v[58:61], v[164:167], v[180:183], v[58:61]
	v_mfma_f32_16x16x32_bf16 v[50:53], v[168:171], v[176:179], v[50:53]
	v_mfma_f32_16x16x32_bf16 v[50:53], v[172:175], v[180:183], v[50:53]
	v_mfma_f32_16x16x32_bf16 v[34:37], v[168:171], v[184:187], v[34:37]
	v_mfma_f32_16x16x32_bf16 v[34:37], v[172:175], v[188:191], v[34:37]
	v_mfma_f32_16x16x32_bf16 v[42:45], v[160:163], v[184:187], v[42:45]
	v_mfma_f32_16x16x32_bf16 v[42:45], v[164:167], v[188:191], v[42:45]
	v_mfma_f32_16x16x32_bf16 v[38:41], v[152:155], v[184:187], v[38:41]
	v_mfma_f32_16x16x32_bf16 v[38:41], v[156:159], v[188:191], v[38:41]
	v_mfma_f32_16x16x32_bf16 v[46:49], v[144:147], v[184:187], v[46:49]
	v_mfma_f32_16x16x32_bf16 v[46:49], v[148:151], v[188:191], v[46:49]
	v_mfma_f32_16x16x32_bf16 v[30:33], v[144:147], v[192:195], v[30:33]
	v_mfma_f32_16x16x32_bf16 v[30:33], v[148:151], v[196:199], v[30:33]
	v_mfma_f32_16x16x32_bf16 v[22:25], v[152:155], v[192:195], v[22:25]
	v_mfma_f32_16x16x32_bf16 v[22:25], v[156:159], v[196:199], v[22:25]
	v_mfma_f32_16x16x32_bf16 v[26:29], v[160:163], v[192:195], v[26:29]
	v_mfma_f32_16x16x32_bf16 v[26:29], v[164:167], v[196:199], v[26:29]
	v_mfma_f32_16x16x32_bf16 v[18:21], v[168:171], v[192:195], v[18:21]
	v_mfma_f32_16x16x32_bf16 v[18:21], v[172:175], v[196:199], v[18:21]
	v_mfma_f32_16x16x32_bf16 v[2:5], v[168:171], v[200:203], v[2:5]
	v_mfma_f32_16x16x32_bf16 v[2:5], v[172:175], v[204:207], v[2:5]
	v_mfma_f32_16x16x32_bf16 v[10:13], v[160:163], v[200:203], v[10:13]
	v_mfma_f32_16x16x32_bf16 v[10:13], v[164:167], v[204:207], v[10:13]
	v_mfma_f32_16x16x32_bf16 v[6:9], v[152:155], v[200:203], v[6:9]
	v_mfma_f32_16x16x32_bf16 v[6:9], v[156:159], v[204:207], v[6:9]
	v_mfma_f32_16x16x32_bf16 v[14:17], v[144:147], v[200:203], v[14:17]
	v_mfma_f32_16x16x32_bf16 v[14:17], v[148:151], v[204:207], v[14:17]
	s_barrier
	ds_read_b128 v[144:147], v141
	ds_read_b128 v[148:151], v141 offset:1024
	ds_read_b128 v[152:155], v141 offset:2048
	ds_read_b128 v[156:159], v141 offset:3072
	ds_read_b128 v[160:163], v142
	ds_read_b128 v[164:167], v142 offset:1024
	ds_read_b128 v[168:171], v142 offset:2048
	ds_read_b128 v[172:175], v142 offset:3072
	s_mov_b32 m0, s50
	s_add_i32 s80, s77, 0x100000
	ds_read_b128 v[176:179], v140 offset:32768
	ds_read_b128 v[180:183], v140 offset:33792
	ds_read_b128 v[184:187], v140 offset:34816
	ds_read_b128 v[188:191], v140 offset:35840
	ds_read_b128 v[192:195], v140 offset:36864
	ds_read_b128 v[196:199], v140 offset:37888
	ds_read_b128 v[200:203], v140 offset:38912
	ds_read_b128 v[204:207], v140 offset:39936
	buffer_load_dwordx4 v136, s[16:19], s80 offen lds
	s_mov_b32 m0, s51
	s_add_i32 s80, s77, 0x180000
	buffer_load_dwordx4 v136, s[16:19], s80 offen lds
	s_waitcnt vmcnt(8) lgkmcnt(0)
	v_mfma_f32_16x16x32_bf16 v[118:121], v[144:147], v[176:179], v[118:121]
	s_barrier
	v_mfma_f32_16x16x32_bf16 v[118:121], v[148:151], v[180:183], v[118:121]
	v_mfma_f32_16x16x32_bf16 v[114:117], v[152:155], v[176:179], v[114:117]
	v_mfma_f32_16x16x32_bf16 v[114:117], v[156:159], v[180:183], v[114:117]
	v_mfma_f32_16x16x32_bf16 v[126:129], v[160:163], v[176:179], v[126:129]
	v_mfma_f32_16x16x32_bf16 v[126:129], v[164:167], v[180:183], v[126:129]
	v_mfma_f32_16x16x32_bf16 v[122:125], v[168:171], v[176:179], v[122:125]
	v_mfma_f32_16x16x32_bf16 v[122:125], v[172:175], v[180:183], v[122:125]
	v_mfma_f32_16x16x32_bf16 v[98:101], v[168:171], v[184:187], v[98:101]
	v_mfma_f32_16x16x32_bf16 v[98:101], v[172:175], v[188:191], v[98:101]
	v_mfma_f32_16x16x32_bf16 v[106:109], v[160:163], v[184:187], v[106:109]
	v_mfma_f32_16x16x32_bf16 v[106:109], v[164:167], v[188:191], v[106:109]
	v_mfma_f32_16x16x32_bf16 v[102:105], v[152:155], v[184:187], v[102:105]
	v_mfma_f32_16x16x32_bf16 v[102:105], v[156:159], v[188:191], v[102:105]
	v_mfma_f32_16x16x32_bf16 v[110:113], v[144:147], v[184:187], v[110:113]
	v_mfma_f32_16x16x32_bf16 v[110:113], v[148:151], v[188:191], v[110:113]
	v_mfma_f32_16x16x32_bf16 v[94:97], v[144:147], v[192:195], v[94:97]
	v_mfma_f32_16x16x32_bf16 v[94:97], v[148:151], v[196:199], v[94:97]
	v_mfma_f32_16x16x32_bf16 v[86:89], v[152:155], v[192:195], v[86:89]
	v_mfma_f32_16x16x32_bf16 v[86:89], v[156:159], v[196:199], v[86:89]
	v_mfma_f32_16x16x32_bf16 v[90:93], v[160:163], v[192:195], v[90:93]
	v_mfma_f32_16x16x32_bf16 v[90:93], v[164:167], v[196:199], v[90:93]
	v_mfma_f32_16x16x32_bf16 v[82:85], v[168:171], v[192:195], v[82:85]
	v_mfma_f32_16x16x32_bf16 v[82:85], v[172:175], v[196:199], v[82:85]
	v_mfma_f32_16x16x32_bf16 v[70:73], v[168:171], v[200:203], v[70:73]
	v_mfma_f32_16x16x32_bf16 v[70:73], v[172:175], v[204:207], v[70:73]
	v_mfma_f32_16x16x32_bf16 v[74:77], v[160:163], v[200:203], v[74:77]
	v_mfma_f32_16x16x32_bf16 v[74:77], v[164:167], v[204:207], v[74:77]
	v_mfma_f32_16x16x32_bf16 v[66:69], v[152:155], v[200:203], v[66:69]
	v_mfma_f32_16x16x32_bf16 v[66:69], v[156:159], v[204:207], v[66:69]
	v_mfma_f32_16x16x32_bf16 v[78:81], v[144:147], v[200:203], v[78:81]
	v_mfma_f32_16x16x32_bf16 v[78:81], v[148:151], v[204:207], v[78:81]
	s_barrier
	s_mov_b32 m0, s53
	s_or_b32 s80, s79, 0x80
	ds_read_b128 v[176:179], v140 offset:49152
	ds_read_b128 v[180:183], v140 offset:50176
	ds_read_b128 v[184:187], v140 offset:51200
	ds_read_b128 v[188:191], v140 offset:52224
	ds_read_b128 v[192:195], v140 offset:53248
	ds_read_b128 v[196:199], v140 offset:54272
	ds_read_b128 v[200:203], v140 offset:55296
	ds_read_b128 v[204:207], v140 offset:56320
	buffer_load_dwordx4 v137, s[12:15], s80 offen lds
	s_add_i32 s80, s79, 0x80080
	s_mov_b32 m0, s54
	s_add_i32 s77, s77, 0x80080
	buffer_load_dwordx4 v137, s[12:15], s80 offen lds
	s_add_i32 s80, s79, 0x100080
	s_mov_b32 m0, s57
	s_add_i32 s79, s79, 0x180080
	buffer_load_dwordx4 v137, s[12:15], s80 offen lds
	s_mov_b32 m0, s58
	s_nop 0
	buffer_load_dwordx4 v137, s[12:15], s79 offen lds
	s_mov_b32 m0, s55
	s_nop 0
	buffer_load_dwordx4 v136, s[16:19], s78 offen lds
	s_mov_b32 m0, s56
	s_nop 0
	buffer_load_dwordx4 v136, s[16:19], s77 offen lds
	s_waitcnt vmcnt(8) lgkmcnt(0)
	v_mfma_f32_16x16x32_bf16 v[62:65], v[144:147], v[176:179], v[62:65]
	s_barrier
	v_mfma_f32_16x16x32_bf16 v[62:65], v[148:151], v[180:183], v[62:65]
	v_mfma_f32_16x16x32_bf16 v[54:57], v[152:155], v[176:179], v[54:57]
	v_mfma_f32_16x16x32_bf16 v[54:57], v[156:159], v[180:183], v[54:57]
	v_mfma_f32_16x16x32_bf16 v[58:61], v[160:163], v[176:179], v[58:61]
	v_mfma_f32_16x16x32_bf16 v[58:61], v[164:167], v[180:183], v[58:61]
	v_mfma_f32_16x16x32_bf16 v[50:53], v[168:171], v[176:179], v[50:53]
	v_mfma_f32_16x16x32_bf16 v[50:53], v[172:175], v[180:183], v[50:53]
	v_mfma_f32_16x16x32_bf16 v[34:37], v[168:171], v[184:187], v[34:37]
	v_mfma_f32_16x16x32_bf16 v[34:37], v[172:175], v[188:191], v[34:37]
	v_mfma_f32_16x16x32_bf16 v[42:45], v[160:163], v[184:187], v[42:45]
	v_mfma_f32_16x16x32_bf16 v[42:45], v[164:167], v[188:191], v[42:45]
	v_mfma_f32_16x16x32_bf16 v[38:41], v[152:155], v[184:187], v[38:41]
	v_mfma_f32_16x16x32_bf16 v[38:41], v[156:159], v[188:191], v[38:41]
	v_mfma_f32_16x16x32_bf16 v[46:49], v[144:147], v[184:187], v[46:49]
	v_mfma_f32_16x16x32_bf16 v[46:49], v[148:151], v[188:191], v[46:49]
	v_mfma_f32_16x16x32_bf16 v[30:33], v[144:147], v[192:195], v[30:33]
	v_mfma_f32_16x16x32_bf16 v[30:33], v[148:151], v[196:199], v[30:33]
	v_mfma_f32_16x16x32_bf16 v[22:25], v[152:155], v[192:195], v[22:25]
	v_mfma_f32_16x16x32_bf16 v[22:25], v[156:159], v[196:199], v[22:25]
	v_mfma_f32_16x16x32_bf16 v[26:29], v[160:163], v[192:195], v[26:29]
	v_mfma_f32_16x16x32_bf16 v[26:29], v[164:167], v[196:199], v[26:29]
	v_mfma_f32_16x16x32_bf16 v[18:21], v[168:171], v[192:195], v[18:21]
	v_mfma_f32_16x16x32_bf16 v[18:21], v[172:175], v[196:199], v[18:21]
	v_mfma_f32_16x16x32_bf16 v[2:5], v[168:171], v[200:203], v[2:5]
	v_mfma_f32_16x16x32_bf16 v[2:5], v[172:175], v[204:207], v[2:5]
	v_mfma_f32_16x16x32_bf16 v[10:13], v[160:163], v[200:203], v[10:13]
	v_mfma_f32_16x16x32_bf16 v[10:13], v[164:167], v[204:207], v[10:13]
	v_mfma_f32_16x16x32_bf16 v[6:9], v[152:155], v[200:203], v[6:9]
	v_mfma_f32_16x16x32_bf16 v[6:9], v[156:159], v[204:207], v[6:9]
	v_mfma_f32_16x16x32_bf16 v[14:17], v[144:147], v[200:203], v[14:17]
	v_mfma_f32_16x16x32_bf16 v[14:17], v[148:151], v[204:207], v[14:17]
	s_barrier
	s_add_i32 s76, s76, 2
	s_addk_i32 s74, 0x100
	s_addk_i32 s75, 0x100
	s_cmp_ge_i32 s76, s27
	s_cbranch_scc0 .LBB0_1382
	s_and_b64 vcc, exec, s[42:43]
	s_cbranch_vccz .LBB0_1385

.LBB0_1402:
	ds_read_b128 v[146:149], v138
	ds_read_b128 v[150:153], v138 offset:1024
	ds_read_b128 v[154:157], v138 offset:2048
	ds_read_b128 v[158:161], v138 offset:3072
	ds_read_b128 v[162:165], v139
	ds_read_b128 v[166:169], v139 offset:1024
	ds_read_b128 v[170:173], v139 offset:2048
	ds_read_b128 v[174:177], v139 offset:3072
	s_add_i32 s22, s75, 0xffe80080
	s_cmp_eq_u32 s62, s77
	s_cselect_b32 s78, s73, s22
	s_cselect_b32 s80, s74, s76
	s_or_b32 s79, s78, 0x80
	s_add_i32 s22, s75, 0xfff80000
	s_mov_b32 m0, s63
	ds_read_b128 v[178:181], v140
	ds_read_b128 v[182:185], v140 offset:1024
	ds_read_b128 v[186:189], v140 offset:2048
	ds_read_b128 v[190:193], v140 offset:3072
	ds_read_b128 v[194:197], v140 offset:4096
	ds_read_b128 v[198:201], v140 offset:5120
	ds_read_b128 v[202:205], v140 offset:6144
	ds_read_b128 v[206:209], v140 offset:7168
	buffer_load_dwordx4 v136, s[16:19], s22 offen lds
	s_mov_b32 m0, s64
	s_nop 0
	buffer_load_dwordx4 v136, s[16:19], s75 offen lds
	s_waitcnt vmcnt(8) lgkmcnt(0)
	v_mfma_f32_16x16x32_bf16 v[118:121], v[146:149], v[178:181], v[118:121]
	s_barrier
	v_mfma_f32_16x16x32_bf16 v[118:121], v[150:153], v[182:185], v[118:121]
	v_mfma_f32_16x16x32_bf16 v[114:117], v[154:157], v[178:181], v[114:117]
	v_mfma_f32_16x16x32_bf16 v[114:117], v[158:161], v[182:185], v[114:117]
	v_mfma_f32_16x16x32_bf16 v[126:129], v[162:165], v[178:181], v[126:129]
	v_mfma_f32_16x16x32_bf16 v[126:129], v[166:169], v[182:185], v[126:129]
	v_mfma_f32_16x16x32_bf16 v[122:125], v[170:173], v[178:181], v[122:125]
	v_mfma_f32_16x16x32_bf16 v[122:125], v[174:177], v[182:185], v[122:125]
	v_mfma_f32_16x16x32_bf16 v[98:101], v[170:173], v[186:189], v[98:101]
	v_mfma_f32_16x16x32_bf16 v[98:101], v[174:177], v[190:193], v[98:101]
	v_mfma_f32_16x16x32_bf16 v[106:109], v[162:165], v[186:189], v[106:109]
	v_mfma_f32_16x16x32_bf16 v[106:109], v[166:169], v[190:193], v[106:109]
	v_mfma_f32_16x16x32_bf16 v[102:105], v[154:157], v[186:189], v[102:105]
	v_mfma_f32_16x16x32_bf16 v[102:105], v[158:161], v[190:193], v[102:105]
	v_mfma_f32_16x16x32_bf16 v[110:113], v[146:149], v[186:189], v[110:113]
	v_mfma_f32_16x16x32_bf16 v[110:113], v[150:153], v[190:193], v[110:113]
	v_mfma_f32_16x16x32_bf16 v[94:97], v[146:149], v[194:197], v[94:97]
	v_mfma_f32_16x16x32_bf16 v[94:97], v[150:153], v[198:201], v[94:97]
	v_mfma_f32_16x16x32_bf16 v[86:89], v[154:157], v[194:197], v[86:89]
	v_mfma_f32_16x16x32_bf16 v[86:89], v[158:161], v[198:201], v[86:89]
	v_mfma_f32_16x16x32_bf16 v[90:93], v[162:165], v[194:197], v[90:93]
	v_mfma_f32_16x16x32_bf16 v[90:93], v[166:169], v[198:201], v[90:93]
	v_mfma_f32_16x16x32_bf16 v[82:85], v[170:173], v[194:197], v[82:85]
	v_mfma_f32_16x16x32_bf16 v[82:85], v[174:177], v[198:201], v[82:85]
	v_mfma_f32_16x16x32_bf16 v[70:73], v[170:173], v[202:205], v[70:73]
	v_mfma_f32_16x16x32_bf16 v[70:73], v[174:177], v[206:209], v[70:73]
	v_mfma_f32_16x16x32_bf16 v[74:77], v[162:165], v[202:205], v[74:77]
	v_mfma_f32_16x16x32_bf16 v[74:77], v[166:169], v[206:209], v[74:77]
	v_mfma_f32_16x16x32_bf16 v[66:69], v[154:157], v[202:205], v[66:69]
	v_mfma_f32_16x16x32_bf16 v[66:69], v[158:161], v[206:209], v[66:69]
	v_mfma_f32_16x16x32_bf16 v[78:81], v[146:149], v[202:205], v[78:81]
	v_mfma_f32_16x16x32_bf16 v[78:81], v[150:153], v[206:209], v[78:81]
	s_barrier
	s_mov_b32 m0, s31
	s_mov_b32 s22, s18
	s_mov_b32 s23, s19
	ds_read_b128 v[178:181], v140 offset:16384
	ds_read_b128 v[182:185], v140 offset:17408
	ds_read_b128 v[186:189], v140 offset:18432
	ds_read_b128 v[190:193], v140 offset:19456
	ds_read_b128 v[194:197], v140 offset:20480
	ds_read_b128 v[198:201], v140 offset:21504
	ds_read_b128 v[202:205], v140 offset:22528
	ds_read_b128 v[206:209], v140 offset:23552
	buffer_load_dwordx4 v137, s[20:23], s80 offen lds
	s_mov_b32 m0, s48
	s_add_i32 s81, s80, 0x80000
	buffer_load_dwordx4 v137, s[20:23], s81 offen lds
	s_mov_b32 m0, s49
	s_add_i32 s81, s80, 0x100000
	buffer_load_dwordx4 v137, s[20:23], s81 offen lds
	s_mov_b32 m0, s50
	s_add_i32 s81, s80, 0x180000
	buffer_load_dwordx4 v137, s[20:23], s81 offen lds
	s_mov_b32 m0, s30
	s_add_i32 s81, s78, 0x80000
	buffer_load_dwordx4 v136, s[16:19], s78 offen lds
	s_mov_b32 m0, s51
	s_nop 0
	buffer_load_dwordx4 v136, s[16:19], s81 offen lds
	s_waitcnt vmcnt(8) lgkmcnt(0)
	v_mfma_f32_16x16x32_bf16 v[62:65], v[146:149], v[178:181], v[62:65]
	s_barrier
	v_mfma_f32_16x16x32_bf16 v[62:65], v[150:153], v[182:185], v[62:65]
	v_mfma_f32_16x16x32_bf16 v[54:57], v[154:157], v[178:181], v[54:57]
	v_mfma_f32_16x16x32_bf16 v[54:57], v[158:161], v[182:185], v[54:57]
	v_mfma_f32_16x16x32_bf16 v[58:61], v[162:165], v[178:181], v[58:61]
	v_mfma_f32_16x16x32_bf16 v[58:61], v[166:169], v[182:185], v[58:61]
	v_mfma_f32_16x16x32_bf16 v[50:53], v[170:173], v[178:181], v[50:53]
	v_mfma_f32_16x16x32_bf16 v[50:53], v[174:177], v[182:185], v[50:53]
	v_mfma_f32_16x16x32_bf16 v[34:37], v[170:173], v[186:189], v[34:37]
	v_mfma_f32_16x16x32_bf16 v[34:37], v[174:177], v[190:193], v[34:37]
	v_mfma_f32_16x16x32_bf16 v[42:45], v[162:165], v[186:189], v[42:45]
	v_mfma_f32_16x16x32_bf16 v[42:45], v[166:169], v[190:193], v[42:45]
	v_mfma_f32_16x16x32_bf16 v[38:41], v[154:157], v[186:189], v[38:41]
	v_mfma_f32_16x16x32_bf16 v[38:41], v[158:161], v[190:193], v[38:41]
	v_mfma_f32_16x16x32_bf16 v[46:49], v[146:149], v[186:189], v[46:49]
	v_mfma_f32_16x16x32_bf16 v[46:49], v[150:153], v[190:193], v[46:49]
	v_mfma_f32_16x16x32_bf16 v[30:33], v[146:149], v[194:197], v[30:33]
	v_mfma_f32_16x16x32_bf16 v[30:33], v[150:153], v[198:201], v[30:33]
	v_mfma_f32_16x16x32_bf16 v[22:25], v[154:157], v[194:197], v[22:25]
	v_mfma_f32_16x16x32_bf16 v[22:25], v[158:161], v[198:201], v[22:25]
	v_mfma_f32_16x16x32_bf16 v[26:29], v[162:165], v[194:197], v[26:29]
	v_mfma_f32_16x16x32_bf16 v[26:29], v[166:169], v[198:201], v[26:29]
	v_mfma_f32_16x16x32_bf16 v[18:21], v[170:173], v[194:197], v[18:21]
	v_mfma_f32_16x16x32_bf16 v[18:21], v[174:177], v[198:201], v[18:21]
	v_mfma_f32_16x16x32_bf16 v[2:5], v[170:173], v[202:205], v[2:5]
	v_mfma_f32_16x16x32_bf16 v[2:5], v[174:177], v[206:209], v[2:5]
	v_mfma_f32_16x16x32_bf16 v[10:13], v[162:165], v[202:205], v[10:13]
	v_mfma_f32_16x16x32_bf16 v[10:13], v[166:169], v[206:209], v[10:13]
	v_mfma_f32_16x16x32_bf16 v[6:9], v[154:157], v[202:205], v[6:9]
	v_mfma_f32_16x16x32_bf16 v[6:9], v[158:161], v[206:209], v[6:9]
	v_mfma_f32_16x16x32_bf16 v[14:17], v[146:149], v[202:205], v[14:17]
	v_mfma_f32_16x16x32_bf16 v[14:17], v[150:153], v[206:209], v[14:17]
	s_barrier
	ds_read_b128 v[146:149], v141
	ds_read_b128 v[150:153], v141 offset:1024
	ds_read_b128 v[154:157], v141 offset:2048
	ds_read_b128 v[158:161], v141 offset:3072
	ds_read_b128 v[162:165], v142
	ds_read_b128 v[166:169], v142 offset:1024
	ds_read_b128 v[170:173], v142 offset:2048
	ds_read_b128 v[174:177], v142 offset:3072
	s_mov_b32 m0, s52
	s_add_i32 s81, s78, 0x100000
	ds_read_b128 v[178:181], v140 offset:32768
	ds_read_b128 v[182:185], v140 offset:33792
	ds_read_b128 v[186:189], v140 offset:34816
	ds_read_b128 v[190:193], v140 offset:35840
	ds_read_b128 v[194:197], v140 offset:36864
	ds_read_b128 v[198:201], v140 offset:37888
	ds_read_b128 v[202:205], v140 offset:38912
	ds_read_b128 v[206:209], v140 offset:39936
	buffer_load_dwordx4 v136, s[16:19], s81 offen lds
	s_mov_b32 m0, s53
	s_add_i32 s81, s78, 0x180000
	buffer_load_dwordx4 v136, s[16:19], s81 offen lds
	s_waitcnt vmcnt(8) lgkmcnt(0)
	v_mfma_f32_16x16x32_bf16 v[118:121], v[146:149], v[178:181], v[118:121]
	s_barrier
	v_mfma_f32_16x16x32_bf16 v[118:121], v[150:153], v[182:185], v[118:121]
	v_mfma_f32_16x16x32_bf16 v[114:117], v[154:157], v[178:181], v[114:117]
	v_mfma_f32_16x16x32_bf16 v[114:117], v[158:161], v[182:185], v[114:117]
	v_mfma_f32_16x16x32_bf16 v[126:129], v[162:165], v[178:181], v[126:129]
	v_mfma_f32_16x16x32_bf16 v[126:129], v[166:169], v[182:185], v[126:129]
	v_mfma_f32_16x16x32_bf16 v[122:125], v[170:173], v[178:181], v[122:125]
	v_mfma_f32_16x16x32_bf16 v[122:125], v[174:177], v[182:185], v[122:125]
	v_mfma_f32_16x16x32_bf16 v[98:101], v[170:173], v[186:189], v[98:101]
	v_mfma_f32_16x16x32_bf16 v[98:101], v[174:177], v[190:193], v[98:101]
	v_mfma_f32_16x16x32_bf16 v[106:109], v[162:165], v[186:189], v[106:109]
	v_mfma_f32_16x16x32_bf16 v[106:109], v[166:169], v[190:193], v[106:109]
	v_mfma_f32_16x16x32_bf16 v[102:105], v[154:157], v[186:189], v[102:105]
	v_mfma_f32_16x16x32_bf16 v[102:105], v[158:161], v[190:193], v[102:105]
	v_mfma_f32_16x16x32_bf16 v[110:113], v[146:149], v[186:189], v[110:113]
	v_mfma_f32_16x16x32_bf16 v[110:113], v[150:153], v[190:193], v[110:113]
	v_mfma_f32_16x16x32_bf16 v[94:97], v[146:149], v[194:197], v[94:97]
	v_mfma_f32_16x16x32_bf16 v[94:97], v[150:153], v[198:201], v[94:97]
	v_mfma_f32_16x16x32_bf16 v[86:89], v[154:157], v[194:197], v[86:89]
	v_mfma_f32_16x16x32_bf16 v[86:89], v[158:161], v[198:201], v[86:89]
	v_mfma_f32_16x16x32_bf16 v[90:93], v[162:165], v[194:197], v[90:93]
	v_mfma_f32_16x16x32_bf16 v[90:93], v[166:169], v[198:201], v[90:93]
	v_mfma_f32_16x16x32_bf16 v[82:85], v[170:173], v[194:197], v[82:85]
	v_mfma_f32_16x16x32_bf16 v[82:85], v[174:177], v[198:201], v[82:85]
	v_mfma_f32_16x16x32_bf16 v[70:73], v[170:173], v[202:205], v[70:73]
	v_mfma_f32_16x16x32_bf16 v[70:73], v[174:177], v[206:209], v[70:73]
	v_mfma_f32_16x16x32_bf16 v[74:77], v[162:165], v[202:205], v[74:77]
	v_mfma_f32_16x16x32_bf16 v[74:77], v[166:169], v[206:209], v[74:77]
	v_mfma_f32_16x16x32_bf16 v[66:69], v[154:157], v[202:205], v[66:69]
	v_mfma_f32_16x16x32_bf16 v[66:69], v[158:161], v[206:209], v[66:69]
	v_mfma_f32_16x16x32_bf16 v[78:81], v[146:149], v[202:205], v[78:81]
	v_mfma_f32_16x16x32_bf16 v[78:81], v[150:153], v[206:209], v[78:81]
	s_barrier
	s_mov_b32 m0, s54
	s_or_b32 s81, s80, 0x80
	ds_read_b128 v[178:181], v140 offset:49152
	ds_read_b128 v[182:185], v140 offset:50176
	ds_read_b128 v[186:189], v140 offset:51200
	ds_read_b128 v[190:193], v140 offset:52224
	ds_read_b128 v[194:197], v140 offset:53248
	ds_read_b128 v[198:201], v140 offset:54272
	ds_read_b128 v[202:205], v140 offset:55296
	ds_read_b128 v[206:209], v140 offset:56320
	buffer_load_dwordx4 v137, s[20:23], s81 offen lds
	s_add_i32 s81, s80, 0x80080
	s_mov_b32 m0, s55
	s_add_i32 s78, s78, 0x80080
	buffer_load_dwordx4 v137, s[20:23], s81 offen lds
	s_add_i32 s81, s80, 0x100080
	s_mov_b32 m0, s58
	s_add_i32 s80, s80, 0x180080
	buffer_load_dwordx4 v137, s[20:23], s81 offen lds
	s_mov_b32 m0, s59
	s_nop 0
	buffer_load_dwordx4 v137, s[20:23], s80 offen lds
	s_mov_b32 m0, s56
	s_nop 0
	buffer_load_dwordx4 v136, s[16:19], s79 offen lds
	s_mov_b32 m0, s57
	s_nop 0
	buffer_load_dwordx4 v136, s[16:19], s78 offen lds
	s_waitcnt vmcnt(8) lgkmcnt(0)
	v_mfma_f32_16x16x32_bf16 v[62:65], v[146:149], v[178:181], v[62:65]
	s_barrier
	v_mfma_f32_16x16x32_bf16 v[62:65], v[150:153], v[182:185], v[62:65]
	v_mfma_f32_16x16x32_bf16 v[54:57], v[154:157], v[178:181], v[54:57]
	v_mfma_f32_16x16x32_bf16 v[54:57], v[158:161], v[182:185], v[54:57]
	v_mfma_f32_16x16x32_bf16 v[58:61], v[162:165], v[178:181], v[58:61]
	v_mfma_f32_16x16x32_bf16 v[58:61], v[166:169], v[182:185], v[58:61]
	v_mfma_f32_16x16x32_bf16 v[50:53], v[170:173], v[178:181], v[50:53]
	v_mfma_f32_16x16x32_bf16 v[50:53], v[174:177], v[182:185], v[50:53]
	v_mfma_f32_16x16x32_bf16 v[34:37], v[170:173], v[186:189], v[34:37]
	v_mfma_f32_16x16x32_bf16 v[34:37], v[174:177], v[190:193], v[34:37]
	v_mfma_f32_16x16x32_bf16 v[42:45], v[162:165], v[186:189], v[42:45]
	v_mfma_f32_16x16x32_bf16 v[42:45], v[166:169], v[190:193], v[42:45]
	v_mfma_f32_16x16x32_bf16 v[38:41], v[154:157], v[186:189], v[38:41]
	v_mfma_f32_16x16x32_bf16 v[38:41], v[158:161], v[190:193], v[38:41]
	v_mfma_f32_16x16x32_bf16 v[46:49], v[146:149], v[186:189], v[46:49]
	v_mfma_f32_16x16x32_bf16 v[46:49], v[150:153], v[190:193], v[46:49]
	v_mfma_f32_16x16x32_bf16 v[30:33], v[146:149], v[194:197], v[30:33]
	v_mfma_f32_16x16x32_bf16 v[30:33], v[150:153], v[198:201], v[30:33]
	v_mfma_f32_16x16x32_bf16 v[22:25], v[154:157], v[194:197], v[22:25]
	v_mfma_f32_16x16x32_bf16 v[22:25], v[158:161], v[198:201], v[22:25]
	v_mfma_f32_16x16x32_bf16 v[26:29], v[162:165], v[194:197], v[26:29]
	v_mfma_f32_16x16x32_bf16 v[26:29], v[166:169], v[198:201], v[26:29]
	v_mfma_f32_16x16x32_bf16 v[18:21], v[170:173], v[194:197], v[18:21]
	v_mfma_f32_16x16x32_bf16 v[18:21], v[174:177], v[198:201], v[18:21]
	v_mfma_f32_16x16x32_bf16 v[2:5], v[170:173], v[202:205], v[2:5]
	v_mfma_f32_16x16x32_bf16 v[2:5], v[174:177], v[206:209], v[2:5]
	v_mfma_f32_16x16x32_bf16 v[10:13], v[162:165], v[202:205], v[10:13]
	v_mfma_f32_16x16x32_bf16 v[10:13], v[166:169], v[206:209], v[10:13]
	v_mfma_f32_16x16x32_bf16 v[6:9], v[154:157], v[202:205], v[6:9]
	v_mfma_f32_16x16x32_bf16 v[6:9], v[158:161], v[206:209], v[6:9]
	v_mfma_f32_16x16x32_bf16 v[14:17], v[146:149], v[202:205], v[14:17]
	v_mfma_f32_16x16x32_bf16 v[14:17], v[150:153], v[206:209], v[14:17]
	s_barrier
	s_add_i32 s77, s77, 2
	s_addk_i32 s75, 0x100
	s_addk_i32 s76, 0x100
	s_cmp_ge_i32 s77, s13
	s_cbranch_scc0 .LBB0_1402
	s_and_b64 vcc, exec, s[46:47]
	s_cbranch_vccz .LBB0_1405

.LBB0_1420:
	ds_read_b128 v[146:149], v138
	ds_read_b128 v[150:153], v138 offset:1024
	ds_read_b128 v[154:157], v138 offset:2048
	ds_read_b128 v[158:161], v138 offset:3072
	ds_read_b128 v[162:165], v139
	ds_read_b128 v[166:169], v139 offset:1024
	ds_read_b128 v[170:173], v139 offset:2048
	ds_read_b128 v[174:177], v139 offset:3072
	s_add_i32 s14, s73, 0xfff40080
	s_cmp_eq_u32 s60, s75
	s_cselect_b32 s76, s71, s14
	s_cselect_b32 s78, s72, s74
	s_or_b32 s77, s76, 0x80
	s_add_i32 s14, s73, 0xfffc0000
	s_mov_b32 m0, s61
	ds_read_b128 v[178:181], v140
	ds_read_b128 v[182:185], v140 offset:1024
	ds_read_b128 v[186:189], v140 offset:2048
	ds_read_b128 v[190:193], v140 offset:3072
	ds_read_b128 v[194:197], v140 offset:4096
	ds_read_b128 v[198:201], v140 offset:5120
	ds_read_b128 v[202:205], v140 offset:6144
	ds_read_b128 v[206:209], v140 offset:7168
	buffer_load_dwordx4 v136, s[16:19], s14 offen lds
	s_mov_b32 m0, s62
	s_nop 0
	buffer_load_dwordx4 v136, s[16:19], s73 offen lds
	s_waitcnt vmcnt(8) lgkmcnt(0)
	s_barrier
	v_mfma_f32_16x16x128_f8f6f4 v[118:121], v[146:153], v[178:185], v[118:121]
	v_mfma_f32_16x16x128_f8f6f4 v[114:117], v[154:161], v[178:185], v[114:117]
	v_mfma_f32_16x16x128_f8f6f4 v[110:113], v[146:153], v[186:193], v[110:113]
	v_mfma_f32_16x16x128_f8f6f4 v[102:105], v[154:161], v[186:193], v[102:105]
	v_mfma_f32_16x16x128_f8f6f4 v[126:129], v[162:169], v[178:185], v[126:129]
	v_mfma_f32_16x16x128_f8f6f4 v[122:125], v[170:177], v[178:185], v[122:125]
	v_mfma_f32_16x16x128_f8f6f4 v[106:109], v[162:169], v[186:193], v[106:109]
	v_mfma_f32_16x16x128_f8f6f4 v[98:101], v[170:177], v[186:193], v[98:101]
	v_mfma_f32_16x16x128_f8f6f4 v[210:213], v[146:153], v[194:201], v[94:97]
	v_mfma_f32_16x16x128_f8f6f4 v[214:217], v[154:161], v[194:201], v[86:89]
	v_mfma_f32_16x16x128_f8f6f4 v[218:221], v[146:153], v[202:209], v[78:81]
	v_mfma_f32_16x16x128_f8f6f4 v[222:225], v[154:161], v[202:209], v[70:73]
	v_mfma_f32_16x16x128_f8f6f4 v[178:181], v[162:169], v[194:201], v[90:93]
	v_mfma_f32_16x16x128_f8f6f4 v[182:185], v[170:177], v[194:201], v[82:85]
	v_mfma_f32_16x16x128_f8f6f4 v[186:189], v[162:169], v[202:209], v[74:77]
	v_mfma_f32_16x16x128_f8f6f4 v[190:193], v[170:177], v[202:209], v[66:69]
	s_barrier
	s_mov_b32 m0, s31
	s_mov_b32 s14, s18
	s_mov_b32 s15, s19
	s_nop 1
	ds_read_b128 v[66:69], v140 offset:16384
	ds_read_b128 v[70:73], v140 offset:17408
	ds_read_b128 v[74:77], v140 offset:18432
	ds_read_b128 v[78:81], v140 offset:19456
	ds_read_b128 v[82:85], v140 offset:20480
	ds_read_b128 v[86:89], v140 offset:21504
	ds_read_b128 v[90:93], v140 offset:22528
	ds_read_b128 v[94:97], v140 offset:23552
	buffer_load_dwordx4 v137, s[12:15], s78 offen lds
	s_mov_b32 m0, s46
	s_add_i32 s79, s78, 0x40000
	buffer_load_dwordx4 v137, s[12:15], s79 offen lds
	s_mov_b32 m0, s47
	s_add_i32 s79, s78, 0x80000
	buffer_load_dwordx4 v137, s[12:15], s79 offen lds
	s_mov_b32 m0, s48
	s_add_i32 s79, s78, 0xc0000
	buffer_load_dwordx4 v137, s[12:15], s79 offen lds
	s_mov_b32 m0, s30
	s_add_i32 s79, s76, 0x40000
	buffer_load_dwordx4 v136, s[16:19], s76 offen lds
	s_mov_b32 m0, s49
	s_nop 0
	buffer_load_dwordx4 v136, s[16:19], s79 offen lds
	s_waitcnt vmcnt(8) lgkmcnt(0)
	s_barrier
	v_mfma_f32_16x16x128_f8f6f4 v[62:65], v[146:153], v[66:73], v[62:65]
	v_mfma_f32_16x16x128_f8f6f4 v[54:57], v[154:161], v[66:73], v[54:57]
	v_mfma_f32_16x16x128_f8f6f4 v[46:49], v[146:153], v[74:81], v[46:49]
	v_mfma_f32_16x16x128_f8f6f4 v[58:61], v[162:169], v[66:73], v[58:61]
	v_mfma_f32_16x16x128_f8f6f4 v[50:53], v[170:177], v[66:73], v[50:53]
	v_mfma_f32_16x16x128_f8f6f4 v[42:45], v[162:169], v[74:81], v[42:45]
	v_mfma_f32_16x16x128_f8f6f4 v[202:205], v[154:161], v[74:81], v[38:41]
	v_mfma_f32_16x16x128_f8f6f4 v[206:209], v[146:153], v[82:89], v[30:33]
	v_mfma_f32_16x16x128_f8f6f4 v[226:229], v[154:161], v[82:89], v[22:25]
	v_mfma_f32_16x16x128_f8f6f4 v[230:233], v[146:153], v[90:97], v[14:17]
	v_mfma_f32_16x16x128_f8f6f4 v[234:237], v[154:161], v[90:97], v[6:9]
	v_mfma_f32_16x16x128_f8f6f4 v[238:241], v[170:177], v[74:81], v[34:37]
	v_mfma_f32_16x16x128_f8f6f4 v[242:245], v[162:169], v[82:89], v[26:29]
	v_mfma_f32_16x16x128_f8f6f4 v[246:249], v[170:177], v[82:89], v[18:21]
	v_mfma_f32_16x16x128_f8f6f4 v[250:253], v[162:169], v[90:97], v[10:13]
	v_mfma_f32_16x16x128_f8f6f4 v[130:133], v[170:177], v[90:97], v[2:5]
	s_barrier
	s_nop 4
	ds_read_b128 v[2:5], v141
	ds_read_b128 v[6:9], v141 offset:1024
	ds_read_b128 v[146:149], v141 offset:2048
	ds_read_b128 v[150:153], v141 offset:3072
	ds_read_b128 v[154:157], v142
	ds_read_b128 v[158:161], v142 offset:1024
	ds_read_b128 v[162:165], v142 offset:2048
	ds_read_b128 v[166:169], v142 offset:3072
	s_mov_b32 m0, s50
	s_add_i32 s79, s76, 0x80000
	ds_read_b128 v[10:13], v140 offset:32768
	ds_read_b128 v[14:17], v140 offset:33792
	ds_read_b128 v[18:21], v140 offset:34816
	ds_read_b128 v[22:25], v140 offset:35840
	ds_read_b128 v[26:29], v140 offset:36864
	ds_read_b128 v[30:33], v140 offset:37888
	ds_read_b128 v[34:37], v140 offset:38912
	ds_read_b128 v[38:41], v140 offset:39936
	buffer_load_dwordx4 v136, s[16:19], s79 offen lds
	s_mov_b32 m0, s51
	s_add_i32 s79, s76, 0xc0000
	buffer_load_dwordx4 v136, s[16:19], s79 offen lds
	s_waitcnt vmcnt(8) lgkmcnt(0)
	s_barrier
	v_mfma_f32_16x16x128_f8f6f4 v[118:121], v[2:9], v[10:17], v[118:121]
	v_mfma_f32_16x16x128_f8f6f4 v[114:117], v[146:153], v[10:17], v[114:117]
	v_mfma_f32_16x16x128_f8f6f4 v[110:113], v[2:9], v[18:25], v[110:113]
	v_mfma_f32_16x16x128_f8f6f4 v[102:105], v[146:153], v[18:25], v[102:105]
	v_mfma_f32_16x16x128_f8f6f4 v[94:97], v[2:9], v[26:33], v[210:213]
	v_mfma_f32_16x16x128_f8f6f4 v[86:89], v[146:153], v[26:33], v[214:217]
	v_mfma_f32_16x16x128_f8f6f4 v[78:81], v[2:9], v[34:41], v[218:221]
	v_mfma_f32_16x16x128_f8f6f4 v[70:73], v[146:153], v[34:41], v[222:225]
	v_mfma_f32_16x16x128_f8f6f4 v[126:129], v[154:161], v[10:17], v[126:129]
	v_mfma_f32_16x16x128_f8f6f4 v[122:125], v[162:169], v[10:17], v[122:125]
	v_mfma_f32_16x16x128_f8f6f4 v[106:109], v[154:161], v[18:25], v[106:109]
	v_mfma_f32_16x16x128_f8f6f4 v[98:101], v[162:169], v[18:25], v[98:101]
	v_mfma_f32_16x16x128_f8f6f4 v[90:93], v[154:161], v[26:33], v[178:181]
	v_mfma_f32_16x16x128_f8f6f4 v[82:85], v[162:169], v[26:33], v[182:185]
	v_mfma_f32_16x16x128_f8f6f4 v[74:77], v[154:161], v[34:41], v[186:189]
	v_mfma_f32_16x16x128_f8f6f4 v[66:69], v[162:169], v[34:41], v[190:193]
	s_barrier
	s_mov_b32 m0, s54
	s_or_b32 s79, s78, 0x80
	ds_read_b128 v[170:173], v140 offset:49152
	ds_read_b128 v[174:177], v140 offset:50176
	ds_read_b128 v[178:181], v140 offset:51200
	ds_read_b128 v[182:185], v140 offset:52224
	ds_read_b128 v[186:189], v140 offset:53248
	ds_read_b128 v[190:193], v140 offset:54272
	ds_read_b128 v[194:197], v140 offset:55296
	ds_read_b128 v[198:201], v140 offset:56320
	buffer_load_dwordx4 v137, s[12:15], s79 offen lds
	s_add_i32 s79, s78, 0x40080
	s_mov_b32 m0, s55
	s_add_i32 s76, s76, 0x40080
	buffer_load_dwordx4 v137, s[12:15], s79 offen lds
	s_add_i32 s79, s78, 0x80080
	s_mov_b32 m0, s58
	s_add_i32 s78, s78, 0xc0080
	buffer_load_dwordx4 v137, s[12:15], s79 offen lds
	s_mov_b32 m0, s59
	s_nop 0
	buffer_load_dwordx4 v137, s[12:15], s78 offen lds
	s_mov_b32 m0, s56
	s_nop 0
	buffer_load_dwordx4 v136, s[16:19], s77 offen lds
	s_mov_b32 m0, s57
	s_nop 0
	buffer_load_dwordx4 v136, s[16:19], s76 offen lds
	s_waitcnt vmcnt(8) lgkmcnt(0)
	s_barrier
	v_mfma_f32_16x16x128_f8f6f4 v[62:65], v[2:9], v[170:177], v[62:65]
	v_mfma_f32_16x16x128_f8f6f4 v[54:57], v[146:153], v[170:177], v[54:57]
	v_mfma_f32_16x16x128_f8f6f4 v[46:49], v[2:9], v[178:185], v[46:49]
	v_mfma_f32_16x16x128_f8f6f4 v[38:41], v[146:153], v[178:185], v[202:205]
	v_mfma_f32_16x16x128_f8f6f4 v[30:33], v[2:9], v[186:193], v[206:209]
	v_mfma_f32_16x16x128_f8f6f4 v[22:25], v[146:153], v[186:193], v[226:229]
	v_mfma_f32_16x16x128_f8f6f4 v[14:17], v[2:9], v[194:201], v[230:233]
	v_mfma_f32_16x16x128_f8f6f4 v[6:9], v[146:153], v[194:201], v[234:237]
	v_mfma_f32_16x16x128_f8f6f4 v[58:61], v[154:161], v[170:177], v[58:61]
	v_mfma_f32_16x16x128_f8f6f4 v[50:53], v[162:169], v[170:177], v[50:53]
	v_mfma_f32_16x16x128_f8f6f4 v[42:45], v[154:161], v[178:185], v[42:45]
	v_mfma_f32_16x16x128_f8f6f4 v[34:37], v[162:169], v[178:185], v[238:241]
	v_mfma_f32_16x16x128_f8f6f4 v[26:29], v[154:161], v[186:193], v[242:245]
	v_mfma_f32_16x16x128_f8f6f4 v[18:21], v[162:169], v[186:193], v[246:249]
	v_mfma_f32_16x16x128_f8f6f4 v[10:13], v[154:161], v[194:201], v[250:253]
	v_mfma_f32_16x16x128_f8f6f4 v[2:5], v[162:169], v[194:201], v[130:133]
	s_barrier
	s_add_i32 s75, s75, 2
	s_addk_i32 s73, 0x100
	s_addk_i32 s74, 0x100
	s_cmp_ge_i32 s75, s25
	s_cbranch_scc0 .LBB0_1420
	s_and_b64 vcc, exec, s[44:45]
	s_cbranch_vccz .LBB0_1423

.LBB0_1519:
	ds_read_b128 v[134:137], v208
	ds_read_b128 v[138:141], v208 offset:1024
	ds_read_b128 v[142:145], v208 offset:2048
	ds_read_b128 v[146:149], v208 offset:3072
	ds_read_b128 v[150:153], v209
	ds_read_b128 v[154:157], v209 offset:1024
	ds_read_b128 v[158:161], v209 offset:2048
	ds_read_b128 v[162:165], v209 offset:3072
	s_add_i32 s18, s80, 0xffbf8080
	s_cmp_eq_u32 s65, s82
	s_cselect_b32 s83, s6, s18
	s_cselect_b32 s85, s7, s81
	s_or_b32 s84, s83, 0x80
	s_add_i32 s18, s80, 0xffea8000
	s_mov_b32 m0, s66
	ds_read_b128 v[166:169], v210
	ds_read_b128 v[170:173], v210 offset:1024
	ds_read_b128 v[174:177], v210 offset:2048
	ds_read_b128 v[178:181], v210 offset:3072
	ds_read_b128 v[182:185], v210 offset:4096
	ds_read_b128 v[186:189], v210 offset:5120
	ds_read_b128 v[190:193], v210 offset:6144
	ds_read_b128 v[194:197], v210 offset:7168
	buffer_load_dwordx4 v206, s[12:15], s18 offen lds
	s_mov_b32 m0, s69
	s_nop 0
	buffer_load_dwordx4 v206, s[12:15], s80 offen lds
	s_waitcnt vmcnt(8) lgkmcnt(0)
	v_mfma_f32_16x16x32_bf16 v[126:129], v[134:137], v[166:169], v[126:129]
	s_barrier
	v_mfma_f32_16x16x32_bf16 v[126:129], v[138:141], v[170:173], v[126:129]
	v_mfma_f32_16x16x32_bf16 v[122:125], v[142:145], v[166:169], v[122:125]
	v_mfma_f32_16x16x32_bf16 v[122:125], v[146:149], v[170:173], v[122:125]
	v_mfma_f32_16x16x32_bf16 v[110:113], v[150:153], v[166:169], v[110:113]
	v_mfma_f32_16x16x32_bf16 v[110:113], v[154:157], v[170:173], v[110:113]
	v_mfma_f32_16x16x32_bf16 v[102:105], v[158:161], v[166:169], v[102:105]
	v_mfma_f32_16x16x32_bf16 v[102:105], v[162:165], v[170:173], v[102:105]
	v_mfma_f32_16x16x32_bf16 v[86:89], v[158:161], v[174:177], v[86:89]
	v_mfma_f32_16x16x32_bf16 v[86:89], v[162:165], v[178:181], v[86:89]
	v_mfma_f32_16x16x32_bf16 v[94:97], v[150:153], v[174:177], v[94:97]
	v_mfma_f32_16x16x32_bf16 v[94:97], v[154:157], v[178:181], v[94:97]
	v_mfma_f32_16x16x32_bf16 v[114:117], v[142:145], v[174:177], v[114:117]
	v_mfma_f32_16x16x32_bf16 v[114:117], v[146:149], v[178:181], v[114:117]
	v_mfma_f32_16x16x32_bf16 v[118:121], v[134:137], v[174:177], v[118:121]
	v_mfma_f32_16x16x32_bf16 v[118:121], v[138:141], v[178:181], v[118:121]
	v_mfma_f32_16x16x32_bf16 v[106:109], v[134:137], v[182:185], v[106:109]
	v_mfma_f32_16x16x32_bf16 v[106:109], v[138:141], v[186:189], v[106:109]
	v_mfma_f32_16x16x32_bf16 v[98:101], v[142:145], v[182:185], v[98:101]
	v_mfma_f32_16x16x32_bf16 v[98:101], v[146:149], v[186:189], v[98:101]
	v_mfma_f32_16x16x32_bf16 v[78:81], v[150:153], v[182:185], v[78:81]
	v_mfma_f32_16x16x32_bf16 v[78:81], v[154:157], v[186:189], v[78:81]
	v_mfma_f32_16x16x32_bf16 v[74:77], v[158:161], v[182:185], v[74:77]
	v_mfma_f32_16x16x32_bf16 v[74:77], v[162:165], v[186:189], v[74:77]
	v_mfma_f32_16x16x32_bf16 v[66:69], v[158:161], v[190:193], v[66:69]
	v_mfma_f32_16x16x32_bf16 v[66:69], v[162:165], v[194:197], v[66:69]
	v_mfma_f32_16x16x32_bf16 v[70:73], v[150:153], v[190:193], v[70:73]
	v_mfma_f32_16x16x32_bf16 v[70:73], v[154:157], v[194:197], v[70:73]
	v_mfma_f32_16x16x32_bf16 v[82:85], v[142:145], v[190:193], v[82:85]
	v_mfma_f32_16x16x32_bf16 v[82:85], v[146:149], v[194:197], v[82:85]
	v_mfma_f32_16x16x32_bf16 v[90:93], v[134:137], v[190:193], v[90:93]
	v_mfma_f32_16x16x32_bf16 v[90:93], v[138:141], v[194:197], v[90:93]
	s_barrier
	s_mov_b32 m0, s27
	s_mov_b32 s18, s14
	s_mov_b32 s19, s15
	ds_read_b128 v[166:169], v210 offset:16384
	ds_read_b128 v[170:173], v210 offset:17408
	ds_read_b128 v[174:177], v210 offset:18432
	ds_read_b128 v[178:181], v210 offset:19456
	ds_read_b128 v[182:185], v210 offset:20480
	ds_read_b128 v[186:189], v210 offset:21504
	ds_read_b128 v[190:193], v210 offset:22528
	ds_read_b128 v[194:197], v210 offset:23552
	buffer_load_dwordx4 v207, s[16:19], s85 offen lds
	s_mov_b32 m0, s30
	s_add_i32 s86, s85, 0x158000
	buffer_load_dwordx4 v207, s[16:19], s86 offen lds
	s_mov_b32 m0, s31
	s_add_i32 s86, s85, 0x2b0000
	buffer_load_dwordx4 v207, s[16:19], s86 offen lds
	s_mov_b32 m0, s50
	s_add_i32 s86, s85, 0x408000
	buffer_load_dwordx4 v207, s[16:19], s86 offen lds
	s_mov_b32 m0, s25
	s_add_i32 s86, s83, 0x158000
	buffer_load_dwordx4 v206, s[12:15], s83 offen lds
	s_mov_b32 m0, s51
	s_nop 0
	buffer_load_dwordx4 v206, s[12:15], s86 offen lds
	s_waitcnt vmcnt(8) lgkmcnt(0)
	v_mfma_f32_16x16x32_bf16 v[62:65], v[134:137], v[166:169], v[62:65]
	s_barrier
	v_mfma_f32_16x16x32_bf16 v[62:65], v[138:141], v[170:173], v[62:65]
	v_mfma_f32_16x16x32_bf16 v[58:61], v[142:145], v[166:169], v[58:61]
	v_mfma_f32_16x16x32_bf16 v[58:61], v[146:149], v[170:173], v[58:61]
	v_mfma_f32_16x16x32_bf16 v[46:49], v[150:153], v[166:169], v[46:49]
	v_mfma_f32_16x16x32_bf16 v[46:49], v[154:157], v[170:173], v[46:49]
	v_mfma_f32_16x16x32_bf16 v[38:41], v[158:161], v[166:169], v[38:41]
	v_mfma_f32_16x16x32_bf16 v[38:41], v[162:165], v[170:173], v[38:41]
	v_mfma_f32_16x16x32_bf16 v[22:25], v[158:161], v[174:177], v[22:25]
	v_mfma_f32_16x16x32_bf16 v[22:25], v[162:165], v[178:181], v[22:25]
	v_mfma_f32_16x16x32_bf16 v[30:33], v[150:153], v[174:177], v[30:33]
	v_mfma_f32_16x16x32_bf16 v[30:33], v[154:157], v[178:181], v[30:33]
	v_mfma_f32_16x16x32_bf16 v[50:53], v[142:145], v[174:177], v[50:53]
	v_mfma_f32_16x16x32_bf16 v[50:53], v[146:149], v[178:181], v[50:53]
	v_mfma_f32_16x16x32_bf16 v[54:57], v[134:137], v[174:177], v[54:57]
	v_mfma_f32_16x16x32_bf16 v[54:57], v[138:141], v[178:181], v[54:57]
	v_mfma_f32_16x16x32_bf16 v[42:45], v[134:137], v[182:185], v[42:45]
	v_mfma_f32_16x16x32_bf16 v[42:45], v[138:141], v[186:189], v[42:45]
	v_mfma_f32_16x16x32_bf16 v[34:37], v[142:145], v[182:185], v[34:37]
	v_mfma_f32_16x16x32_bf16 v[34:37], v[146:149], v[186:189], v[34:37]
	v_mfma_f32_16x16x32_bf16 v[14:17], v[150:153], v[182:185], v[14:17]
	v_mfma_f32_16x16x32_bf16 v[14:17], v[154:157], v[186:189], v[14:17]
	v_mfma_f32_16x16x32_bf16 v[10:13], v[158:161], v[182:185], v[10:13]
	v_mfma_f32_16x16x32_bf16 v[10:13], v[162:165], v[186:189], v[10:13]
	v_mfma_f32_16x16x32_bf16 v[2:5], v[158:161], v[190:193], v[2:5]
	v_mfma_f32_16x16x32_bf16 v[2:5], v[162:165], v[194:197], v[2:5]
	v_mfma_f32_16x16x32_bf16 v[6:9], v[150:153], v[190:193], v[6:9]
	v_mfma_f32_16x16x32_bf16 v[6:9], v[154:157], v[194:197], v[6:9]
	v_mfma_f32_16x16x32_bf16 v[18:21], v[142:145], v[190:193], v[18:21]
	v_mfma_f32_16x16x32_bf16 v[18:21], v[146:149], v[194:197], v[18:21]
	v_mfma_f32_16x16x32_bf16 v[26:29], v[134:137], v[190:193], v[26:29]
	v_mfma_f32_16x16x32_bf16 v[26:29], v[138:141], v[194:197], v[26:29]
	s_barrier
	ds_read_b128 v[134:137], v211
	ds_read_b128 v[138:141], v211 offset:1024
	ds_read_b128 v[142:145], v211 offset:2048
	ds_read_b128 v[146:149], v211 offset:3072
	ds_read_b128 v[150:153], v212
	ds_read_b128 v[154:157], v212 offset:1024
	ds_read_b128 v[158:161], v212 offset:2048
	ds_read_b128 v[162:165], v212 offset:3072
	s_mov_b32 m0, s52
	s_add_i32 s86, s83, 0x2b0000
	ds_read_b128 v[166:169], v210 offset:32768
	ds_read_b128 v[170:173], v210 offset:33792
	ds_read_b128 v[174:177], v210 offset:34816
	ds_read_b128 v[178:181], v210 offset:35840
	ds_read_b128 v[182:185], v210 offset:36864
	ds_read_b128 v[186:189], v210 offset:37888
	ds_read_b128 v[190:193], v210 offset:38912
	ds_read_b128 v[194:197], v210 offset:39936
	buffer_load_dwordx4 v206, s[12:15], s86 offen lds
	s_mov_b32 m0, s53
	s_add_i32 s86, s83, 0x408000
	buffer_load_dwordx4 v206, s[12:15], s86 offen lds
	s_waitcnt vmcnt(8) lgkmcnt(0)
	v_mfma_f32_16x16x32_bf16 v[126:129], v[134:137], v[166:169], v[126:129]
	s_barrier
	v_mfma_f32_16x16x32_bf16 v[126:129], v[138:141], v[170:173], v[126:129]
	v_mfma_f32_16x16x32_bf16 v[122:125], v[142:145], v[166:169], v[122:125]
	v_mfma_f32_16x16x32_bf16 v[122:125], v[146:149], v[170:173], v[122:125]
	v_mfma_f32_16x16x32_bf16 v[110:113], v[150:153], v[166:169], v[110:113]
	v_mfma_f32_16x16x32_bf16 v[110:113], v[154:157], v[170:173], v[110:113]
	v_mfma_f32_16x16x32_bf16 v[102:105], v[158:161], v[166:169], v[102:105]
	v_mfma_f32_16x16x32_bf16 v[102:105], v[162:165], v[170:173], v[102:105]
	v_mfma_f32_16x16x32_bf16 v[86:89], v[158:161], v[174:177], v[86:89]
	v_mfma_f32_16x16x32_bf16 v[86:89], v[162:165], v[178:181], v[86:89]
	v_mfma_f32_16x16x32_bf16 v[94:97], v[150:153], v[174:177], v[94:97]
	v_mfma_f32_16x16x32_bf16 v[94:97], v[154:157], v[178:181], v[94:97]
	v_mfma_f32_16x16x32_bf16 v[114:117], v[142:145], v[174:177], v[114:117]
	v_mfma_f32_16x16x32_bf16 v[114:117], v[146:149], v[178:181], v[114:117]
	v_mfma_f32_16x16x32_bf16 v[118:121], v[134:137], v[174:177], v[118:121]
	v_mfma_f32_16x16x32_bf16 v[118:121], v[138:141], v[178:181], v[118:121]
	v_mfma_f32_16x16x32_bf16 v[106:109], v[134:137], v[182:185], v[106:109]
	v_mfma_f32_16x16x32_bf16 v[106:109], v[138:141], v[186:189], v[106:109]
	v_mfma_f32_16x16x32_bf16 v[98:101], v[142:145], v[182:185], v[98:101]
	v_mfma_f32_16x16x32_bf16 v[98:101], v[146:149], v[186:189], v[98:101]
	v_mfma_f32_16x16x32_bf16 v[78:81], v[150:153], v[182:185], v[78:81]
	v_mfma_f32_16x16x32_bf16 v[78:81], v[154:157], v[186:189], v[78:81]
	v_mfma_f32_16x16x32_bf16 v[74:77], v[158:161], v[182:185], v[74:77]
	v_mfma_f32_16x16x32_bf16 v[74:77], v[162:165], v[186:189], v[74:77]
	v_mfma_f32_16x16x32_bf16 v[66:69], v[158:161], v[190:193], v[66:69]
	v_mfma_f32_16x16x32_bf16 v[66:69], v[162:165], v[194:197], v[66:69]
	v_mfma_f32_16x16x32_bf16 v[70:73], v[150:153], v[190:193], v[70:73]
	v_mfma_f32_16x16x32_bf16 v[70:73], v[154:157], v[194:197], v[70:73]
	v_mfma_f32_16x16x32_bf16 v[82:85], v[142:145], v[190:193], v[82:85]
	v_mfma_f32_16x16x32_bf16 v[82:85], v[146:149], v[194:197], v[82:85]
	v_mfma_f32_16x16x32_bf16 v[90:93], v[134:137], v[190:193], v[90:93]
	v_mfma_f32_16x16x32_bf16 v[90:93], v[138:141], v[194:197], v[90:93]
	s_barrier
	s_mov_b32 m0, s57
	s_or_b32 s86, s85, 0x80
	ds_read_b128 v[166:169], v210 offset:49152
	ds_read_b128 v[170:173], v210 offset:50176
	ds_read_b128 v[174:177], v210 offset:51200
	ds_read_b128 v[178:181], v210 offset:52224
	ds_read_b128 v[182:185], v210 offset:53248
	ds_read_b128 v[186:189], v210 offset:54272
	ds_read_b128 v[190:193], v210 offset:55296
	ds_read_b128 v[194:197], v210 offset:56320
	buffer_load_dwordx4 v207, s[16:19], s86 offen lds
	s_add_i32 s86, s85, 0x158080
	s_mov_b32 m0, s58
	s_add_i32 s83, s83, 0x158080
	buffer_load_dwordx4 v207, s[16:19], s86 offen lds
	s_add_i32 s86, s85, 0x2b0080
	s_mov_b32 m0, s61
	s_add_i32 s85, s85, 0x408080
	buffer_load_dwordx4 v207, s[16:19], s86 offen lds
	s_mov_b32 m0, s62
	s_nop 0
	buffer_load_dwordx4 v207, s[16:19], s85 offen lds
	s_mov_b32 m0, s59
	s_nop 0
	buffer_load_dwordx4 v206, s[12:15], s84 offen lds
	s_mov_b32 m0, s60
	s_nop 0
	buffer_load_dwordx4 v206, s[12:15], s83 offen lds
	s_waitcnt vmcnt(8) lgkmcnt(0)
	v_mfma_f32_16x16x32_bf16 v[62:65], v[134:137], v[166:169], v[62:65]
	s_barrier
	v_mfma_f32_16x16x32_bf16 v[62:65], v[138:141], v[170:173], v[62:65]
	v_mfma_f32_16x16x32_bf16 v[58:61], v[142:145], v[166:169], v[58:61]
	v_mfma_f32_16x16x32_bf16 v[58:61], v[146:149], v[170:173], v[58:61]
	v_mfma_f32_16x16x32_bf16 v[46:49], v[150:153], v[166:169], v[46:49]
	v_mfma_f32_16x16x32_bf16 v[46:49], v[154:157], v[170:173], v[46:49]
	v_mfma_f32_16x16x32_bf16 v[38:41], v[158:161], v[166:169], v[38:41]
	v_mfma_f32_16x16x32_bf16 v[38:41], v[162:165], v[170:173], v[38:41]
	v_mfma_f32_16x16x32_bf16 v[22:25], v[158:161], v[174:177], v[22:25]
	v_mfma_f32_16x16x32_bf16 v[22:25], v[162:165], v[178:181], v[22:25]
	v_mfma_f32_16x16x32_bf16 v[30:33], v[150:153], v[174:177], v[30:33]
	v_mfma_f32_16x16x32_bf16 v[30:33], v[154:157], v[178:181], v[30:33]
	v_mfma_f32_16x16x32_bf16 v[50:53], v[142:145], v[174:177], v[50:53]
	v_mfma_f32_16x16x32_bf16 v[50:53], v[146:149], v[178:181], v[50:53]
	v_mfma_f32_16x16x32_bf16 v[54:57], v[134:137], v[174:177], v[54:57]
	v_mfma_f32_16x16x32_bf16 v[54:57], v[138:141], v[178:181], v[54:57]
	v_mfma_f32_16x16x32_bf16 v[42:45], v[134:137], v[182:185], v[42:45]
	v_mfma_f32_16x16x32_bf16 v[42:45], v[138:141], v[186:189], v[42:45]
	v_mfma_f32_16x16x32_bf16 v[34:37], v[142:145], v[182:185], v[34:37]
	v_mfma_f32_16x16x32_bf16 v[34:37], v[146:149], v[186:189], v[34:37]
	v_mfma_f32_16x16x32_bf16 v[14:17], v[150:153], v[182:185], v[14:17]
	v_mfma_f32_16x16x32_bf16 v[14:17], v[154:157], v[186:189], v[14:17]
	v_mfma_f32_16x16x32_bf16 v[10:13], v[158:161], v[182:185], v[10:13]
	v_mfma_f32_16x16x32_bf16 v[10:13], v[162:165], v[186:189], v[10:13]
	v_mfma_f32_16x16x32_bf16 v[2:5], v[158:161], v[190:193], v[2:5]
	v_mfma_f32_16x16x32_bf16 v[2:5], v[162:165], v[194:197], v[2:5]
	v_mfma_f32_16x16x32_bf16 v[6:9], v[150:153], v[190:193], v[6:9]
	v_mfma_f32_16x16x32_bf16 v[6:9], v[154:157], v[194:197], v[6:9]
	v_mfma_f32_16x16x32_bf16 v[18:21], v[142:145], v[190:193], v[18:21]
	v_mfma_f32_16x16x32_bf16 v[18:21], v[146:149], v[194:197], v[18:21]
	v_mfma_f32_16x16x32_bf16 v[26:29], v[134:137], v[190:193], v[26:29]
	v_mfma_f32_16x16x32_bf16 v[26:29], v[138:141], v[194:197], v[26:29]
	s_barrier
	s_add_i32 s82, s82, 2
	s_addk_i32 s80, 0x100
	s_addk_i32 s81, 0x100
	s_cmp_ge_i32 s82, s3
	s_cbranch_scc0 .LBB0_1519
	v_pk_mul_f32 v[182:183], v[128:129], 0.5 op_sel_hi:[1,0]
	v_pk_mul_f32 v[184:185], v[126:127], 0.5 op_sel_hi:[1,0]
	v_pk_mul_f32 v[186:187], v[124:125], 0.5 op_sel_hi:[1,0]
	v_pk_mul_f32 v[188:189], v[122:123], 0.5 op_sel_hi:[1,0]
	v_pk_mul_f32 v[196:197], v[112:113], 0.5 op_sel_hi:[1,0]
	v_pk_mul_f32 v[194:195], v[110:111], 0.5 op_sel_hi:[1,0]
	v_pk_mul_f32 v[192:193], v[104:105], 0.5 op_sel_hi:[1,0]
	v_pk_mul_f32 v[190:191], v[102:103], 0.5 op_sel_hi:[1,0]
	v_pk_mul_f32 v[180:181], v[120:121], 0.5 op_sel_hi:[1,0]
	v_pk_mul_f32 v[178:179], v[118:119], 0.5 op_sel_hi:[1,0]
	v_pk_mul_f32 v[176:177], v[116:117], 0.5 op_sel_hi:[1,0]
	v_pk_mul_f32 v[174:175], v[114:115], 0.5 op_sel_hi:[1,0]
	v_pk_mul_f32 v[170:171], v[96:97], 0.5 op_sel_hi:[1,0]
	v_pk_mul_f32 v[168:169], v[94:95], 0.5 op_sel_hi:[1,0]
	v_pk_mul_f32 v[166:167], v[88:89], 0.5 op_sel_hi:[1,0]
	v_pk_mul_f32 v[164:165], v[86:87], 0.5 op_sel_hi:[1,0]
	v_pk_mul_f32 v[162:163], v[108:109], 0.5 op_sel_hi:[1,0]
	v_pk_mul_f32 v[160:161], v[106:107], 0.5 op_sel_hi:[1,0]
	v_pk_mul_f32 v[158:159], v[100:101], 0.5 op_sel_hi:[1,0]
	v_pk_mul_f32 v[156:157], v[98:99], 0.5 op_sel_hi:[1,0]
	v_pk_mul_f32 v[154:155], v[80:81], 0.5 op_sel_hi:[1,0]
	v_pk_mul_f32 v[152:153], v[78:79], 0.5 op_sel_hi:[1,0]
	v_pk_mul_f32 v[150:151], v[76:77], 0.5 op_sel_hi:[1,0]
	v_pk_mul_f32 v[148:149], v[74:75], 0.5 op_sel_hi:[1,0]
	v_pk_mul_f32 v[144:145], v[92:93], 0.5 op_sel_hi:[1,0]
	v_pk_mul_f32 v[142:143], v[90:91], 0.5 op_sel_hi:[1,0]
	v_pk_mul_f32 v[140:141], v[84:85], 0.5 op_sel_hi:[1,0]
	v_pk_mul_f32 v[138:139], v[82:83], 0.5 op_sel_hi:[1,0]
	v_pk_mul_f32 v[136:137], v[72:73], 0.5 op_sel_hi:[1,0]
	v_pk_mul_f32 v[134:135], v[70:71], 0.5 op_sel_hi:[1,0]
	v_pk_mul_f32 v[128:129], v[68:69], 0.5 op_sel_hi:[1,0]
	v_pk_mul_f32 v[126:127], v[66:67], 0.5 op_sel_hi:[1,0]
	v_pk_mul_f32 v[122:123], v[64:65], 0.5 op_sel_hi:[1,0]
	v_pk_mul_f32 v[120:121], v[62:63], 0.5 op_sel_hi:[1,0]
	v_pk_mul_f32 v[118:119], v[60:61], 0.5 op_sel_hi:[1,0]
	v_pk_mul_f32 v[116:117], v[58:59], 0.5 op_sel_hi:[1,0]
	v_pk_mul_f32 v[112:113], v[48:49], 0.5 op_sel_hi:[1,0]
	v_pk_mul_f32 v[110:111], v[46:47], 0.5 op_sel_hi:[1,0]
	v_pk_mul_f32 v[108:109], v[40:41], 0.5 op_sel_hi:[1,0]
	v_pk_mul_f32 v[106:107], v[38:39], 0.5 op_sel_hi:[1,0]
	v_pk_mul_f32 v[104:105], v[56:57], 0.5 op_sel_hi:[1,0]
	v_pk_mul_f32 v[102:103], v[54:55], 0.5 op_sel_hi:[1,0]
	v_pk_mul_f32 v[100:101], v[52:53], 0.5 op_sel_hi:[1,0]
	v_pk_mul_f32 v[98:99], v[50:51], 0.5 op_sel_hi:[1,0]
	v_pk_mul_f32 v[96:97], v[32:33], 0.5 op_sel_hi:[1,0]
	v_pk_mul_f32 v[94:95], v[30:31], 0.5 op_sel_hi:[1,0]
	v_pk_mul_f32 v[92:93], v[24:25], 0.5 op_sel_hi:[1,0]
	v_pk_mul_f32 v[90:91], v[22:23], 0.5 op_sel_hi:[1,0]
	v_pk_mul_f32 v[88:89], v[44:45], 0.5 op_sel_hi:[1,0]
	v_pk_mul_f32 v[86:87], v[42:43], 0.5 op_sel_hi:[1,0]
	v_pk_mul_f32 v[84:85], v[36:37], 0.5 op_sel_hi:[1,0]
	v_pk_mul_f32 v[82:83], v[34:35], 0.5 op_sel_hi:[1,0]
	v_pk_mul_f32 v[80:81], v[16:17], 0.5 op_sel_hi:[1,0]
	v_pk_mul_f32 v[78:79], v[14:15], 0.5 op_sel_hi:[1,0]
	v_pk_mul_f32 v[76:77], v[12:13], 0.5 op_sel_hi:[1,0]
	v_pk_mul_f32 v[74:75], v[10:11], 0.5 op_sel_hi:[1,0]
	v_pk_mul_f32 v[72:73], v[28:29], 0.5 op_sel_hi:[1,0]
	v_pk_mul_f32 v[70:71], v[26:27], 0.5 op_sel_hi:[1,0]
	v_pk_mul_f32 v[68:69], v[20:21], 0.5 op_sel_hi:[1,0]
	v_pk_mul_f32 v[66:67], v[18:19], 0.5 op_sel_hi:[1,0]
	v_pk_mul_f32 v[64:65], v[8:9], 0.5 op_sel_hi:[1,0]
	v_pk_mul_f32 v[62:63], v[6:7], 0.5 op_sel_hi:[1,0]
	v_pk_mul_f32 v[60:61], v[4:5], 0.5 op_sel_hi:[1,0]
	v_pk_mul_f32 v[58:59], v[2:3], 0.5 op_sel_hi:[1,0]
	s_and_b64 vcc, exec, s[40:41]
	s_cbranch_vccz .LBB0_1522

.LBB0_1567:
	ds_read_b128 v[134:137], v225
	ds_read_b128 v[138:141], v225 offset:1024
	ds_read_b128 v[142:145], v225 offset:2048
	ds_read_b128 v[146:149], v225 offset:3072
	ds_read_b128 v[150:153], v226
	ds_read_b128 v[154:157], v226 offset:1024
	ds_read_b128 v[158:161], v226 offset:2048
	ds_read_b128 v[162:165], v226 offset:3072
	s_add_i32 s18, s8, 0xffdfc080
	s_cmp_eq_u32 s71, s55
	s_cselect_b32 s56, s6, s18
	s_cselect_b32 s91, s7, s9
	s_or_b32 s57, s56, 0x80
	s_add_i32 s18, s8, 0xfff54000
	s_mov_b32 m0, s72
	ds_read_b128 v[166:169], v227
	ds_read_b128 v[170:173], v227 offset:1024
	ds_read_b128 v[174:177], v227 offset:2048
	ds_read_b128 v[178:181], v227 offset:3072
	ds_read_b128 v[182:185], v227 offset:4096
	ds_read_b128 v[186:189], v227 offset:5120
	ds_read_b128 v[190:193], v227 offset:6144
	ds_read_b128 v[194:197], v227 offset:7168
	buffer_load_dwordx4 v223, s[12:15], s18 offen lds
	s_mov_b32 m0, s75
	s_nop 0
	buffer_load_dwordx4 v223, s[12:15], s8 offen lds
	s_waitcnt vmcnt(8) lgkmcnt(0)
	s_barrier
	v_mfma_f32_16x16x128_f8f6f4 v[126:129], v[134:141], v[166:173], v[126:129]
	v_mfma_f32_16x16x128_f8f6f4 v[122:125], v[142:149], v[166:173], v[122:125]
	v_mfma_f32_16x16x128_f8f6f4 v[118:121], v[134:141], v[174:181], v[118:121]
	v_mfma_f32_16x16x128_f8f6f4 v[114:117], v[142:149], v[174:181], v[114:117]
	v_mfma_f32_16x16x128_f8f6f4 v[106:109], v[134:141], v[182:189], v[106:109]
	v_mfma_f32_16x16x128_f8f6f4 v[98:101], v[142:149], v[182:189], v[98:101]
	v_mfma_f32_16x16x128_f8f6f4 v[110:113], v[150:157], v[166:173], v[110:113]
	v_mfma_f32_16x16x128_f8f6f4 v[102:105], v[158:165], v[166:173], v[102:105]
	v_mfma_f32_16x16x128_f8f6f4 v[198:201], v[134:141], v[190:197], v[90:93]
	v_mfma_f32_16x16x128_f8f6f4 v[202:205], v[142:149], v[190:197], v[82:85]
	v_mfma_f32_16x16x128_f8f6f4 v[166:169], v[150:157], v[174:181], v[94:97]
	v_mfma_f32_16x16x128_f8f6f4 v[170:173], v[158:165], v[174:181], v[86:89]
	v_mfma_f32_16x16x128_f8f6f4 v[174:177], v[150:157], v[182:189], v[78:81]
	v_mfma_f32_16x16x128_f8f6f4 v[178:181], v[158:165], v[182:189], v[74:77]
	v_mfma_f32_16x16x128_f8f6f4 v[182:185], v[150:157], v[190:197], v[70:73]
	v_mfma_f32_16x16x128_f8f6f4 v[186:189], v[158:165], v[190:197], v[66:69]
	s_barrier
	s_mov_b32 m0, s27
	s_mov_b32 s18, s14
	s_mov_b32 s19, s15
	s_nop 1
	ds_read_b128 v[66:69], v227 offset:16384
	ds_read_b128 v[70:73], v227 offset:17408
	ds_read_b128 v[74:77], v227 offset:18432
	ds_read_b128 v[78:81], v227 offset:19456
	ds_read_b128 v[82:85], v227 offset:20480
	ds_read_b128 v[86:89], v227 offset:21504
	ds_read_b128 v[90:93], v227 offset:22528
	ds_read_b128 v[94:97], v227 offset:23552
	buffer_load_dwordx4 v224, s[16:19], s91 offen lds
	s_mov_b32 m0, s30
	s_add_i32 s92, s91, 0xac000
	buffer_load_dwordx4 v224, s[16:19], s92 offen lds
	s_mov_b32 m0, s31
	s_add_i32 s92, s91, 0x158000
	buffer_load_dwordx4 v224, s[16:19], s92 offen lds
	s_mov_b32 m0, s51
	s_add_i32 s92, s91, 0x204000
	buffer_load_dwordx4 v224, s[16:19], s92 offen lds
	s_mov_b32 m0, s25
	s_add_i32 s92, s56, 0xac000
	buffer_load_dwordx4 v223, s[12:15], s56 offen lds
	s_mov_b32 m0, s58
	s_nop 0
	buffer_load_dwordx4 v223, s[12:15], s92 offen lds
	s_waitcnt vmcnt(8) lgkmcnt(0)
	s_barrier
	v_mfma_f32_16x16x128_f8f6f4 v[62:65], v[134:141], v[66:73], v[62:65]
	v_mfma_f32_16x16x128_f8f6f4 v[58:61], v[142:149], v[66:73], v[58:61]
	v_mfma_f32_16x16x128_f8f6f4 v[54:57], v[134:141], v[74:81], v[54:57]
	v_mfma_f32_16x16x128_f8f6f4 v[50:53], v[142:149], v[74:81], v[50:53]
	v_mfma_f32_16x16x128_f8f6f4 v[190:193], v[134:141], v[82:89], v[42:45]
	v_mfma_f32_16x16x128_f8f6f4 v[194:197], v[142:149], v[82:89], v[34:37]
	v_mfma_f32_16x16x128_f8f6f4 v[206:209], v[134:141], v[90:97], v[26:29]
	v_mfma_f32_16x16x128_f8f6f4 v[210:213], v[142:149], v[90:97], v[18:21]
	v_mfma_f32_16x16x128_f8f6f4 v[214:217], v[150:157], v[66:73], v[46:49]
	v_mfma_f32_16x16x128_f8f6f4 v[218:221], v[158:165], v[66:73], v[38:41]
	v_mfma_f32_16x16x128_f8f6f4 v[234:237], v[150:157], v[74:81], v[30:33]
	v_mfma_f32_16x16x128_f8f6f4 v[238:241], v[158:165], v[74:81], v[22:25]
	v_mfma_f32_16x16x128_f8f6f4 v[242:245], v[150:157], v[82:89], v[14:17]
	v_mfma_f32_16x16x128_f8f6f4 v[246:249], v[158:165], v[82:89], v[10:13]
	v_mfma_f32_16x16x128_f8f6f4 v[250:253], v[150:157], v[90:97], v[6:9]
	v_mfma_f32_16x16x128_f8f6f4 v[130:133], v[158:165], v[90:97], v[2:5]
	s_barrier
	s_nop 4
	ds_read_b128 v[2:5], v228
	ds_read_b128 v[6:9], v228 offset:1024
	ds_read_b128 v[10:13], v228 offset:2048
	ds_read_b128 v[14:17], v228 offset:3072
	ds_read_b128 v[134:137], v229
	ds_read_b128 v[138:141], v229 offset:1024
	ds_read_b128 v[142:145], v229 offset:2048
	ds_read_b128 v[146:149], v229 offset:3072
	s_mov_b32 m0, s59
	s_add_i32 s92, s56, 0x158000
	ds_read_b128 v[18:21], v227 offset:32768
	ds_read_b128 v[22:25], v227 offset:33792
	ds_read_b128 v[26:29], v227 offset:34816
	ds_read_b128 v[30:33], v227 offset:35840
	ds_read_b128 v[34:37], v227 offset:36864
	ds_read_b128 v[38:41], v227 offset:37888
	ds_read_b128 v[42:45], v227 offset:38912
	ds_read_b128 v[46:49], v227 offset:39936
	buffer_load_dwordx4 v223, s[12:15], s92 offen lds
	s_mov_b32 m0, s60
	s_add_i32 s92, s56, 0x204000
	buffer_load_dwordx4 v223, s[12:15], s92 offen lds
	s_waitcnt vmcnt(8) lgkmcnt(0)
	s_barrier
	v_mfma_f32_16x16x128_f8f6f4 v[126:129], v[2:9], v[18:25], v[126:129]
	v_mfma_f32_16x16x128_f8f6f4 v[122:125], v[10:17], v[18:25], v[122:125]
	v_mfma_f32_16x16x128_f8f6f4 v[118:121], v[2:9], v[26:33], v[118:121]
	v_mfma_f32_16x16x128_f8f6f4 v[114:117], v[10:17], v[26:33], v[114:117]
	v_mfma_f32_16x16x128_f8f6f4 v[106:109], v[2:9], v[34:41], v[106:109]
	v_mfma_f32_16x16x128_f8f6f4 v[98:101], v[10:17], v[34:41], v[98:101]
	v_mfma_f32_16x16x128_f8f6f4 v[90:93], v[2:9], v[42:49], v[198:201]
	v_mfma_f32_16x16x128_f8f6f4 v[82:85], v[10:17], v[42:49], v[202:205]
	v_mfma_f32_16x16x128_f8f6f4 v[110:113], v[134:141], v[18:25], v[110:113]
	v_mfma_f32_16x16x128_f8f6f4 v[102:105], v[142:149], v[18:25], v[102:105]
	v_mfma_f32_16x16x128_f8f6f4 v[94:97], v[134:141], v[26:33], v[166:169]
	v_mfma_f32_16x16x128_f8f6f4 v[86:89], v[142:149], v[26:33], v[170:173]
	v_mfma_f32_16x16x128_f8f6f4 v[78:81], v[134:141], v[34:41], v[174:177]
	v_mfma_f32_16x16x128_f8f6f4 v[74:77], v[142:149], v[34:41], v[178:181]
	v_mfma_f32_16x16x128_f8f6f4 v[70:73], v[134:141], v[42:49], v[182:185]
	v_mfma_f32_16x16x128_f8f6f4 v[66:69], v[142:149], v[42:49], v[186:189]
	s_barrier
	s_mov_b32 m0, s63
	s_or_b32 s92, s91, 0x80
	ds_read_b128 v[150:153], v227 offset:49152
	ds_read_b128 v[154:157], v227 offset:50176
	ds_read_b128 v[158:161], v227 offset:51200
	ds_read_b128 v[162:165], v227 offset:52224
	ds_read_b128 v[166:169], v227 offset:53248
	ds_read_b128 v[170:173], v227 offset:54272
	ds_read_b128 v[174:177], v227 offset:55296
	ds_read_b128 v[178:181], v227 offset:56320
	buffer_load_dwordx4 v224, s[16:19], s92 offen lds
	s_add_i32 s92, s91, 0xac080
	s_mov_b32 m0, s64
	s_add_i32 s56, s56, 0xac080
	buffer_load_dwordx4 v224, s[16:19], s92 offen lds
	s_add_i32 s92, s91, 0x158080
	s_mov_b32 m0, s67
	s_add_i32 s91, s91, 0x204080
	buffer_load_dwordx4 v224, s[16:19], s92 offen lds
	s_mov_b32 m0, s68
	s_nop 0
	buffer_load_dwordx4 v224, s[16:19], s91 offen lds
	s_mov_b32 m0, s65
	s_nop 0
	buffer_load_dwordx4 v223, s[12:15], s57 offen lds
	s_mov_b32 m0, s66
	s_nop 0
	buffer_load_dwordx4 v223, s[12:15], s56 offen lds
	s_waitcnt vmcnt(8) lgkmcnt(0)
	s_barrier
	v_mfma_f32_16x16x128_f8f6f4 v[62:65], v[2:9], v[150:157], v[62:65]
	v_mfma_f32_16x16x128_f8f6f4 v[58:61], v[10:17], v[150:157], v[58:61]
	v_mfma_f32_16x16x128_f8f6f4 v[54:57], v[2:9], v[158:165], v[54:57]
	v_mfma_f32_16x16x128_f8f6f4 v[50:53], v[10:17], v[158:165], v[50:53]
	v_mfma_f32_16x16x128_f8f6f4 v[42:45], v[2:9], v[166:173], v[190:193]
	v_mfma_f32_16x16x128_f8f6f4 v[34:37], v[10:17], v[166:173], v[194:197]
	v_mfma_f32_16x16x128_f8f6f4 v[26:29], v[2:9], v[174:181], v[206:209]
	v_mfma_f32_16x16x128_f8f6f4 v[18:21], v[10:17], v[174:181], v[210:213]
	v_mfma_f32_16x16x128_f8f6f4 v[46:49], v[134:141], v[150:157], v[214:217]
	v_mfma_f32_16x16x128_f8f6f4 v[38:41], v[142:149], v[150:157], v[218:221]
	v_mfma_f32_16x16x128_f8f6f4 v[30:33], v[134:141], v[158:165], v[234:237]
	v_mfma_f32_16x16x128_f8f6f4 v[22:25], v[142:149], v[158:165], v[238:241]
	v_mfma_f32_16x16x128_f8f6f4 v[14:17], v[134:141], v[166:173], v[242:245]
	v_mfma_f32_16x16x128_f8f6f4 v[10:13], v[142:149], v[166:173], v[246:249]
	v_mfma_f32_16x16x128_f8f6f4 v[6:9], v[134:141], v[174:181], v[250:253]
	v_mfma_f32_16x16x128_f8f6f4 v[2:5], v[142:149], v[174:181], v[130:133]
	s_barrier
	s_add_i32 s55, s55, 2
	s_addk_i32 s8, 0x100
	s_addk_i32 s9, 0x100
	s_cmp_ge_i32 s55, s3
	s_cbranch_scc0 .LBB0_1567
	v_pk_mul_f32 v[208:209], v[128:129], s[50:51] op_sel_hi:[1,0]
	v_pk_mul_f32 v[210:211], v[126:127], s[50:51] op_sel_hi:[1,0]
	v_pk_mul_f32 v[212:213], v[124:125], s[50:51] op_sel_hi:[1,0]
	v_pk_mul_f32 v[122:123], v[122:123], s[50:51] op_sel_hi:[1,0]
	v_pk_mul_f32 v[220:221], v[112:113], s[50:51] op_sel_hi:[1,0]
	v_pk_mul_f32 v[218:219], v[110:111], s[50:51] op_sel_hi:[1,0]
	v_pk_mul_f32 v[216:217], v[104:105], s[50:51] op_sel_hi:[1,0]
	v_pk_mul_f32 v[214:215], v[102:103], s[50:51] op_sel_hi:[1,0]
	v_pk_mul_f32 v[206:207], v[120:121], s[50:51] op_sel_hi:[1,0]
	v_pk_mul_f32 v[146:147], v[118:119], s[50:51] op_sel_hi:[1,0]
	v_pk_mul_f32 v[204:205], v[116:117], s[50:51] op_sel_hi:[1,0]
	v_pk_mul_f32 v[144:145], v[114:115], s[50:51] op_sel_hi:[1,0]
	v_pk_mul_f32 v[148:149], v[96:97], s[50:51] op_sel_hi:[1,0]
	v_pk_mul_f32 v[154:155], v[94:95], s[50:51] op_sel_hi:[1,0]
	v_pk_mul_f32 v[202:203], v[88:89], s[50:51] op_sel_hi:[1,0]
	v_pk_mul_f32 v[200:201], v[86:87], s[50:51] op_sel_hi:[1,0]
	v_pk_mul_f32 v[198:199], v[108:109], s[50:51] op_sel_hi:[1,0]
	v_pk_mul_f32 v[152:153], v[106:107], s[50:51] op_sel_hi:[1,0]
	v_pk_mul_f32 v[196:197], v[100:101], s[50:51] op_sel_hi:[1,0]
	v_pk_mul_f32 v[150:151], v[98:99], s[50:51] op_sel_hi:[1,0]
	v_pk_mul_f32 v[156:157], v[80:81], s[50:51] op_sel_hi:[1,0]
	v_pk_mul_f32 v[162:163], v[78:79], s[50:51] op_sel_hi:[1,0]
	v_pk_mul_f32 v[194:195], v[76:77], s[50:51] op_sel_hi:[1,0]
	v_pk_mul_f32 v[192:193], v[74:75], s[50:51] op_sel_hi:[1,0]
	v_pk_mul_f32 v[190:191], v[92:93], s[50:51] op_sel_hi:[1,0]
	v_pk_mul_f32 v[160:161], v[90:91], s[50:51] op_sel_hi:[1,0]
	v_pk_mul_f32 v[188:189], v[84:85], s[50:51] op_sel_hi:[1,0]
	v_pk_mul_f32 v[158:159], v[82:83], s[50:51] op_sel_hi:[1,0]
	v_pk_mul_f32 v[164:165], v[72:73], s[50:51] op_sel_hi:[1,0]
	v_pk_mul_f32 v[170:171], v[70:71], s[50:51] op_sel_hi:[1,0]
	v_pk_mul_f32 v[186:187], v[68:69], s[50:51] op_sel_hi:[1,0]
	v_pk_mul_f32 v[184:185], v[66:67], s[50:51] op_sel_hi:[1,0]
	v_pk_mul_f32 v[182:183], v[64:65], s[50:51] op_sel_hi:[1,0]
	v_pk_mul_f32 v[168:169], v[62:63], s[50:51] op_sel_hi:[1,0]
	v_pk_mul_f32 v[180:181], v[60:61], s[50:51] op_sel_hi:[1,0]
	v_pk_mul_f32 v[166:167], v[58:59], s[50:51] op_sel_hi:[1,0]
	v_pk_mul_f32 v[172:173], v[48:49], s[50:51] op_sel_hi:[1,0]
	v_pk_mul_f32 v[178:179], v[46:47], s[50:51] op_sel_hi:[1,0]
	v_pk_mul_f32 v[176:177], v[40:41], s[50:51] op_sel_hi:[1,0]
	v_pk_mul_f32 v[174:175], v[38:39], s[50:51] op_sel_hi:[1,0]
	v_pk_mul_f32 v[142:143], v[56:57], s[50:51] op_sel_hi:[1,0]
	v_pk_mul_f32 v[140:141], v[54:55], s[50:51] op_sel_hi:[1,0]
	v_pk_mul_f32 v[138:139], v[52:53], s[50:51] op_sel_hi:[1,0]
	v_pk_mul_f32 v[134:135], v[50:51], s[50:51] op_sel_hi:[1,0]
	v_pk_mul_f32 v[136:137], v[32:33], s[50:51] op_sel_hi:[1,0]
	v_pk_mul_f32 v[128:129], v[30:31], s[50:51] op_sel_hi:[1,0]
	v_pk_mul_f32 v[126:127], v[24:25], s[50:51] op_sel_hi:[1,0]
	v_pk_mul_f32 v[124:125], v[22:23], s[50:51] op_sel_hi:[1,0]
	v_pk_mul_f32 v[102:103], v[44:45], s[50:51] op_sel_hi:[1,0]
	v_pk_mul_f32 v[100:101], v[42:43], s[50:51] op_sel_hi:[1,0]
	v_pk_mul_f32 v[98:99], v[36:37], s[50:51] op_sel_hi:[1,0]
	v_pk_mul_f32 v[94:95], v[34:35], s[50:51] op_sel_hi:[1,0]
	v_pk_mul_f32 v[96:97], v[16:17], s[50:51] op_sel_hi:[1,0]
	v_pk_mul_f32 v[92:93], v[14:15], s[50:51] op_sel_hi:[1,0]
	v_pk_mul_f32 v[90:91], v[12:13], s[50:51] op_sel_hi:[1,0]
	v_pk_mul_f32 v[88:89], v[10:11], s[50:51] op_sel_hi:[1,0]
	v_pk_mul_f32 v[86:87], v[28:29], s[50:51] op_sel_hi:[1,0]
	v_pk_mul_f32 v[84:85], v[26:27], s[50:51] op_sel_hi:[1,0]
	v_pk_mul_f32 v[82:83], v[20:21], s[50:51] op_sel_hi:[1,0]
	v_pk_mul_f32 v[78:79], v[18:19], s[50:51] op_sel_hi:[1,0]
	v_pk_mul_f32 v[80:81], v[8:9], s[50:51] op_sel_hi:[1,0]
	v_pk_mul_f32 v[76:77], v[6:7], s[50:51] op_sel_hi:[1,0]
	v_pk_mul_f32 v[74:75], v[4:5], s[50:51] op_sel_hi:[1,0]
	v_pk_mul_f32 v[72:73], v[2:3], s[50:51] op_sel_hi:[1,0]
	s_and_b64 vcc, exec, s[48:49]
	s_cbranch_vccz .LBB0_1570
